# speedup vs baseline: 1.0468x; 1.0131x over previous
; __device__ __forceinline__ void lds_barrier() { asm volatile("s_waitcnt lgkmcnt(0)" ::: "memory"); __builtin_amdgcn_s_barrier(); asm volatile("" ::: "memory"); }
; __device__ __forceinline__ void wkv_phase(const WkvT& W, unsigned char* lds) {
;     ...
;     for (int unit = blockIdx.x; unit < 256; unit += gridDim.x) {
;         const int q = (unit >> 3) & 3, hb = (unit & 7) + 8 * (unit >> 5), b = hb >> 5, h = hb & 31;
;         const size_t rowbase = (size_t)b * SEQ; const int cbase = h * 64;
;         float kkc[4], kac[4], rkc[4]; WkvRaw raw;
; #pragma unroll
;         for (int e = 0; e < 4; ++e) { const int j = cbase + 4 * (tid & 15) + e; kkc[e] = W.kk[j]; kac[e] = W.ka[j]; rkc[e] = W.rk[j]; }
;         f32x2 S = {0.f, 0.f};
;         const int il = 2 * wave + (lane >> 5), jj = lane & 31;
;         __syncthreads();
;         wkv_issue(W, raw, rowbase, cbase, q, 0, tid);
;         wkv_stage(W, raw, rowbase, h, q, 0, tid, kkc, kac, rkc, sP, sV);
;         lds_barrier();
; #pragma unroll 2
;         for (int c = 0; c < 256; ++c) {
;             const int bi = c & 1, bo = bi * 12288, bn = (bi ^ 1) * 12288;
;             if (c + 1 < 256) wkv_issue(W, raw, rowbase, cbase, q, c + 1, tid);
;             {
;                 const float* pp = sP + bo + jj * 12;
;                 const float* pv = sV + bi * 512 + il;
;                 f32x4 nA = *(const f32x4*)pp, nB = *(const f32x4*)(pp + 4); f32x2 nr = *(const f32x2*)(pp + 8); float nv = pv[0];
.LBB0_1610:
	s_cmp_lt_i32 s84, 15
	s_cselect_b64 s[48:49], -1, 0
	s_and_b64 s[0:1], s[48:49], s[0:1]
	s_andn2_b64 vcc, exec, s[0:1]
	s_cbranch_vccnz .LBB0_1647
	v_readfirstlane_b32 s99, v0
	s_mov_b64 s[52:53], s[78:79]
	s_cmpk_gt_i32 s2, 0xff
	s_cbranch_scc1 .LBB0_1647
	s_add_u32 s54, s52, 0x3500000
	s_addc_u32 s55, s53, 0
	s_add_u32 s56, s52, 0x7500000
	s_addc_u32 s57, s53, 0
	s_add_u32 s68, s52, 0x19500000
	s_addc_u32 s69, s53, 0
	s_add_u32 s86, s52, 0xb500000
	s_addc_u32 s87, s53, 0
	s_add_u32 s88, s52, 0xf500000
	s_addc_u32 s89, s53, 0
	s_add_u32 s90, s52, 0x1e500000
	v_and_b32_e32 v18, 15, v0
	v_and_b32_e32 v4, 0x1f0, v0
	s_addc_u32 s91, s53, 0
	s_add_i32 s3, 0, 0x18000
	v_lshlrev_b32_e32 v4, 2, v4
	v_lshlrev_b32_e32 v5, 4, v18
	v_add3_u32 v15, s3, v4, v5
	v_lshrrev_b32_e32 v5, 3, v0
	v_and_b32_e32 v5, 60, v5
	v_and_b32_e32 v6, 16, v0
	v_and_b32_e32 v2, 31, v0
	v_lshrrev_b32_e32 v14, 4, v0
	v_lshlrev_b32_e32 v20, 2, v18
	v_add_u32_e32 v21, s3, v5
	v_cmp_ne_u32_e64 s[4:5], 0, v6
	v_lshlrev_b32_e32 v6, 6, v18
	s_add_i32 s3, 0, 0x19000
	v_lshlrev_b32_e32 v1, 2, v0
	v_mov_b32_e32 v17, 0
	v_mul_u32_u24_e32 v3, 0x60, v0
	v_mad_u32_u24 v19, v2, 48, 0
	v_cmp_eq_u32_e64 s[6:7], 31, v2
	s_waitcnt vmcnt(1)
	v_add3_u32 v29, s3, v6, v5
	v_add3_u32 v60, s3, v4, v20
	v_cmp_eq_u32_e64 s[10:11], 16, v2
	v_cmp_eq_u32_e64 s[12:13], 17, v2
	v_cmp_eq_u32_e64 s[14:15], 18, v2
	v_cmp_eq_u32_e64 s[16:17], 19, v2
	v_cmp_eq_u32_e64 s[18:19], 20, v2
	v_cmp_eq_u32_e64 s[20:21], 21, v2
	v_cmp_eq_u32_e64 s[22:23], 22, v2
	v_cmp_eq_u32_e64 s[24:25], 23, v2
	v_cmp_eq_u32_e64 s[26:27], 24, v2
	v_cmp_eq_u32_e64 s[28:29], 25, v2
	v_cmp_eq_u32_e64 s[30:31], 26, v2
	v_cmp_eq_u32_e64 s[34:35], 27, v2
	v_cmp_eq_u32_e64 s[36:37], 28, v2
	v_cmp_eq_u32_e64 s[38:39], 29, v2
	v_cmp_eq_u32_e64 s[40:41], 30, v2
	v_and_b32_e32 v243, 8, v0
	v_cmp_ne_u32_e64 s[10:11], 0, v243
	v_and_b32_e32 v243, 4, v0
	v_cmp_ne_u32_e64 s[12:13], 0, v243
	v_and_b32_e32 v243, 2, v0
	v_cmp_ne_u32_e64 s[14:15], 0, v243
	v_and_b32_e32 v243, 1, v0
	v_cmp_ne_u32_e64 s[16:17], 0, v243
	v_readfirstlane_b32 s99, v0
	v_mul_u32_u24_e32 v182, 0x60, v18
	v_and_b32_e32 v188, 8, v18
	v_mul_u32_u24_e32 v183, 0xc0, v18
	v_mad_u32_u24 v182, v188, 6, v182
	v_add_u32_e32 v183, 48, v183
	v_lshrrev_b32_e32 v188, 4, v0
	v_sub_u32_e32 v183, v183, v182
	v_lshlrev_b32_e32 v188, 2, v188
	v_add_u32_e32 v184, 0x10200, v182
	v_add_u32_e32 v186, 0x18000, v188
	v_add_u32_e32 v185, 0x10200, v183
	v_lshl_add_u32 v187, v18, 6, v188
	v_add_u32_e32 v187, 0x19000, v187
	v_lshlrev_b32_e32 v2, 12, v14
	v_lshlrev_b32_e32 v4, 1, v18
	s_mov_b32 s3, 0x13500000
	v_and_b32_e32 v1, 60, v1
	v_cmp_gt_u32_e64 s[0:1], 4, v18
	s_mov_b32 s93, 0
	v_cmp_eq_u32_e64 s[8:9], 0, v18
	v_add_u32_e32 v61, 0x10200, v19
	v_add_u32_e32 v62, 0x10220, v19
	v_add_u32_e32 v63, 0x10210, v19
	v_add_u32_e32 v64, 0x10800, v19
	v_add_u32_e32 v65, 0x10820, v19
	v_add_u32_e32 v66, 0x10810, v19
	v_add_u32_e32 v67, 0x10e00, v19
	v_add_u32_e32 v68, 0x10e20, v19
	v_add_u32_e32 v69, 0x10e10, v19
	v_add_u32_e32 v70, 0x11400, v19
	v_add_u32_e32 v71, 0x11420, v19
	v_add_u32_e32 v72, 0x11410, v19
	v_add_u32_e32 v73, 0x11a00, v19
	v_add_u32_e32 v74, 0x11a20, v19
	v_add_u32_e32 v75, 0x11a10, v19
	v_add_u32_e32 v76, 0x12000, v19
	v_add_u32_e32 v77, 0x12020, v19
	v_add_u32_e32 v78, 0x12010, v19
	v_add_u32_e32 v79, 0x12600, v19
	v_add_u32_e32 v80, 0x12620, v19
	v_add_u32_e32 v81, 0x12610, v19
	v_add_u32_e32 v82, 0x12c00, v19
	v_add_u32_e32 v83, 0x12c20, v19
	v_add_u32_e32 v84, 0x12c10, v19
	v_add_u32_e32 v85, 0x13200, v19
	v_add_u32_e32 v86, 0x13220, v19
	v_add_u32_e32 v87, 0x13210, v19
	v_add_u32_e32 v88, 0x13800, v19
	v_add_u32_e32 v89, 0x13820, v19
	s_waitcnt vmcnt(0)
	v_add_u32_e32 v90, 0x13810, v19
	v_add_u32_e32 v91, 0x13e00, v19
	v_add_u32_e32 v92, 0x13e20, v19
	v_add_u32_e32 v93, 0x13e10, v19
	v_add_u32_e32 v94, 0x14400, v19
	v_add_u32_e32 v95, 0x14420, v19
	v_add_u32_e32 v96, 0x14410, v19
	v_add_u32_e32 v97, 0x14a00, v19
	v_add_u32_e32 v98, 0x14a20, v19
	v_add_u32_e32 v99, 0x14a10, v19
	v_add_u32_e32 v100, 0x15000, v19
	v_add_u32_e32 v101, 0x15020, v19
	v_add_u32_e32 v102, 0x15010, v19
	v_add_u32_e32 v103, 0x15600, v19
	v_add_u32_e32 v104, 0x15620, v19
	v_add_u32_e32 v105, 0x15610, v19
	v_add_u32_e32 v106, 0x15c00, v19
	v_add_u32_e32 v107, 0x15c20, v19
	v_add_u32_e32 v108, 0x15c10, v19
	v_add_u32_e32 v109, 0x16200, v19
	v_add_u32_e32 v110, 0x16220, v19
	v_add_u32_e32 v111, 0x16210, v19
	v_add_u32_e32 v112, 0x16800, v19
	v_add_u32_e32 v113, 0x16820, v19
	v_add_u32_e32 v114, 0x16810, v19
	v_add_u32_e32 v115, 0x16e00, v19
	v_add_u32_e32 v116, 0x16e20, v19
	v_add_u32_e32 v117, 0x16e10, v19
	v_add_u32_e32 v118, 0x17400, v19
	v_add_u32_e32 v119, 0x17420, v19
	v_add_u32_e32 v120, 0x17410, v19
	v_add_u32_e32 v121, 0x17a00, v19
	v_add_u32_e32 v122, 0x17a20, v19
	v_add_u32_e32 v123, 0x17a10, v19
	v_lshlrev_b32_e32 v22, 10, v14
	v_mov_b32_e32 v23, v17
	v_or_b32_e32 v24, 0x13520000, v2
	v_mov_b32_e32 v25, v17
	v_lshlrev_b32_e32 v26, 7, v14
	v_mov_b32_e32 v27, v17
	v_lshl_or_b32 v28, v18, 3, v2
	v_or3_b32 v30, v2, v4, s3
	v_mov_b32_e32 v31, v17
	s_mov_b32 s3, 0xf800000
	v_mov_b32_e32 v124, 0x260
	s_mov_b64 s[94:95], 0x40000
	v_add_u32_e32 v125, 0, v3
	s_mov_b32 s44, s2
	s_mov_b32 s45, s2
	s_branch .LBB0_1614

; __device__ __forceinline__ void wkv_issue(const WkvT& W, WkvRaw& raw, size_t rowbase, int cbase, int q, int c, int tid) {
;     const size_t row = rowbase + (size_t)c * 32 + (tid >> 4), idx = row * DM + cbase + 4 * (tid & 15);
;     raw.r = *(const u32x2*)(W.R + idx); raw.k = *(const u32x2*)(W.K + idx); raw.a = *(const u32x2*)(W.AS + idx); raw.l = *(const u32x2*)(W.LW + idx);
;     if ((tid & 15) < 4) raw.v = *(const u32x2*)(W.V + row * DM + cbase + q * 16 + 4 * (tid & 15));
; }
; __device__ __forceinline__ void wkv_phase(const WkvT& W, unsigned char* lds) {
;     ...
;             if (c + 1 < 256) wkv_issue(W, raw, rowbase, cbase, q, c + 1, tid);
;             {
;                 const float* pp = sP + bo + jj * 12;
;                 const float* pv = sV + bi * 512 + il;
;                 f32x4 nA = *(const f32x4*)pp, nB = *(const f32x4*)(pp + 4); f32x2 nr = *(const f32x2*)(pp + 8); float nv = pv[0];
;                 float yk0 = 0.f, yk1 = 0.f, ep = 0.f;
;                 const bool oddrow = (lane & 16) != 0;
; #pragma unroll
;                 for (int t = 0; t < 32; ++t) {
;                     const f32x2 a2 = {nA[0], nA[1]}, w2 = {nA[2], nA[3]}, b2 = {nB[0], nB[1]}, k2 = {nB[2], nB[3]}, r2 = nr; const float v = nv;
;                     if (t + 1 < 32) { nA = *(const f32x4*)(pp + (t + 1) * 384); nB = *(const f32x4*)(pp + (t + 1) * 384 + 4); nr = *(const f32x2*)(pp + (t + 1) * 384 + 8); nv = pv[(t + 1) * 16]; }
;                     float S0 = S.x, S1 = S.y;
;                     float d = S0 * a2.x; d = __builtin_fmaf(S1, a2.y, d);
;                     float t0 = S0 * w2.x; t0 = __builtin_fmaf(v, k2.x, t0); asm volatile("" : "+v"(t0));
;                     float t1 = S1 * w2.y; t1 = __builtin_fmaf(v, k2.y, t1); asm volatile("" : "+v"(t1));
;                     float yprev; const float sa = wkv_reduce(d, ep, yprev);
;                     S0 = __builtin_fmaf(sa, b2.x, t0); asm volatile("" : "+v"(S0));
;                     S1 = __builtin_fmaf(sa, b2.y, t1); asm volatile("" : "+v"(S1));
;                     ep = S0 * r2.x; ep = __builtin_fmaf(S1, r2.y, ep);
;                     S.x = S0; S.y = S1;
.LBB0_1622:
	s_bitcmp0_b32 s99, 8
	s_cbranch_scc1 .Lwkv4_b1_entry
	v_lshl_add_u64 v[54:55], s[52:53], 0, v[40:41]
	v_add_co_u32_e32 v46, vcc, 0x3520000, v54
	s_nop 1
	v_addc_co_u32_e32 v47, vcc, 0, v55, vcc
	v_add_co_u32_e32 v48, vcc, 0x7520000, v54
	s_nop 1
	v_addc_co_u32_e32 v49, vcc, 0, v55, vcc
	v_add_co_u32_e32 v56, vcc, 0xf520000, v54
	s_nop 1
	v_addc_co_u32_e32 v57, vcc, 0, v55, vcc
	v_add_co_u32_e32 v58, vcc, 0xb520000, v54
	s_nop 1
	v_addc_co_u32_e32 v59, vcc, 0, v55, vcc
	global_load_dwordx2 v[50:51], v[46:47], off
	global_load_dwordx2 v[52:53], v[48:49], off
	s_nop 0
	global_load_dwordx2 v[46:47], v[56:57], off
	global_load_dwordx2 v[48:49], v[58:59], off
	s_and_saveexec_b64 s[46:47], s[0:1]
	s_cbranch_execz .LBB0_1624
	v_lshl_add_u64 v[32:33], s[52:53], 0, v[42:43]
	v_add_co_u32_e32 v32, vcc, 0x19520000, v32
	s_nop 1
	v_addc_co_u32_e32 v33, vcc, 0, v33, vcc
	global_load_dwordx2 v[32:33], v[32:33], off
.LBB0_1624:
	s_or_b64 exec, exec, s[46:47]
	v_add_co_u32_e32 v204, vcc, 0x3510000, v54
	s_nop 1
	v_addc_co_u32_e32 v205, vcc, 0, v55, vcc
	global_load_dwordx2 v[198:199], v[204:205], off
	v_add_co_u32_e32 v206, vcc, 0x7510000, v54
	s_nop 1
	v_addc_co_u32_e32 v207, vcc, 0, v55, vcc
	global_load_dwordx2 v[200:201], v[206:207], off
	v_add_co_u32_e32 v204, vcc, 0xf510000, v54
	s_nop 1
	v_addc_co_u32_e32 v205, vcc, 0, v55, vcc
	global_load_dwordx2 v[194:195], v[204:205], off
	v_add_co_u32_e32 v206, vcc, 0xb510000, v54
	s_nop 1
	v_addc_co_u32_e32 v207, vcc, 0, v55, vcc
	global_load_dwordx2 v[196:197], v[206:207], off
	s_and_saveexec_b64 s[100:101], s[0:1]
	v_lshl_add_u64 v[212:213], s[52:53], 0, v[42:43]
	v_add_co_u32_e32 v212, vcc, 0x19510000, v212
	s_nop 1
	v_addc_co_u32_e32 v213, vcc, 0, v213, vcc
	global_load_dwordx2 v[212:213], v[212:213], off
	s_or_b64 exec, exec, s[100:101]
.Lwkv4_b1_entry:
	s_bitcmp1_b32 s99, 8
	s_cbranch_scc1 .Lwkv4_b1_skip
	ds_read_b128 v[190:193], v182
	ds_read_b128 v[194:197], v182 offset:16
	ds_read_b64 v[228:229], v182 offset:32
	ds_read_b128 v[198:201], v183
	ds_read_b128 v[202:205], v183 offset:16
	ds_read_b64 v[230:231], v183 offset:32
	ds_read_b32 v240, v186 offset:0
	ds_read_b128 v[206:209], v182 offset:1536
	ds_read_b128 v[210:213], v182 offset:1552
	ds_read_b64 v[232:233], v182 offset:1568
	ds_read_b128 v[214:217], v183 offset:1536
	ds_read_b128 v[218:221], v183 offset:1552
	ds_read_b64 v[234:235], v183 offset:1568
	ds_read_b32 v241, v186 offset:64
	s_waitcnt lgkmcnt(7)
	v_pk_mul_f32 v[150:151], v[142:143], v[190:191]
	v_pk_fma_f32 v[150:151], v[144:145], v[198:199], v[150:151]
	v_pk_mul_f32 v[146:147], v[142:143], v[192:193]
	v_add_f32_e32 v154, v150, v151
	v_pk_mul_f32 v[148:149], v[144:145], v[200:201]
	v_pk_fma_f32 v[146:147], v[240:241], v[196:197], v[146:147] op_sel:[0,0,0] op_sel_hi:[0,1,1]
	v_add_f32_dpp v154, v154, v154 quad_perm:[1,0,3,2] row_mask:0xf bank_mask:0xf bound_ctrl:1
	v_pk_fma_f32 v[148:149], v[240:241], v[204:205], v[148:149] op_sel:[0,0,0] op_sel_hi:[0,1,1]
	s_nop 0
	v_add_f32_dpp v154, v154, v154 quad_perm:[2,3,0,1] row_mask:0xf bank_mask:0xf bound_ctrl:1
	ds_read_b128 v[126:129], v182 offset:3072
	ds_read_b128 v[130:133], v182 offset:3088
	v_add_f32_dpp v154, v154, v154 row_half_mirror row_mask:0xf bank_mask:0xf bound_ctrl:1
	ds_read_b64 v[236:237], v182 offset:3104
	ds_read_b128 v[134:137], v183 offset:3072
	v_add_f32_dpp v154, v154, v154 row_mirror row_mask:0xf bank_mask:0xf bound_ctrl:1
	v_pk_fma_f32 v[146:147], v[154:155], v[194:195], v[146:147] op_sel_hi:[0,1,1]
	v_pk_fma_f32 v[148:149], v[154:155], v[202:203], v[148:149] op_sel_hi:[0,1,1]
	ds_read_b128 v[222:225], v183 offset:3088
	ds_read_b64 v[238:239], v183 offset:3104
	ds_read_b32 v242, v186 offset:128
	s_waitcnt lgkmcnt(7)
	v_pk_mul_f32 v[150:151], v[146:147], v[206:207]
	v_pk_fma_f32 v[150:151], v[148:149], v[214:215], v[150:151]
	v_pk_mul_f32 v[152:153], v[146:147], v[228:229]
	v_add_f32_e32 v154, v150, v151
	v_pk_fma_f32 v[152:153], v[148:149], v[230:231], v[152:153]
	v_pk_mul_f32 v[142:143], v[146:147], v[208:209]
	v_add_f32_dpp v154, v154, v154 quad_perm:[1,0,3,2] row_mask:0xf bank_mask:0xf bound_ctrl:1
	v_pk_mul_f32 v[144:145], v[148:149], v[216:217]
	v_add_f32_e32 v156, v152, v153
	v_add_f32_dpp v154, v154, v154 quad_perm:[2,3,0,1] row_mask:0xf bank_mask:0xf bound_ctrl:1
	v_pk_fma_f32 v[142:143], v[240:241], v[212:213], v[142:143] op_sel:[1,0,0] op_sel_hi:[1,1,1]
	v_pk_fma_f32 v[144:145], v[240:241], v[220:221], v[144:145] op_sel:[1,0,0] op_sel_hi:[1,1,1]
	v_add_f32_dpp v154, v154, v154 row_half_mirror row_mask:0xf bank_mask:0xf bound_ctrl:1
	ds_read_b128 v[190:193], v182 offset:4608
	ds_read_b128 v[194:197], v182 offset:4624
	v_add_f32_dpp v154, v154, v154 row_mirror row_mask:0xf bank_mask:0xf bound_ctrl:1
	ds_read_b64 v[228:229], v182 offset:4640
	ds_read_b128 v[198:201], v183 offset:4608
	v_pk_fma_f32 v[142:143], v[154:155], v[210:211], v[142:143] op_sel_hi:[0,1,1]
	v_pk_fma_f32 v[144:145], v[154:155], v[218:219], v[144:145] op_sel_hi:[0,1,1]
	ds_read_b128 v[202:205], v183 offset:4624
	ds_read_b64 v[230:231], v183 offset:4640
	ds_read_b32 v240, v186 offset:192
	s_waitcnt lgkmcnt(7)
; __device__ __forceinline__ void wkv_phase(const WkvT& W, unsigned char* lds) {
;     ...
;                 for (int t = 0; t < 32; ++t) {
;                     const f32x2 a2 = {nA[0], nA[1]}, w2 = {nA[2], nA[3]}, b2 = {nB[0], nB[1]}, k2 = {nB[2], nB[3]}, r2 = nr; const float v = nv;
;                     if (t + 1 < 32) { nA = *(const f32x4*)(pp + (t + 1) * 384); nB = *(const f32x4*)(pp + (t + 1) * 384 + 4); nr = *(const f32x2*)(pp + (t + 1) * 384 + 8); nv = pv[(t + 1) * 16]; }
;                     float S0 = S.x, S1 = S.y;
;                     float d = S0 * a2.x; d = __builtin_fmaf(S1, a2.y, d);
;                     float t0 = S0 * w2.x; t0 = __builtin_fmaf(v, k2.x, t0); asm volatile("" : "+v"(t0));
;                     float t1 = S1 * w2.y; t1 = __builtin_fmaf(v, k2.y, t1); asm volatile("" : "+v"(t1));
;                     float yprev; const float sa = wkv_reduce(d, ep, yprev);
;                     S0 = __builtin_fmaf(sa, b2.x, t0); asm volatile("" : "+v"(S0));
;                     S1 = __builtin_fmaf(sa, b2.y, t1); asm volatile("" : "+v"(S1));
;                     ep = S0 * r2.x; ep = __builtin_fmaf(S1, r2.y, ep);
;                     S.x = S0; S.y = S1;
;                     if (t >= 1) { const bool hit = oddrow && ((lane & 15) == ((t - 1) & 15)); if (t <= 16) yk0 = hit ? yprev : yk0; else yk1 = hit ? yprev : yk1; }
	v_pk_mul_f32 v[150:151], v[142:143], v[126:127]
	v_pk_fma_f32 v[150:151], v[144:145], v[134:135], v[150:151]
	v_pk_mul_f32 v[152:153], v[142:143], v[232:233]
	v_add_f32_e32 v154, v150, v151
	v_pk_fma_f32 v[152:153], v[144:145], v[234:235], v[152:153]
	v_pk_mul_f32 v[146:147], v[142:143], v[128:129]
	v_add_f32_dpp v154, v154, v154 quad_perm:[1,0,3,2] row_mask:0xf bank_mask:0xf bound_ctrl:1
	v_pk_mul_f32 v[148:149], v[144:145], v[136:137]
	v_add_f32_e32 v157, v152, v153
	v_add_f32_dpp v154, v154, v154 quad_perm:[2,3,0,1] row_mask:0xf bank_mask:0xf bound_ctrl:1
	v_pk_fma_f32 v[146:147], v[242:243], v[132:133], v[146:147] op_sel:[0,0,0] op_sel_hi:[0,1,1]
	v_pk_fma_f32 v[148:149], v[242:243], v[224:225], v[148:149] op_sel:[0,0,0] op_sel_hi:[0,1,1]
	v_add_f32_dpp v154, v154, v154 row_half_mirror row_mask:0xf bank_mask:0xf bound_ctrl:1
	ds_read_b128 v[206:209], v182 offset:6144
	ds_read_b128 v[210:213], v182 offset:6160
	v_add_f32_dpp v154, v154, v154 row_mirror row_mask:0xf bank_mask:0xf bound_ctrl:1
	ds_read_b64 v[232:233], v182 offset:6176
	ds_read_b128 v[214:217], v183 offset:6144
	v_pk_fma_f32 v[146:147], v[154:155], v[130:131], v[146:147] op_sel_hi:[0,1,1]
	v_pk_fma_f32 v[148:149], v[154:155], v[222:223], v[148:149] op_sel_hi:[0,1,1]
	ds_read_b128 v[218:221], v183 offset:6160
	ds_read_b64 v[234:235], v183 offset:6176
	ds_read_b32 v241, v186 offset:256
	s_waitcnt lgkmcnt(7)
	v_pk_mul_f32 v[150:151], v[146:147], v[190:191]
	v_pk_fma_f32 v[150:151], v[148:149], v[198:199], v[150:151]
	v_pk_mul_f32 v[152:153], v[146:147], v[236:237]
	v_add_f32_e32 v154, v150, v151
	v_pk_fma_f32 v[152:153], v[148:149], v[238:239], v[152:153]
	v_pk_mul_f32 v[142:143], v[146:147], v[192:193]
	v_add_f32_dpp v154, v154, v154 quad_perm:[1,0,3,2] row_mask:0xf bank_mask:0xf bound_ctrl:1
	v_pk_mul_f32 v[144:145], v[148:149], v[200:201]
	v_add_f32_e32 v158, v152, v153
	v_add_f32_dpp v154, v154, v154 quad_perm:[2,3,0,1] row_mask:0xf bank_mask:0xf bound_ctrl:1
	v_pk_fma_f32 v[142:143], v[240:241], v[196:197], v[142:143] op_sel:[0,0,0] op_sel_hi:[0,1,1]
	v_pk_fma_f32 v[144:145], v[240:241], v[204:205], v[144:145] op_sel:[0,0,0] op_sel_hi:[0,1,1]
	v_add_f32_dpp v154, v154, v154 row_half_mirror row_mask:0xf bank_mask:0xf bound_ctrl:1
	ds_read_b128 v[126:129], v182 offset:7680
	ds_read_b128 v[130:133], v182 offset:7696
	v_add_f32_dpp v154, v154, v154 row_mirror row_mask:0xf bank_mask:0xf bound_ctrl:1
	ds_read_b64 v[236:237], v182 offset:7712
	ds_read_b128 v[134:137], v183 offset:7680
	v_pk_fma_f32 v[142:143], v[154:155], v[194:195], v[142:143] op_sel_hi:[0,1,1]
	v_pk_fma_f32 v[144:145], v[154:155], v[202:203], v[144:145] op_sel_hi:[0,1,1]
	ds_read_b128 v[222:225], v183 offset:7696
	ds_read_b64 v[238:239], v183 offset:7712
	ds_read_b32 v242, v186 offset:320
	s_waitcnt lgkmcnt(7)
	v_pk_mul_f32 v[150:151], v[142:143], v[206:207]
	v_pk_fma_f32 v[150:151], v[144:145], v[214:215], v[150:151]
	v_pk_mul_f32 v[152:153], v[142:143], v[228:229]
	v_add_f32_e32 v154, v150, v151
	v_pk_fma_f32 v[152:153], v[144:145], v[230:231], v[152:153]
	v_pk_mul_f32 v[146:147], v[142:143], v[208:209]
	v_add_f32_dpp v154, v154, v154 quad_perm:[1,0,3,2] row_mask:0xf bank_mask:0xf bound_ctrl:1
	v_pk_mul_f32 v[148:149], v[144:145], v[216:217]
	v_add_f32_e32 v159, v152, v153
	v_add_f32_dpp v154, v154, v154 quad_perm:[2,3,0,1] row_mask:0xf bank_mask:0xf bound_ctrl:1
	v_pk_fma_f32 v[146:147], v[240:241], v[212:213], v[146:147] op_sel:[1,0,0] op_sel_hi:[1,1,1]
	v_pk_fma_f32 v[148:149], v[240:241], v[220:221], v[148:149] op_sel:[1,0,0] op_sel_hi:[1,1,1]
	v_add_f32_dpp v154, v154, v154 row_half_mirror row_mask:0xf bank_mask:0xf bound_ctrl:1
	ds_read_b128 v[190:193], v182 offset:9216
	ds_read_b128 v[194:197], v182 offset:9232
	v_add_f32_dpp v154, v154, v154 row_mirror row_mask:0xf bank_mask:0xf bound_ctrl:1
	ds_read_b64 v[228:229], v182 offset:9248
	ds_read_b128 v[198:201], v183 offset:9216
	v_pk_fma_f32 v[146:147], v[154:155], v[210:211], v[146:147] op_sel_hi:[0,1,1]
	v_pk_fma_f32 v[148:149], v[154:155], v[218:219], v[148:149] op_sel_hi:[0,1,1]
	ds_read_b128 v[202:205], v183 offset:9232
	ds_read_b64 v[230:231], v183 offset:9248
	ds_read_b32 v240, v186 offset:384
	s_waitcnt lgkmcnt(7)
	v_pk_mul_f32 v[150:151], v[146:147], v[126:127]
	v_pk_fma_f32 v[150:151], v[148:149], v[134:135], v[150:151]
	v_pk_mul_f32 v[152:153], v[146:147], v[232:233]
	v_add_f32_e32 v154, v150, v151
	v_pk_fma_f32 v[152:153], v[148:149], v[234:235], v[152:153]
	v_pk_mul_f32 v[142:143], v[146:147], v[128:129]
	v_add_f32_dpp v154, v154, v154 quad_perm:[1,0,3,2] row_mask:0xf bank_mask:0xf bound_ctrl:1
	v_pk_mul_f32 v[144:145], v[148:149], v[136:137]
	v_add_f32_e32 v160, v152, v153
	v_add_f32_dpp v154, v154, v154 quad_perm:[2,3,0,1] row_mask:0xf bank_mask:0xf bound_ctrl:1
	v_pk_fma_f32 v[142:143], v[242:243], v[132:133], v[142:143] op_sel:[0,0,0] op_sel_hi:[0,1,1]
	v_pk_fma_f32 v[144:145], v[242:243], v[224:225], v[144:145] op_sel:[0,0,0] op_sel_hi:[0,1,1]
	v_add_f32_dpp v154, v154, v154 row_half_mirror row_mask:0xf bank_mask:0xf bound_ctrl:1
	ds_read_b128 v[206:209], v182 offset:10752
	ds_read_b128 v[210:213], v182 offset:10768
	v_add_f32_dpp v154, v154, v154 row_mirror row_mask:0xf bank_mask:0xf bound_ctrl:1
	ds_read_b64 v[232:233], v182 offset:10784
	ds_read_b128 v[214:217], v183 offset:10752
	v_pk_fma_f32 v[142:143], v[154:155], v[130:131], v[142:143] op_sel_hi:[0,1,1]
	v_pk_fma_f32 v[144:145], v[154:155], v[222:223], v[144:145] op_sel_hi:[0,1,1]
	ds_read_b128 v[218:221], v183 offset:10768
	ds_read_b64 v[234:235], v183 offset:10784
	ds_read_b32 v241, v186 offset:448
	s_waitcnt lgkmcnt(7)
; __device__ __forceinline__ void wkv_phase(const WkvT& W, unsigned char* lds) {
;     ...
;                 for (int t = 0; t < 32; ++t) {
;                     const f32x2 a2 = {nA[0], nA[1]}, w2 = {nA[2], nA[3]}, b2 = {nB[0], nB[1]}, k2 = {nB[2], nB[3]}, r2 = nr; const float v = nv;
;                     if (t + 1 < 32) { nA = *(const f32x4*)(pp + (t + 1) * 384); nB = *(const f32x4*)(pp + (t + 1) * 384 + 4); nr = *(const f32x2*)(pp + (t + 1) * 384 + 8); nv = pv[(t + 1) * 16]; }
;                     float S0 = S.x, S1 = S.y;
;                     float d = S0 * a2.x; d = __builtin_fmaf(S1, a2.y, d);
;                     float t0 = S0 * w2.x; t0 = __builtin_fmaf(v, k2.x, t0); asm volatile("" : "+v"(t0));
;                     float t1 = S1 * w2.y; t1 = __builtin_fmaf(v, k2.y, t1); asm volatile("" : "+v"(t1));
;                     float yprev; const float sa = wkv_reduce(d, ep, yprev);
;                     S0 = __builtin_fmaf(sa, b2.x, t0); asm volatile("" : "+v"(S0));
;                     S1 = __builtin_fmaf(sa, b2.y, t1); asm volatile("" : "+v"(S1));
;                     ep = S0 * r2.x; ep = __builtin_fmaf(S1, r2.y, ep);
;                     S.x = S0; S.y = S1;
;                     if (t >= 1) { const bool hit = oddrow && ((lane & 15) == ((t - 1) & 15)); if (t <= 16) yk0 = hit ? yprev : yk0; else yk1 = hit ? yprev : yk1; }
	v_pk_mul_f32 v[150:151], v[142:143], v[190:191]
	v_pk_fma_f32 v[150:151], v[144:145], v[198:199], v[150:151]
	v_pk_mul_f32 v[152:153], v[142:143], v[236:237]
	v_add_f32_e32 v154, v150, v151
	v_pk_fma_f32 v[152:153], v[144:145], v[238:239], v[152:153]
	v_pk_mul_f32 v[146:147], v[142:143], v[192:193]
	v_add_f32_dpp v154, v154, v154 quad_perm:[1,0,3,2] row_mask:0xf bank_mask:0xf bound_ctrl:1
	v_pk_mul_f32 v[148:149], v[144:145], v[200:201]
	v_add_f32_e32 v161, v152, v153
	v_add_f32_dpp v154, v154, v154 quad_perm:[2,3,0,1] row_mask:0xf bank_mask:0xf bound_ctrl:1
	v_pk_fma_f32 v[146:147], v[240:241], v[196:197], v[146:147] op_sel:[0,0,0] op_sel_hi:[0,1,1]
	v_pk_fma_f32 v[148:149], v[240:241], v[204:205], v[148:149] op_sel:[0,0,0] op_sel_hi:[0,1,1]
	v_add_f32_dpp v154, v154, v154 row_half_mirror row_mask:0xf bank_mask:0xf bound_ctrl:1
	ds_read_b128 v[126:129], v182 offset:12288
	ds_read_b128 v[130:133], v182 offset:12304
	v_add_f32_dpp v154, v154, v154 row_mirror row_mask:0xf bank_mask:0xf bound_ctrl:1
	ds_read_b64 v[236:237], v182 offset:12320
	ds_read_b128 v[134:137], v183 offset:12288
	v_pk_fma_f32 v[146:147], v[154:155], v[194:195], v[146:147] op_sel_hi:[0,1,1]
	v_pk_fma_f32 v[148:149], v[154:155], v[202:203], v[148:149] op_sel_hi:[0,1,1]
	ds_read_b128 v[222:225], v183 offset:12304
	ds_read_b64 v[238:239], v183 offset:12320
	ds_read_b32 v242, v186 offset:512
	s_waitcnt lgkmcnt(7)
	v_pk_mul_f32 v[150:151], v[146:147], v[206:207]
	v_pk_fma_f32 v[150:151], v[148:149], v[214:215], v[150:151]
	v_pk_mul_f32 v[152:153], v[146:147], v[228:229]
	v_add_f32_e32 v154, v150, v151
	v_pk_fma_f32 v[152:153], v[148:149], v[230:231], v[152:153]
	v_pk_mul_f32 v[142:143], v[146:147], v[208:209]
	v_add_f32_dpp v154, v154, v154 quad_perm:[1,0,3,2] row_mask:0xf bank_mask:0xf bound_ctrl:1
	v_pk_mul_f32 v[144:145], v[148:149], v[216:217]
	v_add_f32_e32 v162, v152, v153
	v_add_f32_dpp v154, v154, v154 quad_perm:[2,3,0,1] row_mask:0xf bank_mask:0xf bound_ctrl:1
	v_pk_fma_f32 v[142:143], v[240:241], v[212:213], v[142:143] op_sel:[1,0,0] op_sel_hi:[1,1,1]
	v_pk_fma_f32 v[144:145], v[240:241], v[220:221], v[144:145] op_sel:[1,0,0] op_sel_hi:[1,1,1]
	v_add_f32_dpp v154, v154, v154 row_half_mirror row_mask:0xf bank_mask:0xf bound_ctrl:1
	ds_read_b128 v[190:193], v182 offset:13824
	ds_read_b128 v[194:197], v182 offset:13840
	v_add_f32_dpp v154, v154, v154 row_mirror row_mask:0xf bank_mask:0xf bound_ctrl:1
	ds_read_b64 v[228:229], v182 offset:13856
	ds_read_b128 v[198:201], v183 offset:13824
	v_pk_fma_f32 v[142:143], v[154:155], v[210:211], v[142:143] op_sel_hi:[0,1,1]
	v_pk_fma_f32 v[144:145], v[154:155], v[218:219], v[144:145] op_sel_hi:[0,1,1]
	ds_read_b128 v[202:205], v183 offset:13840
	ds_read_b64 v[230:231], v183 offset:13856
	ds_read_b32 v240, v186 offset:576
	s_waitcnt lgkmcnt(7)
	v_pk_mul_f32 v[150:151], v[142:143], v[126:127]
	v_pk_fma_f32 v[150:151], v[144:145], v[134:135], v[150:151]
	v_pk_mul_f32 v[152:153], v[142:143], v[232:233]
	v_add_f32_e32 v154, v150, v151
	v_pk_fma_f32 v[152:153], v[144:145], v[234:235], v[152:153]
	v_pk_mul_f32 v[146:147], v[142:143], v[128:129]
	v_add_f32_dpp v154, v154, v154 quad_perm:[1,0,3,2] row_mask:0xf bank_mask:0xf bound_ctrl:1
	v_pk_mul_f32 v[148:149], v[144:145], v[136:137]
	v_add_f32_e32 v163, v152, v153
	v_add_f32_dpp v154, v154, v154 quad_perm:[2,3,0,1] row_mask:0xf bank_mask:0xf bound_ctrl:1
	v_pk_fma_f32 v[146:147], v[242:243], v[132:133], v[146:147] op_sel:[0,0,0] op_sel_hi:[0,1,1]
	v_pk_fma_f32 v[148:149], v[242:243], v[224:225], v[148:149] op_sel:[0,0,0] op_sel_hi:[0,1,1]
	v_add_f32_dpp v154, v154, v154 row_half_mirror row_mask:0xf bank_mask:0xf bound_ctrl:1
	ds_read_b128 v[206:209], v182 offset:15360
	ds_read_b128 v[210:213], v182 offset:15376
	v_add_f32_dpp v154, v154, v154 row_mirror row_mask:0xf bank_mask:0xf bound_ctrl:1
	ds_read_b64 v[232:233], v182 offset:15392
	ds_read_b128 v[214:217], v183 offset:15360
	v_pk_fma_f32 v[146:147], v[154:155], v[130:131], v[146:147] op_sel_hi:[0,1,1]
	v_pk_fma_f32 v[148:149], v[154:155], v[222:223], v[148:149] op_sel_hi:[0,1,1]
	ds_read_b128 v[218:221], v183 offset:15376
	ds_read_b64 v[234:235], v183 offset:15392
	ds_read_b32 v241, v186 offset:640
	s_waitcnt lgkmcnt(7)
	v_pk_mul_f32 v[150:151], v[146:147], v[190:191]
	v_pk_fma_f32 v[150:151], v[148:149], v[198:199], v[150:151]
	v_pk_mul_f32 v[152:153], v[146:147], v[236:237]
	v_add_f32_e32 v154, v150, v151
	v_pk_fma_f32 v[152:153], v[148:149], v[238:239], v[152:153]
	v_pk_mul_f32 v[142:143], v[146:147], v[192:193]
	v_add_f32_dpp v154, v154, v154 quad_perm:[1,0,3,2] row_mask:0xf bank_mask:0xf bound_ctrl:1
	v_pk_mul_f32 v[144:145], v[148:149], v[200:201]
	v_add_f32_e32 v164, v152, v153
	v_add_f32_dpp v154, v154, v154 quad_perm:[2,3,0,1] row_mask:0xf bank_mask:0xf bound_ctrl:1
	v_pk_fma_f32 v[142:143], v[240:241], v[196:197], v[142:143] op_sel:[0,0,0] op_sel_hi:[0,1,1]
	v_pk_fma_f32 v[144:145], v[240:241], v[204:205], v[144:145] op_sel:[0,0,0] op_sel_hi:[0,1,1]
	v_add_f32_dpp v154, v154, v154 row_half_mirror row_mask:0xf bank_mask:0xf bound_ctrl:1
	ds_read_b128 v[126:129], v182 offset:16896
	ds_read_b128 v[130:133], v182 offset:16912
	v_add_f32_dpp v154, v154, v154 row_mirror row_mask:0xf bank_mask:0xf bound_ctrl:1
	ds_read_b64 v[236:237], v182 offset:16928
	ds_read_b128 v[134:137], v183 offset:16896
	v_pk_fma_f32 v[142:143], v[154:155], v[194:195], v[142:143] op_sel_hi:[0,1,1]
	v_pk_fma_f32 v[144:145], v[154:155], v[202:203], v[144:145] op_sel_hi:[0,1,1]
	ds_read_b128 v[222:225], v183 offset:16912
	ds_read_b64 v[238:239], v183 offset:16928
	ds_read_b32 v242, v186 offset:704
	s_waitcnt lgkmcnt(7)
; __device__ __forceinline__ void wkv_phase(const WkvT& W, unsigned char* lds) {
;     ...
;                 for (int t = 0; t < 32; ++t) {
;                     const f32x2 a2 = {nA[0], nA[1]}, w2 = {nA[2], nA[3]}, b2 = {nB[0], nB[1]}, k2 = {nB[2], nB[3]}, r2 = nr; const float v = nv;
;                     if (t + 1 < 32) { nA = *(const f32x4*)(pp + (t + 1) * 384); nB = *(const f32x4*)(pp + (t + 1) * 384 + 4); nr = *(const f32x2*)(pp + (t + 1) * 384 + 8); nv = pv[(t + 1) * 16]; }
;                     float S0 = S.x, S1 = S.y;
;                     float d = S0 * a2.x; d = __builtin_fmaf(S1, a2.y, d);
;                     float t0 = S0 * w2.x; t0 = __builtin_fmaf(v, k2.x, t0); asm volatile("" : "+v"(t0));
;                     float t1 = S1 * w2.y; t1 = __builtin_fmaf(v, k2.y, t1); asm volatile("" : "+v"(t1));
;                     float yprev; const float sa = wkv_reduce(d, ep, yprev);
;                     S0 = __builtin_fmaf(sa, b2.x, t0); asm volatile("" : "+v"(S0));
;                     S1 = __builtin_fmaf(sa, b2.y, t1); asm volatile("" : "+v"(S1));
;                     ep = S0 * r2.x; ep = __builtin_fmaf(S1, r2.y, ep);
;                     S.x = S0; S.y = S1;
;                     if (t >= 1) { const bool hit = oddrow && ((lane & 15) == ((t - 1) & 15)); if (t <= 16) yk0 = hit ? yprev : yk0; else yk1 = hit ? yprev : yk1; }
	v_pk_mul_f32 v[150:151], v[142:143], v[206:207]
	v_pk_fma_f32 v[150:151], v[144:145], v[214:215], v[150:151]
	v_pk_mul_f32 v[152:153], v[142:143], v[228:229]
	v_add_f32_e32 v154, v150, v151
	v_pk_fma_f32 v[152:153], v[144:145], v[230:231], v[152:153]
	v_pk_mul_f32 v[146:147], v[142:143], v[208:209]
	v_add_f32_dpp v154, v154, v154 quad_perm:[1,0,3,2] row_mask:0xf bank_mask:0xf bound_ctrl:1
	v_pk_mul_f32 v[148:149], v[144:145], v[216:217]
	v_add_f32_e32 v165, v152, v153
	v_add_f32_dpp v154, v154, v154 quad_perm:[2,3,0,1] row_mask:0xf bank_mask:0xf bound_ctrl:1
	v_pk_fma_f32 v[146:147], v[240:241], v[212:213], v[146:147] op_sel:[1,0,0] op_sel_hi:[1,1,1]
	v_pk_fma_f32 v[148:149], v[240:241], v[220:221], v[148:149] op_sel:[1,0,0] op_sel_hi:[1,1,1]
	v_add_f32_dpp v154, v154, v154 row_half_mirror row_mask:0xf bank_mask:0xf bound_ctrl:1
	ds_read_b128 v[190:193], v182 offset:18432
	ds_read_b128 v[194:197], v182 offset:18448
	v_add_f32_dpp v154, v154, v154 row_mirror row_mask:0xf bank_mask:0xf bound_ctrl:1
	ds_read_b64 v[228:229], v182 offset:18464
	ds_read_b128 v[198:201], v183 offset:18432
	v_pk_fma_f32 v[146:147], v[154:155], v[210:211], v[146:147] op_sel_hi:[0,1,1]
	v_pk_fma_f32 v[148:149], v[154:155], v[218:219], v[148:149] op_sel_hi:[0,1,1]
	ds_read_b128 v[202:205], v183 offset:18448
	ds_read_b64 v[230:231], v183 offset:18464
	ds_read_b32 v240, v186 offset:768
	s_waitcnt lgkmcnt(7)
	v_pk_mul_f32 v[150:151], v[146:147], v[126:127]
	v_pk_fma_f32 v[150:151], v[148:149], v[134:135], v[150:151]
	v_pk_mul_f32 v[152:153], v[146:147], v[232:233]
	v_add_f32_e32 v154, v150, v151
	v_pk_fma_f32 v[152:153], v[148:149], v[234:235], v[152:153]
	v_pk_mul_f32 v[142:143], v[146:147], v[128:129]
	v_add_f32_dpp v154, v154, v154 quad_perm:[1,0,3,2] row_mask:0xf bank_mask:0xf bound_ctrl:1
	v_pk_mul_f32 v[144:145], v[148:149], v[136:137]
	v_add_f32_e32 v166, v152, v153
	v_add_f32_dpp v154, v154, v154 quad_perm:[2,3,0,1] row_mask:0xf bank_mask:0xf bound_ctrl:1
	v_pk_fma_f32 v[142:143], v[242:243], v[132:133], v[142:143] op_sel:[0,0,0] op_sel_hi:[0,1,1]
	v_pk_fma_f32 v[144:145], v[242:243], v[224:225], v[144:145] op_sel:[0,0,0] op_sel_hi:[0,1,1]
	v_add_f32_dpp v154, v154, v154 row_half_mirror row_mask:0xf bank_mask:0xf bound_ctrl:1
	ds_read_b128 v[206:209], v182 offset:19968
	ds_read_b128 v[210:213], v182 offset:19984
	v_add_f32_dpp v154, v154, v154 row_mirror row_mask:0xf bank_mask:0xf bound_ctrl:1
	ds_read_b64 v[232:233], v182 offset:20000
	ds_read_b128 v[214:217], v183 offset:19968
	v_pk_fma_f32 v[142:143], v[154:155], v[130:131], v[142:143] op_sel_hi:[0,1,1]
	v_pk_fma_f32 v[144:145], v[154:155], v[222:223], v[144:145] op_sel_hi:[0,1,1]
	ds_read_b128 v[218:221], v183 offset:19984
	ds_read_b64 v[234:235], v183 offset:20000
	ds_read_b32 v241, v186 offset:832
	s_waitcnt lgkmcnt(7)
	v_pk_mul_f32 v[150:151], v[142:143], v[190:191]
	v_pk_fma_f32 v[150:151], v[144:145], v[198:199], v[150:151]
	v_pk_mul_f32 v[152:153], v[142:143], v[236:237]
	v_add_f32_e32 v154, v150, v151
	v_pk_fma_f32 v[152:153], v[144:145], v[238:239], v[152:153]
	v_pk_mul_f32 v[146:147], v[142:143], v[192:193]
	v_add_f32_dpp v154, v154, v154 quad_perm:[1,0,3,2] row_mask:0xf bank_mask:0xf bound_ctrl:1
	v_pk_mul_f32 v[148:149], v[144:145], v[200:201]
	v_add_f32_e32 v167, v152, v153
	v_add_f32_dpp v154, v154, v154 quad_perm:[2,3,0,1] row_mask:0xf bank_mask:0xf bound_ctrl:1
	v_pk_fma_f32 v[146:147], v[240:241], v[196:197], v[146:147] op_sel:[0,0,0] op_sel_hi:[0,1,1]
	v_pk_fma_f32 v[148:149], v[240:241], v[204:205], v[148:149] op_sel:[0,0,0] op_sel_hi:[0,1,1]
	v_add_f32_dpp v154, v154, v154 row_half_mirror row_mask:0xf bank_mask:0xf bound_ctrl:1
	ds_read_b128 v[126:129], v182 offset:21504
	ds_read_b128 v[130:133], v182 offset:21520
	v_add_f32_dpp v154, v154, v154 row_mirror row_mask:0xf bank_mask:0xf bound_ctrl:1
	ds_read_b64 v[236:237], v182 offset:21536
	ds_read_b128 v[134:137], v183 offset:21504
	v_pk_fma_f32 v[146:147], v[154:155], v[194:195], v[146:147] op_sel_hi:[0,1,1]
	v_pk_fma_f32 v[148:149], v[154:155], v[202:203], v[148:149] op_sel_hi:[0,1,1]
	ds_read_b128 v[222:225], v183 offset:21520
	ds_read_b64 v[238:239], v183 offset:21536
	ds_read_b32 v242, v186 offset:896
	s_waitcnt lgkmcnt(7)
	v_pk_mul_f32 v[150:151], v[146:147], v[206:207]
	v_pk_fma_f32 v[150:151], v[148:149], v[214:215], v[150:151]
	v_pk_mul_f32 v[152:153], v[146:147], v[228:229]
	v_add_f32_e32 v154, v150, v151
	v_pk_fma_f32 v[152:153], v[148:149], v[230:231], v[152:153]
	v_pk_mul_f32 v[142:143], v[146:147], v[208:209]
	v_add_f32_dpp v154, v154, v154 quad_perm:[1,0,3,2] row_mask:0xf bank_mask:0xf bound_ctrl:1
	v_pk_mul_f32 v[144:145], v[148:149], v[216:217]
	v_add_f32_e32 v168, v152, v153
	v_add_f32_dpp v154, v154, v154 quad_perm:[2,3,0,1] row_mask:0xf bank_mask:0xf bound_ctrl:1
	v_pk_fma_f32 v[142:143], v[240:241], v[212:213], v[142:143] op_sel:[1,0,0] op_sel_hi:[1,1,1]
	v_pk_fma_f32 v[144:145], v[240:241], v[220:221], v[144:145] op_sel:[1,0,0] op_sel_hi:[1,1,1]
	v_add_f32_dpp v154, v154, v154 row_half_mirror row_mask:0xf bank_mask:0xf bound_ctrl:1
	ds_read_b128 v[190:193], v182 offset:23040
	ds_read_b128 v[194:197], v182 offset:23056
	v_add_f32_dpp v154, v154, v154 row_mirror row_mask:0xf bank_mask:0xf bound_ctrl:1
	ds_read_b64 v[228:229], v182 offset:23072
	ds_read_b128 v[198:201], v183 offset:23040
	v_pk_fma_f32 v[142:143], v[154:155], v[210:211], v[142:143] op_sel_hi:[0,1,1]
	v_pk_fma_f32 v[144:145], v[154:155], v[218:219], v[144:145] op_sel_hi:[0,1,1]
	ds_read_b128 v[202:205], v183 offset:23056
	ds_read_b64 v[230:231], v183 offset:23072
	ds_read_b32 v240, v186 offset:960
	s_waitcnt lgkmcnt(7)
; __device__ __forceinline__ void wkv_phase(const WkvT& W, unsigned char* lds) {
;     ...
;                 for (int t = 0; t < 32; ++t) {
;                     const f32x2 a2 = {nA[0], nA[1]}, w2 = {nA[2], nA[3]}, b2 = {nB[0], nB[1]}, k2 = {nB[2], nB[3]}, r2 = nr; const float v = nv;
;                     if (t + 1 < 32) { nA = *(const f32x4*)(pp + (t + 1) * 384); nB = *(const f32x4*)(pp + (t + 1) * 384 + 4); nr = *(const f32x2*)(pp + (t + 1) * 384 + 8); nv = pv[(t + 1) * 16]; }
;                     float S0 = S.x, S1 = S.y;
;                     float d = S0 * a2.x; d = __builtin_fmaf(S1, a2.y, d);
;                     float t0 = S0 * w2.x; t0 = __builtin_fmaf(v, k2.x, t0); asm volatile("" : "+v"(t0));
;                     float t1 = S1 * w2.y; t1 = __builtin_fmaf(v, k2.y, t1); asm volatile("" : "+v"(t1));
;                     float yprev; const float sa = wkv_reduce(d, ep, yprev);
;                     S0 = __builtin_fmaf(sa, b2.x, t0); asm volatile("" : "+v"(S0));
;                     S1 = __builtin_fmaf(sa, b2.y, t1); asm volatile("" : "+v"(S1));
;                     ep = S0 * r2.x; ep = __builtin_fmaf(S1, r2.y, ep);
;                     S.x = S0; S.y = S1;
;                     if (t >= 1) { const bool hit = oddrow && ((lane & 15) == ((t - 1) & 15)); if (t <= 16) yk0 = hit ? yprev : yk0; else yk1 = hit ? yprev : yk1; }
;                 }
;                 { float ylast; (void)wkv_reduce(0.f, ep, ylast); yk1 = (oddrow && (lane & 15) == 15) ? ylast : yk1; }
;                 if (oddrow) { sY[bi * 512 + (lane & 15) * 16 + il] = yk0; sY[bi * 512 + (16 + (lane & 15)) * 16 + il] = yk1; }
	v_pk_mul_f32 v[150:151], v[142:143], v[126:127]
	v_pk_fma_f32 v[150:151], v[144:145], v[134:135], v[150:151]
	v_pk_mul_f32 v[152:153], v[142:143], v[232:233]
	v_add_f32_e32 v154, v150, v151
	v_pk_fma_f32 v[152:153], v[144:145], v[234:235], v[152:153]
	v_pk_mul_f32 v[146:147], v[142:143], v[128:129]
	v_add_f32_dpp v154, v154, v154 quad_perm:[1,0,3,2] row_mask:0xf bank_mask:0xf bound_ctrl:1
	v_pk_mul_f32 v[148:149], v[144:145], v[136:137]
	v_add_f32_e32 v169, v152, v153
	v_add_f32_dpp v154, v154, v154 quad_perm:[2,3,0,1] row_mask:0xf bank_mask:0xf bound_ctrl:1
	v_pk_fma_f32 v[146:147], v[242:243], v[132:133], v[146:147] op_sel:[0,0,0] op_sel_hi:[0,1,1]
	v_pk_fma_f32 v[148:149], v[242:243], v[224:225], v[148:149] op_sel:[0,0,0] op_sel_hi:[0,1,1]
	v_add_f32_dpp v154, v154, v154 row_half_mirror row_mask:0xf bank_mask:0xf bound_ctrl:1
	ds_read_b128 v[206:209], v182 offset:24576
	ds_read_b128 v[210:213], v182 offset:24592
	v_add_f32_dpp v154, v154, v154 row_mirror row_mask:0xf bank_mask:0xf bound_ctrl:1
	ds_read_b64 v[232:233], v182 offset:24608
	ds_read_b128 v[214:217], v183 offset:24576
	v_pk_fma_f32 v[146:147], v[154:155], v[130:131], v[146:147] op_sel_hi:[0,1,1]
	v_pk_fma_f32 v[148:149], v[154:155], v[222:223], v[148:149] op_sel_hi:[0,1,1]
	ds_read_b128 v[218:221], v183 offset:24592
	ds_read_b64 v[234:235], v183 offset:24608
	ds_read_b32 v241, v186 offset:1024
	s_waitcnt lgkmcnt(7)
	v_pk_mul_f32 v[150:151], v[146:147], v[190:191]
	v_pk_fma_f32 v[150:151], v[148:149], v[198:199], v[150:151]
	v_pk_mul_f32 v[152:153], v[146:147], v[236:237]
	v_add_f32_e32 v154, v150, v151
	v_pk_fma_f32 v[152:153], v[148:149], v[238:239], v[152:153]
	v_pk_mul_f32 v[142:143], v[146:147], v[192:193]
	v_add_f32_dpp v154, v154, v154 quad_perm:[1,0,3,2] row_mask:0xf bank_mask:0xf bound_ctrl:1
	v_pk_mul_f32 v[144:145], v[148:149], v[200:201]
	v_add_f32_e32 v170, v152, v153
	v_add_f32_dpp v154, v154, v154 quad_perm:[2,3,0,1] row_mask:0xf bank_mask:0xf bound_ctrl:1
	v_pk_fma_f32 v[142:143], v[240:241], v[196:197], v[142:143] op_sel:[0,0,0] op_sel_hi:[0,1,1]
	v_pk_fma_f32 v[144:145], v[240:241], v[204:205], v[144:145] op_sel:[0,0,0] op_sel_hi:[0,1,1]
	v_add_f32_dpp v154, v154, v154 row_half_mirror row_mask:0xf bank_mask:0xf bound_ctrl:1
	ds_read_b128 v[126:129], v182 offset:26112
	ds_read_b128 v[130:133], v182 offset:26128
	v_add_f32_dpp v154, v154, v154 row_mirror row_mask:0xf bank_mask:0xf bound_ctrl:1
	ds_read_b64 v[236:237], v182 offset:26144
	ds_read_b128 v[134:137], v183 offset:26112
	v_pk_fma_f32 v[142:143], v[154:155], v[194:195], v[142:143] op_sel_hi:[0,1,1]
	v_pk_fma_f32 v[144:145], v[154:155], v[202:203], v[144:145] op_sel_hi:[0,1,1]
	ds_read_b128 v[222:225], v183 offset:26128
	ds_read_b64 v[238:239], v183 offset:26144
	ds_read_b32 v242, v186 offset:1088
	s_waitcnt lgkmcnt(7)
	v_pk_mul_f32 v[150:151], v[142:143], v[206:207]
	v_pk_fma_f32 v[150:151], v[144:145], v[214:215], v[150:151]
	v_pk_mul_f32 v[152:153], v[142:143], v[228:229]
	v_add_f32_e32 v154, v150, v151
	v_pk_fma_f32 v[152:153], v[144:145], v[230:231], v[152:153]
	v_pk_mul_f32 v[146:147], v[142:143], v[208:209]
	v_add_f32_dpp v154, v154, v154 quad_perm:[1,0,3,2] row_mask:0xf bank_mask:0xf bound_ctrl:1
	v_pk_mul_f32 v[148:149], v[144:145], v[216:217]
	v_add_f32_e32 v171, v152, v153
	v_add_f32_dpp v154, v154, v154 quad_perm:[2,3,0,1] row_mask:0xf bank_mask:0xf bound_ctrl:1
	v_pk_fma_f32 v[146:147], v[240:241], v[212:213], v[146:147] op_sel:[1,0,0] op_sel_hi:[1,1,1]
	v_pk_fma_f32 v[148:149], v[240:241], v[220:221], v[148:149] op_sel:[1,0,0] op_sel_hi:[1,1,1]
	v_add_f32_dpp v154, v154, v154 row_half_mirror row_mask:0xf bank_mask:0xf bound_ctrl:1
	ds_read_b128 v[190:193], v182 offset:27648
	ds_read_b128 v[194:197], v182 offset:27664
	v_add_f32_dpp v154, v154, v154 row_mirror row_mask:0xf bank_mask:0xf bound_ctrl:1
	ds_read_b64 v[228:229], v182 offset:27680
	ds_read_b128 v[198:201], v183 offset:27648
	v_pk_fma_f32 v[146:147], v[154:155], v[210:211], v[146:147] op_sel_hi:[0,1,1]
	v_pk_fma_f32 v[148:149], v[154:155], v[218:219], v[148:149] op_sel_hi:[0,1,1]
	ds_read_b128 v[202:205], v183 offset:27664
	ds_read_b64 v[230:231], v183 offset:27680
	ds_read_b32 v240, v186 offset:1152
	s_waitcnt lgkmcnt(7)
	v_cndmask_b32_e64 v172, v164, v156, s[10:11]
	v_cndmask_b32_e64 v174, v165, v157, s[10:11]
	v_cndmask_b32_e64 v176, v166, v158, s[10:11]
	v_cndmask_b32_e64 v178, v167, v159, s[10:11]
	v_cndmask_b32_e64 v173, v156, v164, s[10:11]
	v_cndmask_b32_e64 v175, v157, v165, s[10:11]
	v_cndmask_b32_e64 v177, v158, v166, s[10:11]
	v_cndmask_b32_e64 v179, v159, v167, s[10:11]
	v_add_f32_dpp v156, v172, v173 row_ror:8 row_mask:0xf bank_mask:0xf
	v_add_f32_dpp v157, v174, v175 row_ror:8 row_mask:0xf bank_mask:0xf
	v_add_f32_dpp v158, v176, v177 row_ror:8 row_mask:0xf bank_mask:0xf
	v_add_f32_dpp v159, v178, v179 row_ror:8 row_mask:0xf bank_mask:0xf
	v_cndmask_b32_e64 v172, v168, v160, s[10:11]
	v_cndmask_b32_e64 v174, v169, v161, s[10:11]
	v_cndmask_b32_e64 v176, v170, v162, s[10:11]
	v_cndmask_b32_e64 v178, v171, v163, s[10:11]
	v_cndmask_b32_e64 v173, v160, v168, s[10:11]
	v_cndmask_b32_e64 v175, v161, v169, s[10:11]
	v_cndmask_b32_e64 v177, v162, v170, s[10:11]
	v_cndmask_b32_e64 v179, v163, v171, s[10:11]
	v_add_f32_dpp v160, v172, v173 row_ror:8 row_mask:0xf bank_mask:0xf
	v_add_f32_dpp v161, v174, v175 row_ror:8 row_mask:0xf bank_mask:0xf
	v_add_f32_dpp v162, v176, v177 row_ror:8 row_mask:0xf bank_mask:0xf
	v_add_f32_dpp v163, v178, v179 row_ror:8 row_mask:0xf bank_mask:0xf
	v_cndmask_b32_e64 v172, v160, v156, s[12:13]
	v_cndmask_b32_e64 v174, v161, v157, s[12:13]
	v_cndmask_b32_e64 v176, v162, v158, s[12:13]
; __device__ __forceinline__ void wkv_phase(const WkvT& W, unsigned char* lds) {
;     ...
;                 for (int t = 0; t < 32; ++t) {
;                     const f32x2 a2 = {nA[0], nA[1]}, w2 = {nA[2], nA[3]}, b2 = {nB[0], nB[1]}, k2 = {nB[2], nB[3]}, r2 = nr; const float v = nv;
;                     if (t + 1 < 32) { nA = *(const f32x4*)(pp + (t + 1) * 384); nB = *(const f32x4*)(pp + (t + 1) * 384 + 4); nr = *(const f32x2*)(pp + (t + 1) * 384 + 8); nv = pv[(t + 1) * 16]; }
;                     float S0 = S.x, S1 = S.y;
;                     float d = S0 * a2.x; d = __builtin_fmaf(S1, a2.y, d);
;                     float t0 = S0 * w2.x; t0 = __builtin_fmaf(v, k2.x, t0); asm volatile("" : "+v"(t0));
;                     float t1 = S1 * w2.y; t1 = __builtin_fmaf(v, k2.y, t1); asm volatile("" : "+v"(t1));
;                     float yprev; const float sa = wkv_reduce(d, ep, yprev);
;                     S0 = __builtin_fmaf(sa, b2.x, t0); asm volatile("" : "+v"(S0));
;                     S1 = __builtin_fmaf(sa, b2.y, t1); asm volatile("" : "+v"(S1));
;                     ep = S0 * r2.x; ep = __builtin_fmaf(S1, r2.y, ep);
;                     S.x = S0; S.y = S1;
;                     if (t >= 1) { const bool hit = oddrow && ((lane & 15) == ((t - 1) & 15)); if (t <= 16) yk0 = hit ? yprev : yk0; else yk1 = hit ? yprev : yk1; }
;                 }
;                 { float ylast; (void)wkv_reduce(0.f, ep, ylast); yk1 = (oddrow && (lane & 15) == 15) ? ylast : yk1; }
;                 if (oddrow) { sY[bi * 512 + (lane & 15) * 16 + il] = yk0; sY[bi * 512 + (16 + (lane & 15)) * 16 + il] = yk1; }
	v_cndmask_b32_e64 v178, v163, v159, s[12:13]
	v_cndmask_b32_e64 v173, v156, v160, s[12:13]
	v_cndmask_b32_e64 v175, v157, v161, s[12:13]
	v_cndmask_b32_e64 v177, v158, v162, s[12:13]
	v_cndmask_b32_e64 v179, v159, v163, s[12:13]
	v_add_f32_dpp v156, v172, v173 row_half_mirror row_mask:0xf bank_mask:0xf
	v_add_f32_dpp v157, v174, v175 row_half_mirror row_mask:0xf bank_mask:0xf
	v_add_f32_dpp v158, v176, v177 row_half_mirror row_mask:0xf bank_mask:0xf
	v_add_f32_dpp v159, v178, v179 row_half_mirror row_mask:0xf bank_mask:0xf
	v_cndmask_b32_e64 v172, v158, v156, s[14:15]
	v_cndmask_b32_e64 v174, v159, v157, s[14:15]
	v_cndmask_b32_e64 v173, v156, v158, s[14:15]
	v_cndmask_b32_e64 v175, v157, v159, s[14:15]
	v_add_f32_dpp v156, v172, v173 quad_perm:[2,3,0,1] row_mask:0xf bank_mask:0xf
	v_add_f32_dpp v157, v174, v175 quad_perm:[2,3,0,1] row_mask:0xf bank_mask:0xf
	v_cndmask_b32_e64 v172, v157, v156, s[16:17]
	v_cndmask_b32_e64 v173, v156, v157, s[16:17]
	s_nop 0
	v_add_f32_dpp v156, v172, v173 quad_perm:[1,0,3,2] row_mask:0xf bank_mask:0xf
	v_mov_b32_e32 v180, v156
	v_pk_mul_f32 v[150:151], v[146:147], v[126:127]
	v_pk_fma_f32 v[150:151], v[148:149], v[134:135], v[150:151]
	v_pk_mul_f32 v[152:153], v[146:147], v[232:233]
	v_add_f32_e32 v154, v150, v151
	v_pk_fma_f32 v[152:153], v[148:149], v[234:235], v[152:153]
	v_pk_mul_f32 v[142:143], v[146:147], v[128:129]
	v_add_f32_dpp v154, v154, v154 quad_perm:[1,0,3,2] row_mask:0xf bank_mask:0xf bound_ctrl:1
	v_pk_mul_f32 v[144:145], v[148:149], v[136:137]
	v_add_f32_e32 v156, v152, v153
	v_add_f32_dpp v154, v154, v154 quad_perm:[2,3,0,1] row_mask:0xf bank_mask:0xf bound_ctrl:1
	v_pk_fma_f32 v[142:143], v[242:243], v[132:133], v[142:143] op_sel:[0,0,0] op_sel_hi:[0,1,1]
	v_pk_fma_f32 v[144:145], v[242:243], v[224:225], v[144:145] op_sel:[0,0,0] op_sel_hi:[0,1,1]
	v_add_f32_dpp v154, v154, v154 row_half_mirror row_mask:0xf bank_mask:0xf bound_ctrl:1
	ds_read_b128 v[206:209], v182 offset:29184
	ds_read_b128 v[210:213], v182 offset:29200
	v_add_f32_dpp v154, v154, v154 row_mirror row_mask:0xf bank_mask:0xf bound_ctrl:1
	ds_read_b64 v[232:233], v182 offset:29216
	ds_read_b128 v[214:217], v183 offset:29184
	v_pk_fma_f32 v[142:143], v[154:155], v[130:131], v[142:143] op_sel_hi:[0,1,1]
	v_pk_fma_f32 v[144:145], v[154:155], v[222:223], v[144:145] op_sel_hi:[0,1,1]
	ds_read_b128 v[218:221], v183 offset:29200
	ds_read_b64 v[234:235], v183 offset:29216
	ds_read_b32 v241, v186 offset:1216
	s_waitcnt lgkmcnt(7)
	v_pk_mul_f32 v[150:151], v[142:143], v[190:191]
	v_pk_fma_f32 v[150:151], v[144:145], v[198:199], v[150:151]
	v_pk_mul_f32 v[152:153], v[142:143], v[236:237]
	v_add_f32_e32 v154, v150, v151
	v_pk_fma_f32 v[152:153], v[144:145], v[238:239], v[152:153]
	v_pk_mul_f32 v[146:147], v[142:143], v[192:193]
	v_add_f32_dpp v154, v154, v154 quad_perm:[1,0,3,2] row_mask:0xf bank_mask:0xf bound_ctrl:1
	v_pk_mul_f32 v[148:149], v[144:145], v[200:201]
	v_add_f32_e32 v157, v152, v153
	v_add_f32_dpp v154, v154, v154 quad_perm:[2,3,0,1] row_mask:0xf bank_mask:0xf bound_ctrl:1
	v_pk_fma_f32 v[146:147], v[240:241], v[196:197], v[146:147] op_sel:[0,0,0] op_sel_hi:[0,1,1]
	v_pk_fma_f32 v[148:149], v[240:241], v[204:205], v[148:149] op_sel:[0,0,0] op_sel_hi:[0,1,1]
	v_add_f32_dpp v154, v154, v154 row_half_mirror row_mask:0xf bank_mask:0xf bound_ctrl:1
	ds_read_b128 v[126:129], v182 offset:30720
	ds_read_b128 v[130:133], v182 offset:30736
	v_add_f32_dpp v154, v154, v154 row_mirror row_mask:0xf bank_mask:0xf bound_ctrl:1
	ds_read_b64 v[236:237], v182 offset:30752
	ds_read_b128 v[134:137], v183 offset:30720
	v_pk_fma_f32 v[146:147], v[154:155], v[194:195], v[146:147] op_sel_hi:[0,1,1]
	v_pk_fma_f32 v[148:149], v[154:155], v[202:203], v[148:149] op_sel_hi:[0,1,1]
	ds_read_b128 v[222:225], v183 offset:30736
	ds_read_b64 v[238:239], v183 offset:30752
	ds_read_b32 v242, v186 offset:1280
	s_waitcnt lgkmcnt(7)
	v_pk_mul_f32 v[150:151], v[146:147], v[206:207]
	v_pk_fma_f32 v[150:151], v[148:149], v[214:215], v[150:151]
	v_pk_mul_f32 v[152:153], v[146:147], v[228:229]
	v_add_f32_e32 v154, v150, v151
	v_pk_fma_f32 v[152:153], v[148:149], v[230:231], v[152:153]
	v_pk_mul_f32 v[142:143], v[146:147], v[208:209]
	v_add_f32_dpp v154, v154, v154 quad_perm:[1,0,3,2] row_mask:0xf bank_mask:0xf bound_ctrl:1
	v_pk_mul_f32 v[144:145], v[148:149], v[216:217]
	v_add_f32_e32 v158, v152, v153
	v_add_f32_dpp v154, v154, v154 quad_perm:[2,3,0,1] row_mask:0xf bank_mask:0xf bound_ctrl:1
	v_pk_fma_f32 v[142:143], v[240:241], v[212:213], v[142:143] op_sel:[1,0,0] op_sel_hi:[1,1,1]
	v_pk_fma_f32 v[144:145], v[240:241], v[220:221], v[144:145] op_sel:[1,0,0] op_sel_hi:[1,1,1]
	v_add_f32_dpp v154, v154, v154 row_half_mirror row_mask:0xf bank_mask:0xf bound_ctrl:1
	ds_read_b128 v[190:193], v182 offset:32256
	ds_read_b128 v[194:197], v182 offset:32272
	v_add_f32_dpp v154, v154, v154 row_mirror row_mask:0xf bank_mask:0xf bound_ctrl:1
	ds_read_b64 v[228:229], v182 offset:32288
	ds_read_b128 v[198:201], v183 offset:32256
	v_pk_fma_f32 v[142:143], v[154:155], v[210:211], v[142:143] op_sel_hi:[0,1,1]
	v_pk_fma_f32 v[144:145], v[154:155], v[218:219], v[144:145] op_sel_hi:[0,1,1]
	ds_read_b128 v[202:205], v183 offset:32272
	ds_read_b64 v[230:231], v183 offset:32288
	ds_read_b32 v240, v186 offset:1344
	s_waitcnt lgkmcnt(7)
; __device__ __forceinline__ void wkv_phase(const WkvT& W, unsigned char* lds) {
;     ...
;                 for (int t = 0; t < 32; ++t) {
;                     const f32x2 a2 = {nA[0], nA[1]}, w2 = {nA[2], nA[3]}, b2 = {nB[0], nB[1]}, k2 = {nB[2], nB[3]}, r2 = nr; const float v = nv;
;                     if (t + 1 < 32) { nA = *(const f32x4*)(pp + (t + 1) * 384); nB = *(const f32x4*)(pp + (t + 1) * 384 + 4); nr = *(const f32x2*)(pp + (t + 1) * 384 + 8); nv = pv[(t + 1) * 16]; }
;                     float S0 = S.x, S1 = S.y;
;                     float d = S0 * a2.x; d = __builtin_fmaf(S1, a2.y, d);
;                     float t0 = S0 * w2.x; t0 = __builtin_fmaf(v, k2.x, t0); asm volatile("" : "+v"(t0));
;                     float t1 = S1 * w2.y; t1 = __builtin_fmaf(v, k2.y, t1); asm volatile("" : "+v"(t1));
;                     float yprev; const float sa = wkv_reduce(d, ep, yprev);
;                     S0 = __builtin_fmaf(sa, b2.x, t0); asm volatile("" : "+v"(S0));
;                     S1 = __builtin_fmaf(sa, b2.y, t1); asm volatile("" : "+v"(S1));
;                     ep = S0 * r2.x; ep = __builtin_fmaf(S1, r2.y, ep);
;                     S.x = S0; S.y = S1;
;                     if (t >= 1) { const bool hit = oddrow && ((lane & 15) == ((t - 1) & 15)); if (t <= 16) yk0 = hit ? yprev : yk0; else yk1 = hit ? yprev : yk1; }
;                 }
	v_pk_mul_f32 v[150:151], v[142:143], v[126:127]
	v_pk_fma_f32 v[150:151], v[144:145], v[134:135], v[150:151]
	v_pk_mul_f32 v[152:153], v[142:143], v[232:233]
	v_add_f32_e32 v154, v150, v151
	v_pk_fma_f32 v[152:153], v[144:145], v[234:235], v[152:153]
	v_pk_mul_f32 v[146:147], v[142:143], v[128:129]
	v_add_f32_dpp v154, v154, v154 quad_perm:[1,0,3,2] row_mask:0xf bank_mask:0xf bound_ctrl:1
	v_pk_mul_f32 v[148:149], v[144:145], v[136:137]
	v_add_f32_e32 v159, v152, v153
	v_add_f32_dpp v154, v154, v154 quad_perm:[2,3,0,1] row_mask:0xf bank_mask:0xf bound_ctrl:1
	v_pk_fma_f32 v[146:147], v[242:243], v[132:133], v[146:147] op_sel:[0,0,0] op_sel_hi:[0,1,1]
	v_pk_fma_f32 v[148:149], v[242:243], v[224:225], v[148:149] op_sel:[0,0,0] op_sel_hi:[0,1,1]
	v_add_f32_dpp v154, v154, v154 row_half_mirror row_mask:0xf bank_mask:0xf bound_ctrl:1
	ds_read_b128 v[206:209], v182 offset:33792
	ds_read_b128 v[210:213], v182 offset:33808
	v_add_f32_dpp v154, v154, v154 row_mirror row_mask:0xf bank_mask:0xf bound_ctrl:1
	ds_read_b64 v[232:233], v182 offset:33824
	ds_read_b128 v[214:217], v183 offset:33792
	v_pk_fma_f32 v[146:147], v[154:155], v[130:131], v[146:147] op_sel_hi:[0,1,1]
	v_pk_fma_f32 v[148:149], v[154:155], v[222:223], v[148:149] op_sel_hi:[0,1,1]
	ds_read_b128 v[218:221], v183 offset:33808
	ds_read_b64 v[234:235], v183 offset:33824
	ds_read_b32 v241, v186 offset:1408
	s_waitcnt lgkmcnt(7)
	v_pk_mul_f32 v[150:151], v[146:147], v[190:191]
	v_pk_fma_f32 v[150:151], v[148:149], v[198:199], v[150:151]
	v_pk_mul_f32 v[152:153], v[146:147], v[236:237]
	v_add_f32_e32 v154, v150, v151
	v_pk_fma_f32 v[152:153], v[148:149], v[238:239], v[152:153]
	v_pk_mul_f32 v[142:143], v[146:147], v[192:193]
	v_add_f32_dpp v154, v154, v154 quad_perm:[1,0,3,2] row_mask:0xf bank_mask:0xf bound_ctrl:1
	v_pk_mul_f32 v[144:145], v[148:149], v[200:201]
	v_add_f32_e32 v160, v152, v153
	v_add_f32_dpp v154, v154, v154 quad_perm:[2,3,0,1] row_mask:0xf bank_mask:0xf bound_ctrl:1
	v_pk_fma_f32 v[142:143], v[240:241], v[196:197], v[142:143] op_sel:[0,0,0] op_sel_hi:[0,1,1]
	v_pk_fma_f32 v[144:145], v[240:241], v[204:205], v[144:145] op_sel:[0,0,0] op_sel_hi:[0,1,1]
	v_add_f32_dpp v154, v154, v154 row_half_mirror row_mask:0xf bank_mask:0xf bound_ctrl:1
	ds_read_b128 v[126:129], v182 offset:35328
	ds_read_b128 v[130:133], v182 offset:35344
	v_add_f32_dpp v154, v154, v154 row_mirror row_mask:0xf bank_mask:0xf bound_ctrl:1
	ds_read_b64 v[236:237], v182 offset:35360
	ds_read_b128 v[134:137], v183 offset:35328
	v_pk_fma_f32 v[142:143], v[154:155], v[194:195], v[142:143] op_sel_hi:[0,1,1]
	v_pk_fma_f32 v[144:145], v[154:155], v[202:203], v[144:145] op_sel_hi:[0,1,1]
	ds_read_b128 v[222:225], v183 offset:35344
	ds_read_b64 v[238:239], v183 offset:35360
	ds_read_b32 v242, v186 offset:1472
	s_waitcnt lgkmcnt(7)
	v_pk_mul_f32 v[150:151], v[142:143], v[206:207]
	v_pk_fma_f32 v[150:151], v[144:145], v[214:215], v[150:151]
	v_pk_mul_f32 v[152:153], v[142:143], v[228:229]
	v_add_f32_e32 v154, v150, v151
	v_pk_fma_f32 v[152:153], v[144:145], v[230:231], v[152:153]
	v_pk_mul_f32 v[146:147], v[142:143], v[208:209]
	v_add_f32_dpp v154, v154, v154 quad_perm:[1,0,3,2] row_mask:0xf bank_mask:0xf bound_ctrl:1
	v_pk_mul_f32 v[148:149], v[144:145], v[216:217]
	v_add_f32_e32 v161, v152, v153
	v_add_f32_dpp v154, v154, v154 quad_perm:[2,3,0,1] row_mask:0xf bank_mask:0xf bound_ctrl:1
	v_pk_fma_f32 v[146:147], v[240:241], v[212:213], v[146:147] op_sel:[1,0,0] op_sel_hi:[1,1,1]
	v_pk_fma_f32 v[148:149], v[240:241], v[220:221], v[148:149] op_sel:[1,0,0] op_sel_hi:[1,1,1]
	v_add_f32_dpp v154, v154, v154 row_half_mirror row_mask:0xf bank_mask:0xf bound_ctrl:1
	ds_read_b128 v[190:193], v182 offset:36864
	ds_read_b128 v[194:197], v182 offset:36880
	v_add_f32_dpp v154, v154, v154 row_mirror row_mask:0xf bank_mask:0xf bound_ctrl:1
	ds_read_b64 v[228:229], v182 offset:36896
	ds_read_b128 v[198:201], v183 offset:36864
	v_pk_fma_f32 v[146:147], v[154:155], v[210:211], v[146:147] op_sel_hi:[0,1,1]
	v_pk_fma_f32 v[148:149], v[154:155], v[218:219], v[148:149] op_sel_hi:[0,1,1]
	ds_read_b128 v[202:205], v183 offset:36880
	ds_read_b64 v[230:231], v183 offset:36896
	ds_read_b32 v240, v186 offset:1536
	s_waitcnt lgkmcnt(7)
	v_pk_mul_f32 v[150:151], v[146:147], v[126:127]
	v_pk_fma_f32 v[150:151], v[148:149], v[134:135], v[150:151]
	v_pk_mul_f32 v[152:153], v[146:147], v[232:233]
	v_add_f32_e32 v154, v150, v151
	v_pk_fma_f32 v[152:153], v[148:149], v[234:235], v[152:153]
	v_pk_mul_f32 v[142:143], v[146:147], v[128:129]
	v_add_f32_dpp v154, v154, v154 quad_perm:[1,0,3,2] row_mask:0xf bank_mask:0xf bound_ctrl:1
	v_pk_mul_f32 v[144:145], v[148:149], v[136:137]
	v_add_f32_e32 v162, v152, v153
	v_add_f32_dpp v154, v154, v154 quad_perm:[2,3,0,1] row_mask:0xf bank_mask:0xf bound_ctrl:1
	v_pk_fma_f32 v[142:143], v[242:243], v[132:133], v[142:143] op_sel:[0,0,0] op_sel_hi:[0,1,1]
	v_pk_fma_f32 v[144:145], v[242:243], v[224:225], v[144:145] op_sel:[0,0,0] op_sel_hi:[0,1,1]
	v_add_f32_dpp v154, v154, v154 row_half_mirror row_mask:0xf bank_mask:0xf bound_ctrl:1
	ds_read_b128 v[206:209], v182 offset:38400
	ds_read_b128 v[210:213], v182 offset:38416
	v_add_f32_dpp v154, v154, v154 row_mirror row_mask:0xf bank_mask:0xf bound_ctrl:1
	ds_read_b64 v[232:233], v182 offset:38432
	ds_read_b128 v[214:217], v183 offset:38400
	v_pk_fma_f32 v[142:143], v[154:155], v[130:131], v[142:143] op_sel_hi:[0,1,1]
	v_pk_fma_f32 v[144:145], v[154:155], v[222:223], v[144:145] op_sel_hi:[0,1,1]
	ds_read_b128 v[218:221], v183 offset:38416
	ds_read_b64 v[234:235], v183 offset:38432
	ds_read_b32 v241, v186 offset:1600
	s_waitcnt lgkmcnt(7)
; __device__ __forceinline__ void wkv_phase(const WkvT& W, unsigned char* lds) {
;     ...
;                 for (int t = 0; t < 32; ++t) {
;                     const f32x2 a2 = {nA[0], nA[1]}, w2 = {nA[2], nA[3]}, b2 = {nB[0], nB[1]}, k2 = {nB[2], nB[3]}, r2 = nr; const float v = nv;
;                     if (t + 1 < 32) { nA = *(const f32x4*)(pp + (t + 1) * 384); nB = *(const f32x4*)(pp + (t + 1) * 384 + 4); nr = *(const f32x2*)(pp + (t + 1) * 384 + 8); nv = pv[(t + 1) * 16]; }
;                     float S0 = S.x, S1 = S.y;
;                     float d = S0 * a2.x; d = __builtin_fmaf(S1, a2.y, d);
;                     float t0 = S0 * w2.x; t0 = __builtin_fmaf(v, k2.x, t0); asm volatile("" : "+v"(t0));
;                     float t1 = S1 * w2.y; t1 = __builtin_fmaf(v, k2.y, t1); asm volatile("" : "+v"(t1));
;                     float yprev; const float sa = wkv_reduce(d, ep, yprev);
;                     S0 = __builtin_fmaf(sa, b2.x, t0); asm volatile("" : "+v"(S0));
;                     S1 = __builtin_fmaf(sa, b2.y, t1); asm volatile("" : "+v"(S1));
;                     ep = S0 * r2.x; ep = __builtin_fmaf(S1, r2.y, ep);
;                     S.x = S0; S.y = S1;
;                     if (t >= 1) { const bool hit = oddrow && ((lane & 15) == ((t - 1) & 15)); if (t <= 16) yk0 = hit ? yprev : yk0; else yk1 = hit ? yprev : yk1; }
;                 }
	v_pk_mul_f32 v[150:151], v[142:143], v[190:191]
	v_pk_fma_f32 v[150:151], v[144:145], v[198:199], v[150:151]
	v_pk_mul_f32 v[152:153], v[142:143], v[236:237]
	v_add_f32_e32 v154, v150, v151
	v_pk_fma_f32 v[152:153], v[144:145], v[238:239], v[152:153]
	v_pk_mul_f32 v[146:147], v[142:143], v[192:193]
	v_add_f32_dpp v154, v154, v154 quad_perm:[1,0,3,2] row_mask:0xf bank_mask:0xf bound_ctrl:1
	v_pk_mul_f32 v[148:149], v[144:145], v[200:201]
	v_add_f32_e32 v163, v152, v153
	v_add_f32_dpp v154, v154, v154 quad_perm:[2,3,0,1] row_mask:0xf bank_mask:0xf bound_ctrl:1
	v_pk_fma_f32 v[146:147], v[240:241], v[196:197], v[146:147] op_sel:[0,0,0] op_sel_hi:[0,1,1]
	v_pk_fma_f32 v[148:149], v[240:241], v[204:205], v[148:149] op_sel:[0,0,0] op_sel_hi:[0,1,1]
	v_add_f32_dpp v154, v154, v154 row_half_mirror row_mask:0xf bank_mask:0xf bound_ctrl:1
	ds_read_b128 v[126:129], v182 offset:39936
	ds_read_b128 v[130:133], v182 offset:39952
	v_add_f32_dpp v154, v154, v154 row_mirror row_mask:0xf bank_mask:0xf bound_ctrl:1
	ds_read_b64 v[236:237], v182 offset:39968
	ds_read_b128 v[134:137], v183 offset:39936
	v_pk_fma_f32 v[146:147], v[154:155], v[194:195], v[146:147] op_sel_hi:[0,1,1]
	v_pk_fma_f32 v[148:149], v[154:155], v[202:203], v[148:149] op_sel_hi:[0,1,1]
	ds_read_b128 v[222:225], v183 offset:39952
	ds_read_b64 v[238:239], v183 offset:39968
	ds_read_b32 v242, v186 offset:1664
	s_waitcnt lgkmcnt(7)
	v_pk_mul_f32 v[150:151], v[146:147], v[206:207]
	v_pk_fma_f32 v[150:151], v[148:149], v[214:215], v[150:151]
	v_pk_mul_f32 v[152:153], v[146:147], v[228:229]
	v_add_f32_e32 v154, v150, v151
	v_pk_fma_f32 v[152:153], v[148:149], v[230:231], v[152:153]
	v_pk_mul_f32 v[142:143], v[146:147], v[208:209]
	v_add_f32_dpp v154, v154, v154 quad_perm:[1,0,3,2] row_mask:0xf bank_mask:0xf bound_ctrl:1
	v_pk_mul_f32 v[144:145], v[148:149], v[216:217]
	v_add_f32_e32 v164, v152, v153
	v_add_f32_dpp v154, v154, v154 quad_perm:[2,3,0,1] row_mask:0xf bank_mask:0xf bound_ctrl:1
	v_pk_fma_f32 v[142:143], v[240:241], v[212:213], v[142:143] op_sel:[1,0,0] op_sel_hi:[1,1,1]
	v_pk_fma_f32 v[144:145], v[240:241], v[220:221], v[144:145] op_sel:[1,0,0] op_sel_hi:[1,1,1]
	v_add_f32_dpp v154, v154, v154 row_half_mirror row_mask:0xf bank_mask:0xf bound_ctrl:1
	ds_read_b128 v[190:193], v182 offset:41472
	ds_read_b128 v[194:197], v182 offset:41488
	v_add_f32_dpp v154, v154, v154 row_mirror row_mask:0xf bank_mask:0xf bound_ctrl:1
	ds_read_b64 v[228:229], v182 offset:41504
	ds_read_b128 v[198:201], v183 offset:41472
	v_pk_fma_f32 v[142:143], v[154:155], v[210:211], v[142:143] op_sel_hi:[0,1,1]
	v_pk_fma_f32 v[144:145], v[154:155], v[218:219], v[144:145] op_sel_hi:[0,1,1]
	ds_read_b128 v[202:205], v183 offset:41488
	ds_read_b64 v[230:231], v183 offset:41504
	ds_read_b32 v240, v186 offset:1728
	s_waitcnt lgkmcnt(7)
	v_pk_mul_f32 v[150:151], v[142:143], v[126:127]
	v_pk_fma_f32 v[150:151], v[144:145], v[134:135], v[150:151]
	v_pk_mul_f32 v[152:153], v[142:143], v[232:233]
	v_add_f32_e32 v154, v150, v151
	v_pk_fma_f32 v[152:153], v[144:145], v[234:235], v[152:153]
	v_pk_mul_f32 v[146:147], v[142:143], v[128:129]
	v_add_f32_dpp v154, v154, v154 quad_perm:[1,0,3,2] row_mask:0xf bank_mask:0xf bound_ctrl:1
	v_pk_mul_f32 v[148:149], v[144:145], v[136:137]
	v_add_f32_e32 v165, v152, v153
	v_add_f32_dpp v154, v154, v154 quad_perm:[2,3,0,1] row_mask:0xf bank_mask:0xf bound_ctrl:1
	v_pk_fma_f32 v[146:147], v[242:243], v[132:133], v[146:147] op_sel:[0,0,0] op_sel_hi:[0,1,1]
	v_pk_fma_f32 v[148:149], v[242:243], v[224:225], v[148:149] op_sel:[0,0,0] op_sel_hi:[0,1,1]
	v_add_f32_dpp v154, v154, v154 row_half_mirror row_mask:0xf bank_mask:0xf bound_ctrl:1
	ds_read_b128 v[206:209], v182 offset:43008
	ds_read_b128 v[210:213], v182 offset:43024
	v_add_f32_dpp v154, v154, v154 row_mirror row_mask:0xf bank_mask:0xf bound_ctrl:1
	ds_read_b64 v[232:233], v182 offset:43040
	ds_read_b128 v[214:217], v183 offset:43008
	v_pk_fma_f32 v[146:147], v[154:155], v[130:131], v[146:147] op_sel_hi:[0,1,1]
	v_pk_fma_f32 v[148:149], v[154:155], v[222:223], v[148:149] op_sel_hi:[0,1,1]
	ds_read_b128 v[218:221], v183 offset:43024
	ds_read_b64 v[234:235], v183 offset:43040
	ds_read_b32 v241, v186 offset:1792
	s_waitcnt lgkmcnt(7)
	v_pk_mul_f32 v[150:151], v[146:147], v[190:191]
	v_pk_fma_f32 v[150:151], v[148:149], v[198:199], v[150:151]
	v_pk_mul_f32 v[152:153], v[146:147], v[236:237]
	v_add_f32_e32 v154, v150, v151
	v_pk_fma_f32 v[152:153], v[148:149], v[238:239], v[152:153]
	v_pk_mul_f32 v[142:143], v[146:147], v[192:193]
	v_add_f32_dpp v154, v154, v154 quad_perm:[1,0,3,2] row_mask:0xf bank_mask:0xf bound_ctrl:1
	v_pk_mul_f32 v[144:145], v[148:149], v[200:201]
	v_add_f32_e32 v166, v152, v153
	v_add_f32_dpp v154, v154, v154 quad_perm:[2,3,0,1] row_mask:0xf bank_mask:0xf bound_ctrl:1
	v_pk_fma_f32 v[142:143], v[240:241], v[196:197], v[142:143] op_sel:[0,0,0] op_sel_hi:[0,1,1]
	v_pk_fma_f32 v[144:145], v[240:241], v[204:205], v[144:145] op_sel:[0,0,0] op_sel_hi:[0,1,1]
	v_add_f32_dpp v154, v154, v154 row_half_mirror row_mask:0xf bank_mask:0xf bound_ctrl:1
	ds_read_b128 v[126:129], v182 offset:44544
	ds_read_b128 v[130:133], v182 offset:44560
	v_add_f32_dpp v154, v154, v154 row_mirror row_mask:0xf bank_mask:0xf bound_ctrl:1
	ds_read_b64 v[236:237], v182 offset:44576
	ds_read_b128 v[134:137], v183 offset:44544
	v_pk_fma_f32 v[142:143], v[154:155], v[194:195], v[142:143] op_sel_hi:[0,1,1]
	v_pk_fma_f32 v[144:145], v[154:155], v[202:203], v[144:145] op_sel_hi:[0,1,1]
	ds_read_b128 v[222:225], v183 offset:44560
	ds_read_b64 v[238:239], v183 offset:44576
	ds_read_b32 v242, v186 offset:1856
	s_waitcnt lgkmcnt(7)
; __device__ __forceinline__ void wkv_phase(const WkvT& W, unsigned char* lds) {
;     ...
;                 for (int t = 0; t < 32; ++t) {
;                     const f32x2 a2 = {nA[0], nA[1]}, w2 = {nA[2], nA[3]}, b2 = {nB[0], nB[1]}, k2 = {nB[2], nB[3]}, r2 = nr; const float v = nv;
;                     if (t + 1 < 32) { nA = *(const f32x4*)(pp + (t + 1) * 384); nB = *(const f32x4*)(pp + (t + 1) * 384 + 4); nr = *(const f32x2*)(pp + (t + 1) * 384 + 8); nv = pv[(t + 1) * 16]; }
;                     float S0 = S.x, S1 = S.y;
;                     float d = S0 * a2.x; d = __builtin_fmaf(S1, a2.y, d);
;                     float t0 = S0 * w2.x; t0 = __builtin_fmaf(v, k2.x, t0); asm volatile("" : "+v"(t0));
;                     float t1 = S1 * w2.y; t1 = __builtin_fmaf(v, k2.y, t1); asm volatile("" : "+v"(t1));
;                     float yprev; const float sa = wkv_reduce(d, ep, yprev);
;                     S0 = __builtin_fmaf(sa, b2.x, t0); asm volatile("" : "+v"(S0));
;                     S1 = __builtin_fmaf(sa, b2.y, t1); asm volatile("" : "+v"(S1));
;                     ep = S0 * r2.x; ep = __builtin_fmaf(S1, r2.y, ep);
;                     S.x = S0; S.y = S1;
;                     if (t >= 1) { const bool hit = oddrow && ((lane & 15) == ((t - 1) & 15)); if (t <= 16) yk0 = hit ? yprev : yk0; else yk1 = hit ? yprev : yk1; }
;                 }
	v_pk_mul_f32 v[150:151], v[142:143], v[206:207]
	v_pk_fma_f32 v[150:151], v[144:145], v[214:215], v[150:151]
	v_pk_mul_f32 v[152:153], v[142:143], v[228:229]
	v_add_f32_e32 v154, v150, v151
	v_pk_fma_f32 v[152:153], v[144:145], v[230:231], v[152:153]
	v_pk_mul_f32 v[146:147], v[142:143], v[208:209]
	v_add_f32_dpp v154, v154, v154 quad_perm:[1,0,3,2] row_mask:0xf bank_mask:0xf bound_ctrl:1
	v_pk_mul_f32 v[148:149], v[144:145], v[216:217]
	v_add_f32_e32 v167, v152, v153
	v_add_f32_dpp v154, v154, v154 quad_perm:[2,3,0,1] row_mask:0xf bank_mask:0xf bound_ctrl:1
	v_pk_fma_f32 v[146:147], v[240:241], v[212:213], v[146:147] op_sel:[1,0,0] op_sel_hi:[1,1,1]
	v_pk_fma_f32 v[148:149], v[240:241], v[220:221], v[148:149] op_sel:[1,0,0] op_sel_hi:[1,1,1]
	v_add_f32_dpp v154, v154, v154 row_half_mirror row_mask:0xf bank_mask:0xf bound_ctrl:1
	ds_read_b128 v[190:193], v182 offset:46080
	ds_read_b128 v[194:197], v182 offset:46096
	v_add_f32_dpp v154, v154, v154 row_mirror row_mask:0xf bank_mask:0xf bound_ctrl:1
	ds_read_b64 v[228:229], v182 offset:46112
	ds_read_b128 v[198:201], v183 offset:46080
	v_pk_fma_f32 v[146:147], v[154:155], v[210:211], v[146:147] op_sel_hi:[0,1,1]
	v_pk_fma_f32 v[148:149], v[154:155], v[218:219], v[148:149] op_sel_hi:[0,1,1]
	ds_read_b128 v[202:205], v183 offset:46096
	ds_read_b64 v[230:231], v183 offset:46112
	ds_read_b32 v240, v186 offset:1920
	s_waitcnt lgkmcnt(7)
	v_pk_mul_f32 v[150:151], v[146:147], v[126:127]
	v_pk_fma_f32 v[150:151], v[148:149], v[134:135], v[150:151]
	v_pk_mul_f32 v[152:153], v[146:147], v[232:233]
	v_add_f32_e32 v154, v150, v151
	v_pk_fma_f32 v[152:153], v[148:149], v[234:235], v[152:153]
	v_pk_mul_f32 v[142:143], v[146:147], v[128:129]
	v_add_f32_dpp v154, v154, v154 quad_perm:[1,0,3,2] row_mask:0xf bank_mask:0xf bound_ctrl:1
	v_pk_mul_f32 v[144:145], v[148:149], v[136:137]
	v_add_f32_e32 v168, v152, v153
	v_add_f32_dpp v154, v154, v154 quad_perm:[2,3,0,1] row_mask:0xf bank_mask:0xf bound_ctrl:1
	v_pk_fma_f32 v[142:143], v[242:243], v[132:133], v[142:143] op_sel:[0,0,0] op_sel_hi:[0,1,1]
	v_pk_fma_f32 v[144:145], v[242:243], v[224:225], v[144:145] op_sel:[0,0,0] op_sel_hi:[0,1,1]
	v_add_f32_dpp v154, v154, v154 row_half_mirror row_mask:0xf bank_mask:0xf bound_ctrl:1
	ds_read_b128 v[206:209], v182 offset:47616
	ds_read_b128 v[210:213], v182 offset:47632
	v_add_f32_dpp v154, v154, v154 row_mirror row_mask:0xf bank_mask:0xf bound_ctrl:1
	ds_read_b64 v[232:233], v182 offset:47648
	ds_read_b128 v[214:217], v183 offset:47616
	v_pk_fma_f32 v[142:143], v[154:155], v[130:131], v[142:143] op_sel_hi:[0,1,1]
	v_pk_fma_f32 v[144:145], v[154:155], v[222:223], v[144:145] op_sel_hi:[0,1,1]
	ds_read_b128 v[218:221], v183 offset:47632
	ds_read_b64 v[234:235], v183 offset:47648
	ds_read_b32 v241, v186 offset:1984
	s_waitcnt lgkmcnt(7)
	v_pk_mul_f32 v[150:151], v[142:143], v[190:191]
	v_pk_fma_f32 v[150:151], v[144:145], v[198:199], v[150:151]
	v_pk_mul_f32 v[152:153], v[142:143], v[236:237]
	v_add_f32_e32 v154, v150, v151
	v_pk_fma_f32 v[152:153], v[144:145], v[238:239], v[152:153]
	v_pk_mul_f32 v[146:147], v[142:143], v[192:193]
	v_add_f32_dpp v154, v154, v154 quad_perm:[1,0,3,2] row_mask:0xf bank_mask:0xf bound_ctrl:1
	v_pk_mul_f32 v[148:149], v[144:145], v[200:201]
	v_add_f32_e32 v169, v152, v153
	v_add_f32_dpp v154, v154, v154 quad_perm:[2,3,0,1] row_mask:0xf bank_mask:0xf bound_ctrl:1
	v_pk_fma_f32 v[146:147], v[240:241], v[196:197], v[146:147] op_sel:[0,0,0] op_sel_hi:[0,1,1]
	v_pk_fma_f32 v[148:149], v[240:241], v[204:205], v[148:149] op_sel:[0,0,0] op_sel_hi:[0,1,1]
	v_add_f32_dpp v154, v154, v154 row_half_mirror row_mask:0xf bank_mask:0xf bound_ctrl:1
	s_nop 1
	v_add_f32_dpp v154, v154, v154 row_mirror row_mask:0xf bank_mask:0xf bound_ctrl:1
	v_pk_fma_f32 v[146:147], v[154:155], v[194:195], v[146:147] op_sel_hi:[0,1,1]
	v_pk_fma_f32 v[148:149], v[154:155], v[202:203], v[148:149] op_sel_hi:[0,1,1]
	s_waitcnt lgkmcnt(0)
; __device__ __forceinline__ void wkv_phase(const WkvT& W, unsigned char* lds) {
;     ...
;                 for (int t = 0; t < 32; ++t) {
;                     const f32x2 a2 = {nA[0], nA[1]}, w2 = {nA[2], nA[3]}, b2 = {nB[0], nB[1]}, k2 = {nB[2], nB[3]}, r2 = nr; const float v = nv;
;                     if (t + 1 < 32) { nA = *(const f32x4*)(pp + (t + 1) * 384); nB = *(const f32x4*)(pp + (t + 1) * 384 + 4); nr = *(const f32x2*)(pp + (t + 1) * 384 + 8); nv = pv[(t + 1) * 16]; }
;                     float S0 = S.x, S1 = S.y;
;                     float d = S0 * a2.x; d = __builtin_fmaf(S1, a2.y, d);
;                     float t0 = S0 * w2.x; t0 = __builtin_fmaf(v, k2.x, t0); asm volatile("" : "+v"(t0));
;                     float t1 = S1 * w2.y; t1 = __builtin_fmaf(v, k2.y, t1); asm volatile("" : "+v"(t1));
;                     float yprev; const float sa = wkv_reduce(d, ep, yprev);
;                     S0 = __builtin_fmaf(sa, b2.x, t0); asm volatile("" : "+v"(S0));
;                     S1 = __builtin_fmaf(sa, b2.y, t1); asm volatile("" : "+v"(S1));
;                     ep = S0 * r2.x; ep = __builtin_fmaf(S1, r2.y, ep);
;                     S.x = S0; S.y = S1;
;                     if (t >= 1) { const bool hit = oddrow && ((lane & 15) == ((t - 1) & 15)); if (t <= 16) yk0 = hit ? yprev : yk0; else yk1 = hit ? yprev : yk1; }
;                 }
;                 { float ylast; (void)wkv_reduce(0.f, ep, ylast); yk1 = (oddrow && (lane & 15) == 15) ? ylast : yk1; }
;                 if (oddrow) { sY[bi * 512 + (lane & 15) * 16 + il] = yk0; sY[bi * 512 + (16 + (lane & 15)) * 16 + il] = yk1; }
	v_pk_mul_f32 v[150:151], v[146:147], v[206:207]
	v_pk_fma_f32 v[150:151], v[148:149], v[214:215], v[150:151]
	v_pk_mul_f32 v[152:153], v[146:147], v[228:229]
	v_add_f32_e32 v154, v150, v151
	v_pk_fma_f32 v[152:153], v[148:149], v[230:231], v[152:153]
	v_pk_mul_f32 v[142:143], v[146:147], v[208:209]
	v_add_f32_dpp v154, v154, v154 quad_perm:[1,0,3,2] row_mask:0xf bank_mask:0xf bound_ctrl:1
	v_pk_mul_f32 v[144:145], v[148:149], v[216:217]
	v_add_f32_e32 v170, v152, v153
	v_add_f32_dpp v154, v154, v154 quad_perm:[2,3,0,1] row_mask:0xf bank_mask:0xf bound_ctrl:1
	v_pk_fma_f32 v[142:143], v[240:241], v[212:213], v[142:143] op_sel:[1,0,0] op_sel_hi:[1,1,1]
	v_pk_fma_f32 v[144:145], v[240:241], v[220:221], v[144:145] op_sel:[1,0,0] op_sel_hi:[1,1,1]
	v_add_f32_dpp v154, v154, v154 row_half_mirror row_mask:0xf bank_mask:0xf bound_ctrl:1
	s_nop 1
	v_add_f32_dpp v154, v154, v154 row_mirror row_mask:0xf bank_mask:0xf bound_ctrl:1
	v_pk_fma_f32 v[142:143], v[154:155], v[210:211], v[142:143] op_sel_hi:[0,1,1]
	v_pk_fma_f32 v[144:145], v[154:155], v[218:219], v[144:145] op_sel_hi:[0,1,1]
	v_pk_mul_f32 v[152:153], v[142:143], v[232:233]
	v_pk_fma_f32 v[152:153], v[144:145], v[234:235], v[152:153]
	s_nop 0
	v_add_f32_e32 v171, v152, v153
	v_cndmask_b32_e64 v172, v164, v156, s[10:11]
	v_cndmask_b32_e64 v174, v165, v157, s[10:11]
	v_cndmask_b32_e64 v176, v166, v158, s[10:11]
	v_cndmask_b32_e64 v178, v167, v159, s[10:11]
	v_cndmask_b32_e64 v173, v156, v164, s[10:11]
	v_cndmask_b32_e64 v175, v157, v165, s[10:11]
	v_cndmask_b32_e64 v177, v158, v166, s[10:11]
	v_cndmask_b32_e64 v179, v159, v167, s[10:11]
	v_add_f32_dpp v156, v172, v173 row_ror:8 row_mask:0xf bank_mask:0xf
	v_add_f32_dpp v157, v174, v175 row_ror:8 row_mask:0xf bank_mask:0xf
	v_add_f32_dpp v158, v176, v177 row_ror:8 row_mask:0xf bank_mask:0xf
	v_add_f32_dpp v159, v178, v179 row_ror:8 row_mask:0xf bank_mask:0xf
	v_cndmask_b32_e64 v172, v168, v160, s[10:11]
	v_cndmask_b32_e64 v174, v169, v161, s[10:11]
	v_cndmask_b32_e64 v176, v170, v162, s[10:11]
	v_cndmask_b32_e64 v178, v171, v163, s[10:11]
	v_cndmask_b32_e64 v173, v160, v168, s[10:11]
	v_cndmask_b32_e64 v175, v161, v169, s[10:11]
	v_cndmask_b32_e64 v177, v162, v170, s[10:11]
	v_cndmask_b32_e64 v179, v163, v171, s[10:11]
	v_add_f32_dpp v160, v172, v173 row_ror:8 row_mask:0xf bank_mask:0xf
	v_add_f32_dpp v161, v174, v175 row_ror:8 row_mask:0xf bank_mask:0xf
	v_add_f32_dpp v162, v176, v177 row_ror:8 row_mask:0xf bank_mask:0xf
	v_add_f32_dpp v163, v178, v179 row_ror:8 row_mask:0xf bank_mask:0xf
	v_cndmask_b32_e64 v172, v160, v156, s[12:13]
	v_cndmask_b32_e64 v174, v161, v157, s[12:13]
	v_cndmask_b32_e64 v176, v162, v158, s[12:13]
	v_cndmask_b32_e64 v178, v163, v159, s[12:13]
	v_cndmask_b32_e64 v173, v156, v160, s[12:13]
	v_cndmask_b32_e64 v175, v157, v161, s[12:13]
	v_cndmask_b32_e64 v177, v158, v162, s[12:13]
	v_cndmask_b32_e64 v179, v159, v163, s[12:13]
	v_add_f32_dpp v156, v172, v173 row_half_mirror row_mask:0xf bank_mask:0xf
	v_add_f32_dpp v157, v174, v175 row_half_mirror row_mask:0xf bank_mask:0xf
	v_add_f32_dpp v158, v176, v177 row_half_mirror row_mask:0xf bank_mask:0xf
	v_add_f32_dpp v159, v178, v179 row_half_mirror row_mask:0xf bank_mask:0xf
	v_cndmask_b32_e64 v172, v158, v156, s[14:15]
	v_cndmask_b32_e64 v174, v159, v157, s[14:15]
	v_cndmask_b32_e64 v173, v156, v158, s[14:15]
	v_cndmask_b32_e64 v175, v157, v159, s[14:15]
	v_add_f32_dpp v156, v172, v173 quad_perm:[2,3,0,1] row_mask:0xf bank_mask:0xf
	v_add_f32_dpp v157, v174, v175 quad_perm:[2,3,0,1] row_mask:0xf bank_mask:0xf
	v_cndmask_b32_e64 v172, v157, v156, s[16:17]
	v_cndmask_b32_e64 v173, v156, v157, s[16:17]
	s_nop 0
	v_add_f32_dpp v156, v172, v173 quad_perm:[1,0,3,2] row_mask:0xf bank_mask:0xf
	v_mov_b32_e32 v181, v156
	ds_write2st64_b32 v187, v180, v181 offset0:0 offset1:4
.Lwkv4_b1_skip:
	s_mov_b64 s[46:47], exec
	s_bitcmp0_b32 s99, 8
	s_cbranch_scc1 .Lwkv4_join1

; __device__ __forceinline__ float bflo(unsigned w) { return __uint_as_float(w << 16); }
; __device__ __forceinline__ float bfhi(unsigned w) { return __uint_as_float(w & 0xffff0000u); }
; __device__ __forceinline__ float row16_sum(float x) { x += dpp_f(x, 0); x += dpp_f(x, 1); x += dpp_f(x, 2); x += dpp_f(x, 3); return x; }
; __device__ __forceinline__ void wkv_stage(const WkvT& W, const WkvRaw& raw, size_t rowbase, int h, int q, int c, int tid, const float (&kkc)[4], const float (&kac)[4], const float (&rkc)[4],
;                                           float* sP, float* sV) {
;     const float r[4] = {bflo(raw.r[0]), bfhi(raw.r[0]), bflo(raw.r[1]), bfhi(raw.r[1])}, k[4] = {bflo(raw.k[0]), bfhi(raw.k[0]), bflo(raw.k[1]), bfhi(raw.k[1])};
;     const float a[4] = {bflo(raw.a[0]), bfhi(raw.a[0]), bflo(raw.a[1]), bfhi(raw.a[1])}, l[4] = {bflo(raw.l[0]), bfhi(raw.l[0]), bflo(raw.l[1]), bfhi(raw.l[1])};
;     float kkr[4], km[4], n2 = 0.f, bs = 0.f;
; #pragma unroll
;     for (int e = 0; e < 4; ++e) { kkr[e] = k[e] * kkc[e]; n2 += kkr[e] * kkr[e]; km[e] = k[e] * (1.f + (a[e] - 1.f) * kac[e]); bs += r[e] * km[e] * rkc[e]; }
;     n2 = row16_sum(n2); bs = row16_sum(bs);
;     const float inv = __builtin_amdgcn_rcpf(fmaxf(sqrtf(n2), 1e-12f));
;     const int t = tid >> 4;
;     float* rec = sP + (t * 32 + 2 * (tid & 15)) * 12;
; #pragma unroll
;     for (int hlf = 0; hlf < 2; ++hlf) { const int e = 2 * hlf; float* rp = rec + hlf * 12;
;         *(f32x4*)(rp) = (f32x4){-kkr[e] * inv, -kkr[e + 1] * inv, __builtin_amdgcn_exp2f(LOG2E_ * l[e]), __builtin_amdgcn_exp2f(LOG2E_ * l[e + 1])};
;         *(f32x4*)(rp + 4) = (f32x4){kkr[e] * inv * a[e], kkr[e + 1] * inv * a[e + 1], km[e], km[e + 1]};
;         *(f32x2*)(rp + 8) = (f32x2){r[e], r[e + 1]}; }
;     if ((tid & 15) < 4) *(f32x4*)(sV + t * 16 + 4 * (tid & 15)) = (f32x4){bflo(raw.v[0]), bfhi(raw.v[0]), bflo(raw.v[1]), bfhi(raw.v[1])};
;     if (q == 0 && (tid & 15) == 0) W.bonus[(rowbase + (size_t)c * 32 + t) * 32 + h] = bs;
; }
.LBB0_1630:
	s_or_b64 exec, exec, s[46:47]
	v_add_u32_e32 v208, 0xffffa000, v125
	v_add_u32_e32 v209, 0xfffffc00, v15
	v_subrev_co_u32_e32 v210, vcc, 0x800, v38
	s_nop 1
	v_subbrev_co_u32_e32 v211, vcc, 0, v39, vcc
	s_waitcnt vmcnt(2)
	v_lshlrev_b32_e32 v126, 16, v200
	v_and_b32_e32 v127, 0xffff0000, v200
	v_and_b32_e32 v135, 0xffff0000, v201
	v_lshlrev_b32_e32 v134, 16, v201
	v_pk_mul_f32 v[128:129], v[6:7], v[126:127]
	v_pk_mul_f32 v[136:137], v[8:9], v[134:135]
	v_pk_mul_f32 v[206:207], v[128:129], v[128:129]
	v_pk_mul_f32 v[204:205], v[136:137], v[136:137]
	v_add_f32_e32 v16, v206, v207
	v_add_f32_e32 v16, v204, v16
	v_add_f32_e32 v16, v205, v16
	s_waitcnt vmcnt(0)
	v_lshlrev_b32_e32 v205, 16, v196
	v_and_b32_e32 v207, 0xffff0000, v196
	v_add_f32_dpp v16, v16, v16 quad_perm:[1,0,3,2] row_mask:0xf bank_mask:0xf bound_ctrl:1
	v_and_b32_e32 v139, 0xffff0000, v197
	v_lshlrev_b32_e32 v130, 16, v198
	v_add_f32_dpp v16, v16, v16 quad_perm:[2,3,0,1] row_mask:0xf bank_mask:0xf bound_ctrl:1
	v_and_b32_e32 v131, 0xffff0000, v198
	v_lshlrev_b32_e32 v132, 16, v199
	v_add_f32_dpp v16, v16, v16 row_half_mirror row_mask:0xf bank_mask:0xf bound_ctrl:1
	v_and_b32_e32 v133, 0xffff0000, v199
	s_nop 0
	v_add_f32_dpp v16, v16, v16 row_mirror row_mask:0xf bank_mask:0xf bound_ctrl:1
	v_mul_f32_e32 v204, 0x4f800000, v16
	v_cmp_gt_f32_e32 vcc, s3, v16
	s_nop 1
	v_cndmask_b32_e32 v16, v16, v204, vcc
	v_sqrt_f32_e32 v204, v16
	s_nop 0
	v_add_u32_e32 v206, -1, v204
	v_fma_f32 v138, -v206, v204, v16
	v_cmp_ge_f32_e64 s[46:47], 0, v138
	v_add_u32_e32 v138, 1, v204
	s_nop 0
	v_cndmask_b32_e64 v206, v204, v206, s[46:47]
	v_fma_f32 v204, -v138, v204, v16
	v_cmp_lt_f32_e64 s[46:47], 0, v204
	s_nop 1
	v_cndmask_b32_e64 v204, v206, v138, s[46:47]
	v_mul_f32_e32 v206, 0x37800000, v204
	v_cndmask_b32_e32 v204, v204, v206, vcc
	v_cmp_class_f32_e32 vcc, v16, v124
	s_nop 1
	v_cndmask_b32_e32 v16, v204, v16, vcc
	v_max_f32_e32 v16, 0x2b8cbccc, v16
	v_rcp_f32_e32 v138, v16
	v_mul_f32_e32 v16, 0x3fb8aa3b, v205
	v_exp_f32_e32 v206, v16
	v_mul_f32_e32 v16, 0x3fb8aa3b, v207
	v_exp_f32_e32 v207, v16
	v_pk_mul_f32 v[204:205], v[138:139], v[128:129] op_sel_hi:[0,1] neg_lo:[0,1] neg_hi:[0,1]
	v_lshlrev_b32_e32 v16, 16, v197
	v_mul_f32_e32 v16, 0x3fb8aa3b, v16
	ds_write_b128 v208, v[204:207] offset:49152
	v_lshlrev_b32_e32 v204, 16, v194
	v_and_b32_e32 v205, 0xffff0000, v194
	v_pk_add_f32 v[206:207], v[204:205], -1.0 op_sel_hi:[1,0]
	s_nop 0
	v_pk_fma_f32 v[206:207], v[10:11], v[206:207], 1.0 op_sel_hi:[1,1,0]
	s_nop 0
	v_pk_mul_f32 v[206:207], v[206:207], v[126:127]
	s_nop 0
	v_mul_f32_e32 v126, v206, v130
	v_fma_f32 v140, v2, v126, 0
	v_mul_f32_e32 v126, v207, v131
	v_fmac_f32_e32 v140, v3, v126
	v_pk_mul_f32 v[126:127], v[128:129], v[138:139] op_sel_hi:[1,0]
	v_exp_f32_e32 v128, v16
	v_mul_f32_e32 v16, 0x3fb8aa3b, v139
	v_exp_f32_e32 v129, v16
	v_pk_mul_f32 v[204:205], v[126:127], v[204:205]
	ds_write_b128 v208, v[204:207] offset:49168
	v_lshlrev_b32_e32 v206, 16, v195
	v_and_b32_e32 v207, 0xffff0000, v195
	v_pk_add_f32 v[204:205], v[206:207], -1.0 op_sel_hi:[1,0]
	v_pk_mul_f32 v[126:127], v[138:139], v[136:137] op_sel_hi:[0,1] neg_lo:[0,1] neg_hi:[0,1]
	v_pk_fma_f32 v[204:205], v[12:13], v[204:205], 1.0 op_sel_hi:[1,1,0]
	ds_write_b128 v208, v[126:129] offset:49200
	v_pk_mul_f32 v[128:129], v[204:205], v[134:135]
	v_pk_mul_f32 v[126:127], v[136:137], v[138:139] op_sel_hi:[1,0]
	v_mul_f32_e32 v16, v128, v132
	v_mul_f32_e32 v204, v129, v133
	v_fmac_f32_e32 v140, v4, v16
	v_fmac_f32_e32 v140, v5, v204
	v_pk_mul_f32 v[126:127], v[126:127], v[206:207]
	v_add_u32_e32 v205, 0xc000, v208
	v_add_f32_dpp v16, v140, v140 quad_perm:[1,0,3,2] row_mask:0xf bank_mask:0xf bound_ctrl:1
	ds_write_b128 v208, v[126:129] offset:49216
	ds_write2_b64 v205, v[130:131], v[132:133] offset0:4 offset1:10
	v_add_f32_dpp v16, v16, v16 quad_perm:[2,3,0,1] row_mask:0xf bank_mask:0xf bound_ctrl:1
	s_nop 1
	v_add_f32_dpp v16, v16, v16 row_half_mirror row_mask:0xf bank_mask:0xf bound_ctrl:1
	s_nop 1
	v_mov_b32_dpp v204, v16 row_mirror row_mask:0xf bank_mask:0xf bound_ctrl:1
	s_and_saveexec_b64 s[46:47], s[0:1]
	v_lshlrev_b32_e32 v126, 16, v212
	v_and_b32_e32 v127, 0xffff0000, v212
	v_lshlrev_b32_e32 v128, 16, v213
	v_and_b32_e32 v129, 0xffff0000, v213
	ds_write_b128 v209, v[126:129] offset:2048
	s_or_b64 exec, exec, s[46:47]
	s_and_saveexec_b64 s[46:47], s[42:43]
	s_cbranch_execz .Lst1b_1630
	v_add_f32_e32 v16, v16, v204
	v_lshl_add_u64 v[204:205], s[52:53], 0, v[210:211]
	v_add_co_u32_e32 v204, vcc, 0x1e501000, v204
	s_nop 1
	v_addc_co_u32_e32 v205, vcc, 0, v205, vcc
	global_store_dword v[204:205], v16, off

; __device__ __forceinline__ bf16_t f2bf(float f) { return (bf16_t)(pk2(f, 0.f) & 0xffffu); }
; __device__ __forceinline__ float row16_sum(float x) { x += dpp_f(x, 0); x += dpp_f(x, 1); x += dpp_f(x, 2); x += dpp_f(x, 3); return x; }
; __device__ __forceinline__ void wkv_phase(const WkvT& W, unsigned char* lds) {
;     ...
;             {
;                 const int t = tid >> 4, i = tid & 15; const float yv = sY[bi * 512 + t * 16 + i];
;                 const size_t row = rowbase + (size_t)c * 32 + t;
;                 W.Y[row * DM + cbase + q * 16 + i] = f2bf(yv);
;                 const float s1 = row16_sum(yv), s2 = row16_sum(yv * yv);
;                 if (i == 0) *(f32x2*)(W.stats + ((row * 32 + h) * 4 + q) * 2) = (f32x2){s1, s2};
;             }
.Lwkv4_join1:
	s_waitcnt lgkmcnt(0)
	s_barrier
	s_bitcmp0_b32 s99, 8
	s_cbranch_scc1 .Lwkv4_fl1_done
	ds_read_b32 v56, v60
	v_lshl_add_u64 v[58:59], s[52:53], 0, v[44:45]
	s_waitcnt lgkmcnt(0)
	v_mul_f32_e32 v57, v56, v56
	v_mov_b32_dpp v126, v56 quad_perm:[1,0,3,2] row_mask:0xf bank_mask:0xf bound_ctrl:1
	s_nop 0
	v_mov_b32_dpp v127, v57 quad_perm:[1,0,3,2] row_mask:0xf bank_mask:0xf bound_ctrl:1
	v_cvt_pk_bf16_f32 v16, v56, s0
	v_pk_add_f32 v[56:57], v[56:57], v[126:127]
	global_store_short v[58:59], v16, off
	s_nop 0
	v_mov_b32_dpp v58, v56 quad_perm:[2,3,0,1] row_mask:0xf bank_mask:0xf bound_ctrl:1
	v_mov_b32_dpp v59, v57 quad_perm:[2,3,0,1] row_mask:0xf bank_mask:0xf bound_ctrl:1
	v_pk_add_f32 v[56:57], v[56:57], v[58:59]
	s_nop 1
	v_mov_b32_dpp v58, v56 row_half_mirror row_mask:0xf bank_mask:0xf bound_ctrl:1
	v_mov_b32_dpp v59, v57 row_half_mirror row_mask:0xf bank_mask:0xf bound_ctrl:1
	v_pk_add_f32 v[56:57], v[56:57], v[58:59]
	s_nop 1
	v_mov_b32_dpp v58, v56 row_mirror row_mask:0xf bank_mask:0xf bound_ctrl:1
	v_mov_b32_dpp v59, v57 row_mirror row_mask:0xf bank_mask:0xf bound_ctrl:1
	s_and_saveexec_b64 s[46:47], s[8:9]
	s_cbranch_execz .LBB0_1632
	v_pk_add_f32 v[56:57], v[56:57], v[58:59]
	v_lshl_add_u64 v[58:59], s[52:53], 0, v[34:35]
	v_add_co_u32_e32 v58, vcc, 0x1d500000, v58
	s_nop 1
	v_addc_co_u32_e32 v59, vcc, 0, v59, vcc
	global_store_dwordx2 v[58:59], v[56:57], off
.LBB0_1632:
	s_or_b64 exec, exec, s[46:47]
	v_add_u32_e32 v220, 0xfffffc00, v60
	v_subrev_co_u32_e32 v222, vcc, 0x10000, v44
	s_nop 1
	v_subbrev_co_u32_e32 v223, vcc, 0, v45, vcc
	v_subrev_co_u32_e32 v224, vcc, 0x4000, v34
	s_nop 1
	v_subbrev_co_u32_e32 v225, vcc, 0, v35, vcc
	ds_read_b32 v56, v220
	v_lshl_add_u64 v[58:59], s[52:53], 0, v[222:223]
	s_waitcnt lgkmcnt(0)
	v_mul_f32_e32 v57, v56, v56
	v_mov_b32_dpp v126, v56 quad_perm:[1,0,3,2] row_mask:0xf bank_mask:0xf bound_ctrl:1
	s_nop 0
	v_mov_b32_dpp v127, v57 quad_perm:[1,0,3,2] row_mask:0xf bank_mask:0xf bound_ctrl:1
	v_cvt_pk_bf16_f32 v16, v56, s0
	v_pk_add_f32 v[56:57], v[56:57], v[126:127]
	global_store_short v[58:59], v16, off
	s_nop 0
	v_mov_b32_dpp v58, v56 quad_perm:[2,3,0,1] row_mask:0xf bank_mask:0xf bound_ctrl:1
	v_mov_b32_dpp v59, v57 quad_perm:[2,3,0,1] row_mask:0xf bank_mask:0xf bound_ctrl:1
	v_pk_add_f32 v[56:57], v[56:57], v[58:59]
	s_nop 1
	v_mov_b32_dpp v58, v56 row_half_mirror row_mask:0xf bank_mask:0xf bound_ctrl:1
	v_mov_b32_dpp v59, v57 row_half_mirror row_mask:0xf bank_mask:0xf bound_ctrl:1
	v_pk_add_f32 v[56:57], v[56:57], v[58:59]
	s_nop 1
	v_mov_b32_dpp v58, v56 row_mirror row_mask:0xf bank_mask:0xf bound_ctrl:1
	v_mov_b32_dpp v59, v57 row_mirror row_mask:0xf bank_mask:0xf bound_ctrl:1
	s_and_saveexec_b64 s[46:47], s[8:9]
	s_cbranch_execz .Lfl1b_1632
	v_pk_add_f32 v[56:57], v[56:57], v[58:59]
	v_lshl_add_u64 v[58:59], s[52:53], 0, v[224:225]
	v_add_co_u32_e32 v58, vcc, 0x1d500000, v58
	s_nop 1
	v_addc_co_u32_e32 v59, vcc, 0, v59, vcc
	global_store_dwordx2 v[58:59], v[56:57], off

; __device__ __forceinline__ void wkv_issue(const WkvT& W, WkvRaw& raw, size_t rowbase, int cbase, int q, int c, int tid) {
;     const size_t row = rowbase + (size_t)c * 32 + (tid >> 4), idx = row * DM + cbase + 4 * (tid & 15);
;     raw.r = *(const u32x2*)(W.R + idx); raw.k = *(const u32x2*)(W.K + idx); raw.a = *(const u32x2*)(W.AS + idx); raw.l = *(const u32x2*)(W.LW + idx);
;     if ((tid & 15) < 4) raw.v = *(const u32x2*)(W.V + row * DM + cbase + q * 16 + 4 * (tid & 15));
; }
; __device__ __forceinline__ void wkv_phase(const WkvT& W, unsigned char* lds) {
;     ...
;                 const float* pp = sP + bo + jj * 12;
;                 const float* pv = sV + bi * 512 + il;
;                 f32x4 nA = *(const f32x4*)pp, nB = *(const f32x4*)(pp + 4); f32x2 nr = *(const f32x2*)(pp + 8); float nv = pv[0];
;                 float yk0 = 0.f, yk1 = 0.f, ep = 0.f;
;                 const bool oddrow = (lane & 16) != 0;
; #pragma unroll
;                 for (int t = 0; t < 32; ++t) {
;                     const f32x2 a2 = {nA[0], nA[1]}, w2 = {nA[2], nA[3]}, b2 = {nB[0], nB[1]}, k2 = {nB[2], nB[3]}, r2 = nr; const float v = nv;
;                     if (t + 1 < 32) { nA = *(const f32x4*)(pp + (t + 1) * 384); nB = *(const f32x4*)(pp + (t + 1) * 384 + 4); nr = *(const f32x2*)(pp + (t + 1) * 384 + 8); nv = pv[(t + 1) * 16]; }
;                     float S0 = S.x, S1 = S.y;
;                     float d = S0 * a2.x; d = __builtin_fmaf(S1, a2.y, d);
;                     float t0 = S0 * w2.x; t0 = __builtin_fmaf(v, k2.x, t0); asm volatile("" : "+v"(t0));
;                     float t1 = S1 * w2.y; t1 = __builtin_fmaf(v, k2.y, t1); asm volatile("" : "+v"(t1));
;                     float yprev; const float sa = wkv_reduce(d, ep, yprev);
;                     S0 = __builtin_fmaf(sa, b2.x, t0); asm volatile("" : "+v"(S0));
;                     S1 = __builtin_fmaf(sa, b2.y, t1); asm volatile("" : "+v"(S1));
.Lwkv4_fl1_done:
	s_cmp_lg_u32 s80, 0
	s_cselect_b64 s[46:47], -1, 0
	s_cmp_eq_u32 s80, 0
	s_cbranch_scc1 .LBB0_1636
	s_bitcmp0_b32 s99, 8
	s_cbranch_scc1 .LBB0_1636
	v_mov_b32_e32 v218, v54
	v_mov_b32_e32 v219, v55
	v_add_co_u32_e32 v46, vcc, 0x3540000, v54
	s_nop 1
	v_addc_co_u32_e32 v47, vcc, 0, v55, vcc
	v_add_co_u32_e32 v48, vcc, 0x7540000, v54
	s_nop 1
	v_addc_co_u32_e32 v49, vcc, 0, v55, vcc
	v_add_co_u32_e32 v56, vcc, 0xf540000, v54
	s_nop 1
	v_addc_co_u32_e32 v57, vcc, 0, v55, vcc
	v_add_co_u32_e32 v54, vcc, 0xb540000, v54
	s_nop 1
	v_addc_co_u32_e32 v55, vcc, 0, v55, vcc
	global_load_dwordx2 v[50:51], v[46:47], off
	global_load_dwordx2 v[52:53], v[48:49], off
	s_nop 0
	global_load_dwordx2 v[46:47], v[56:57], off
	global_load_dwordx2 v[48:49], v[54:55], off
	s_and_saveexec_b64 s[96:97], s[0:1]
	s_cbranch_execz .LBB0_1635
	v_lshl_add_u64 v[32:33], s[52:53], 0, v[42:43]
	v_add_co_u32_e32 v32, vcc, 0x19540000, v32
	s_nop 1
	v_addc_co_u32_e32 v33, vcc, 0, v33, vcc
	global_load_dwordx2 v[32:33], v[32:33], off
.LBB0_1635:
	s_or_b64 exec, exec, s[96:97]
	v_add_co_u32_e32 v204, vcc, 0x3530000, v218
	s_nop 1
	v_addc_co_u32_e32 v205, vcc, 0, v219, vcc
	global_load_dwordx2 v[198:199], v[204:205], off
	v_add_co_u32_e32 v206, vcc, 0x7530000, v218
	s_nop 1
	v_addc_co_u32_e32 v207, vcc, 0, v219, vcc
	global_load_dwordx2 v[200:201], v[206:207], off
	v_add_co_u32_e32 v204, vcc, 0xf530000, v218
	s_nop 1
	v_addc_co_u32_e32 v205, vcc, 0, v219, vcc
	global_load_dwordx2 v[194:195], v[204:205], off
	v_add_co_u32_e32 v206, vcc, 0xb530000, v218
	s_nop 1
	v_addc_co_u32_e32 v207, vcc, 0, v219, vcc
	global_load_dwordx2 v[196:197], v[206:207], off
	s_and_saveexec_b64 s[100:101], s[0:1]
	v_lshl_add_u64 v[212:213], s[52:53], 0, v[42:43]
	v_add_co_u32_e32 v212, vcc, 0x19530000, v212
	s_nop 1
	v_addc_co_u32_e32 v213, vcc, 0, v213, vcc
	global_load_dwordx2 v[212:213], v[212:213], off
	s_or_b64 exec, exec, s[100:101]
.LBB0_1636:
	s_bitcmp1_b32 s99, 8
	s_cbranch_scc1 .Lwkv4_b2_skip
	ds_read_b128 v[190:193], v182 offset:49152
	ds_read_b128 v[194:197], v182 offset:49168
	ds_read_b64 v[228:229], v182 offset:49184
	ds_read_b128 v[198:201], v183 offset:49152
	ds_read_b128 v[202:205], v183 offset:49168
	ds_read_b64 v[230:231], v183 offset:49184
	ds_read_b32 v240, v186 offset:2048
	ds_read_b128 v[206:209], v182 offset:50688
	ds_read_b128 v[210:213], v182 offset:50704
	ds_read_b64 v[232:233], v182 offset:50720
	ds_read_b128 v[214:217], v183 offset:50688
	ds_read_b128 v[218:221], v183 offset:50704
	ds_read_b64 v[234:235], v183 offset:50720
	ds_read_b32 v241, v186 offset:2112
	s_waitcnt lgkmcnt(7)
	v_pk_mul_f32 v[150:151], v[142:143], v[190:191]
	v_pk_fma_f32 v[150:151], v[144:145], v[198:199], v[150:151]
	v_pk_mul_f32 v[146:147], v[142:143], v[192:193]
	v_add_f32_e32 v154, v150, v151
	v_pk_mul_f32 v[148:149], v[144:145], v[200:201]
	v_pk_fma_f32 v[146:147], v[240:241], v[196:197], v[146:147] op_sel:[0,0,0] op_sel_hi:[0,1,1]
	v_add_f32_dpp v154, v154, v154 quad_perm:[1,0,3,2] row_mask:0xf bank_mask:0xf bound_ctrl:1
	v_pk_fma_f32 v[148:149], v[240:241], v[204:205], v[148:149] op_sel:[0,0,0] op_sel_hi:[0,1,1]
	s_nop 0
	v_add_f32_dpp v154, v154, v154 quad_perm:[2,3,0,1] row_mask:0xf bank_mask:0xf bound_ctrl:1
	ds_read_b128 v[126:129], v182 offset:52224
	ds_read_b128 v[130:133], v182 offset:52240
	v_add_f32_dpp v154, v154, v154 row_half_mirror row_mask:0xf bank_mask:0xf bound_ctrl:1
	ds_read_b64 v[236:237], v182 offset:52256
	ds_read_b128 v[134:137], v183 offset:52224
	v_add_f32_dpp v154, v154, v154 row_mirror row_mask:0xf bank_mask:0xf bound_ctrl:1
	v_pk_fma_f32 v[146:147], v[154:155], v[194:195], v[146:147] op_sel_hi:[0,1,1]
	v_pk_fma_f32 v[148:149], v[154:155], v[202:203], v[148:149] op_sel_hi:[0,1,1]
	ds_read_b128 v[222:225], v183 offset:52240
	ds_read_b64 v[238:239], v183 offset:52256
	ds_read_b32 v242, v186 offset:2176
	s_waitcnt lgkmcnt(7)
	v_pk_mul_f32 v[150:151], v[146:147], v[206:207]
	v_pk_fma_f32 v[150:151], v[148:149], v[214:215], v[150:151]
	v_pk_mul_f32 v[152:153], v[146:147], v[228:229]
	v_add_f32_e32 v154, v150, v151
	v_pk_fma_f32 v[152:153], v[148:149], v[230:231], v[152:153]
	v_pk_mul_f32 v[142:143], v[146:147], v[208:209]
	v_add_f32_dpp v154, v154, v154 quad_perm:[1,0,3,2] row_mask:0xf bank_mask:0xf bound_ctrl:1
	v_pk_mul_f32 v[144:145], v[148:149], v[216:217]
	v_add_f32_e32 v156, v152, v153
	v_add_f32_dpp v154, v154, v154 quad_perm:[2,3,0,1] row_mask:0xf bank_mask:0xf bound_ctrl:1
	v_pk_fma_f32 v[142:143], v[240:241], v[212:213], v[142:143] op_sel:[1,0,0] op_sel_hi:[1,1,1]
	v_pk_fma_f32 v[144:145], v[240:241], v[220:221], v[144:145] op_sel:[1,0,0] op_sel_hi:[1,1,1]
	v_add_f32_dpp v154, v154, v154 row_half_mirror row_mask:0xf bank_mask:0xf bound_ctrl:1
	ds_read_b128 v[190:193], v182 offset:53760
	ds_read_b128 v[194:197], v182 offset:53776
	v_add_f32_dpp v154, v154, v154 row_mirror row_mask:0xf bank_mask:0xf bound_ctrl:1
	ds_read_b64 v[228:229], v182 offset:53792
	ds_read_b128 v[198:201], v183 offset:53760
	v_pk_fma_f32 v[142:143], v[154:155], v[210:211], v[142:143] op_sel_hi:[0,1,1]
	v_pk_fma_f32 v[144:145], v[154:155], v[218:219], v[144:145] op_sel_hi:[0,1,1]
	ds_read_b128 v[202:205], v183 offset:53776
	ds_read_b64 v[230:231], v183 offset:53792
	ds_read_b32 v240, v186 offset:2240
	s_waitcnt lgkmcnt(7)
; __device__ __forceinline__ void wkv_phase(const WkvT& W, unsigned char* lds) {
;     ...
;                 for (int t = 0; t < 32; ++t) {
;                     const f32x2 a2 = {nA[0], nA[1]}, w2 = {nA[2], nA[3]}, b2 = {nB[0], nB[1]}, k2 = {nB[2], nB[3]}, r2 = nr; const float v = nv;
;                     if (t + 1 < 32) { nA = *(const f32x4*)(pp + (t + 1) * 384); nB = *(const f32x4*)(pp + (t + 1) * 384 + 4); nr = *(const f32x2*)(pp + (t + 1) * 384 + 8); nv = pv[(t + 1) * 16]; }
;                     float S0 = S.x, S1 = S.y;
;                     float d = S0 * a2.x; d = __builtin_fmaf(S1, a2.y, d);
;                     float t0 = S0 * w2.x; t0 = __builtin_fmaf(v, k2.x, t0); asm volatile("" : "+v"(t0));
;                     float t1 = S1 * w2.y; t1 = __builtin_fmaf(v, k2.y, t1); asm volatile("" : "+v"(t1));
;                     float yprev; const float sa = wkv_reduce(d, ep, yprev);
;                     S0 = __builtin_fmaf(sa, b2.x, t0); asm volatile("" : "+v"(S0));
;                     S1 = __builtin_fmaf(sa, b2.y, t1); asm volatile("" : "+v"(S1));
;                     ep = S0 * r2.x; ep = __builtin_fmaf(S1, r2.y, ep);
;                     S.x = S0; S.y = S1;
;                     if (t >= 1) { const bool hit = oddrow && ((lane & 15) == ((t - 1) & 15)); if (t <= 16) yk0 = hit ? yprev : yk0; else yk1 = hit ? yprev : yk1; }
;                 }
	v_pk_mul_f32 v[150:151], v[142:143], v[126:127]
	v_pk_fma_f32 v[150:151], v[144:145], v[134:135], v[150:151]
	v_pk_mul_f32 v[152:153], v[142:143], v[232:233]
	v_add_f32_e32 v154, v150, v151
	v_pk_fma_f32 v[152:153], v[144:145], v[234:235], v[152:153]
	v_pk_mul_f32 v[146:147], v[142:143], v[128:129]
	v_add_f32_dpp v154, v154, v154 quad_perm:[1,0,3,2] row_mask:0xf bank_mask:0xf bound_ctrl:1
	v_pk_mul_f32 v[148:149], v[144:145], v[136:137]
	v_add_f32_e32 v157, v152, v153
	v_add_f32_dpp v154, v154, v154 quad_perm:[2,3,0,1] row_mask:0xf bank_mask:0xf bound_ctrl:1
	v_pk_fma_f32 v[146:147], v[242:243], v[132:133], v[146:147] op_sel:[0,0,0] op_sel_hi:[0,1,1]
	v_pk_fma_f32 v[148:149], v[242:243], v[224:225], v[148:149] op_sel:[0,0,0] op_sel_hi:[0,1,1]
	v_add_f32_dpp v154, v154, v154 row_half_mirror row_mask:0xf bank_mask:0xf bound_ctrl:1
	ds_read_b128 v[206:209], v182 offset:55296
	ds_read_b128 v[210:213], v182 offset:55312
	v_add_f32_dpp v154, v154, v154 row_mirror row_mask:0xf bank_mask:0xf bound_ctrl:1
	ds_read_b64 v[232:233], v182 offset:55328
	ds_read_b128 v[214:217], v183 offset:55296
	v_pk_fma_f32 v[146:147], v[154:155], v[130:131], v[146:147] op_sel_hi:[0,1,1]
	v_pk_fma_f32 v[148:149], v[154:155], v[222:223], v[148:149] op_sel_hi:[0,1,1]
	ds_read_b128 v[218:221], v183 offset:55312
	ds_read_b64 v[234:235], v183 offset:55328
	ds_read_b32 v241, v186 offset:2304
	s_waitcnt lgkmcnt(7)
	v_pk_mul_f32 v[150:151], v[146:147], v[190:191]
	v_pk_fma_f32 v[150:151], v[148:149], v[198:199], v[150:151]
	v_pk_mul_f32 v[152:153], v[146:147], v[236:237]
	v_add_f32_e32 v154, v150, v151
	v_pk_fma_f32 v[152:153], v[148:149], v[238:239], v[152:153]
	v_pk_mul_f32 v[142:143], v[146:147], v[192:193]
	v_add_f32_dpp v154, v154, v154 quad_perm:[1,0,3,2] row_mask:0xf bank_mask:0xf bound_ctrl:1
	v_pk_mul_f32 v[144:145], v[148:149], v[200:201]
	v_add_f32_e32 v158, v152, v153
	v_add_f32_dpp v154, v154, v154 quad_perm:[2,3,0,1] row_mask:0xf bank_mask:0xf bound_ctrl:1
	v_pk_fma_f32 v[142:143], v[240:241], v[196:197], v[142:143] op_sel:[0,0,0] op_sel_hi:[0,1,1]
	v_pk_fma_f32 v[144:145], v[240:241], v[204:205], v[144:145] op_sel:[0,0,0] op_sel_hi:[0,1,1]
	v_add_f32_dpp v154, v154, v154 row_half_mirror row_mask:0xf bank_mask:0xf bound_ctrl:1
	ds_read_b128 v[126:129], v182 offset:56832
	ds_read_b128 v[130:133], v182 offset:56848
	v_add_f32_dpp v154, v154, v154 row_mirror row_mask:0xf bank_mask:0xf bound_ctrl:1
	ds_read_b64 v[236:237], v182 offset:56864
	ds_read_b128 v[134:137], v183 offset:56832
	v_pk_fma_f32 v[142:143], v[154:155], v[194:195], v[142:143] op_sel_hi:[0,1,1]
	v_pk_fma_f32 v[144:145], v[154:155], v[202:203], v[144:145] op_sel_hi:[0,1,1]
	ds_read_b128 v[222:225], v183 offset:56848
	ds_read_b64 v[238:239], v183 offset:56864
	ds_read_b32 v242, v186 offset:2368
	s_waitcnt lgkmcnt(7)
	v_pk_mul_f32 v[150:151], v[142:143], v[206:207]
	v_pk_fma_f32 v[150:151], v[144:145], v[214:215], v[150:151]
	v_pk_mul_f32 v[152:153], v[142:143], v[228:229]
	v_add_f32_e32 v154, v150, v151
	v_pk_fma_f32 v[152:153], v[144:145], v[230:231], v[152:153]
	v_pk_mul_f32 v[146:147], v[142:143], v[208:209]
	v_add_f32_dpp v154, v154, v154 quad_perm:[1,0,3,2] row_mask:0xf bank_mask:0xf bound_ctrl:1
	v_pk_mul_f32 v[148:149], v[144:145], v[216:217]
	v_add_f32_e32 v159, v152, v153
	v_add_f32_dpp v154, v154, v154 quad_perm:[2,3,0,1] row_mask:0xf bank_mask:0xf bound_ctrl:1
	v_pk_fma_f32 v[146:147], v[240:241], v[212:213], v[146:147] op_sel:[1,0,0] op_sel_hi:[1,1,1]
	v_pk_fma_f32 v[148:149], v[240:241], v[220:221], v[148:149] op_sel:[1,0,0] op_sel_hi:[1,1,1]
	v_add_f32_dpp v154, v154, v154 row_half_mirror row_mask:0xf bank_mask:0xf bound_ctrl:1
	ds_read_b128 v[190:193], v182 offset:58368
	ds_read_b128 v[194:197], v182 offset:58384
	v_add_f32_dpp v154, v154, v154 row_mirror row_mask:0xf bank_mask:0xf bound_ctrl:1
	ds_read_b64 v[228:229], v182 offset:58400
	ds_read_b128 v[198:201], v183 offset:58368
	v_pk_fma_f32 v[146:147], v[154:155], v[210:211], v[146:147] op_sel_hi:[0,1,1]
	v_pk_fma_f32 v[148:149], v[154:155], v[218:219], v[148:149] op_sel_hi:[0,1,1]
	ds_read_b128 v[202:205], v183 offset:58384
	ds_read_b64 v[230:231], v183 offset:58400
	ds_read_b32 v240, v186 offset:2432
	s_waitcnt lgkmcnt(7)
	v_pk_mul_f32 v[150:151], v[146:147], v[126:127]
	v_pk_fma_f32 v[150:151], v[148:149], v[134:135], v[150:151]
	v_pk_mul_f32 v[152:153], v[146:147], v[232:233]
	v_add_f32_e32 v154, v150, v151
	v_pk_fma_f32 v[152:153], v[148:149], v[234:235], v[152:153]
	v_pk_mul_f32 v[142:143], v[146:147], v[128:129]
	v_add_f32_dpp v154, v154, v154 quad_perm:[1,0,3,2] row_mask:0xf bank_mask:0xf bound_ctrl:1
	v_pk_mul_f32 v[144:145], v[148:149], v[136:137]
	v_add_f32_e32 v160, v152, v153
	v_add_f32_dpp v154, v154, v154 quad_perm:[2,3,0,1] row_mask:0xf bank_mask:0xf bound_ctrl:1
	v_pk_fma_f32 v[142:143], v[242:243], v[132:133], v[142:143] op_sel:[0,0,0] op_sel_hi:[0,1,1]
	v_pk_fma_f32 v[144:145], v[242:243], v[224:225], v[144:145] op_sel:[0,0,0] op_sel_hi:[0,1,1]
	v_add_f32_dpp v154, v154, v154 row_half_mirror row_mask:0xf bank_mask:0xf bound_ctrl:1
	ds_read_b128 v[206:209], v182 offset:59904
	ds_read_b128 v[210:213], v182 offset:59920
	v_add_f32_dpp v154, v154, v154 row_mirror row_mask:0xf bank_mask:0xf bound_ctrl:1
	ds_read_b64 v[232:233], v182 offset:59936
	ds_read_b128 v[214:217], v183 offset:59904
	v_pk_fma_f32 v[142:143], v[154:155], v[130:131], v[142:143] op_sel_hi:[0,1,1]
	v_pk_fma_f32 v[144:145], v[154:155], v[222:223], v[144:145] op_sel_hi:[0,1,1]
	ds_read_b128 v[218:221], v183 offset:59920
	ds_read_b64 v[234:235], v183 offset:59936
	ds_read_b32 v241, v186 offset:2496
	s_waitcnt lgkmcnt(7)
; __device__ __forceinline__ void wkv_phase(const WkvT& W, unsigned char* lds) {
;     ...
;                 for (int t = 0; t < 32; ++t) {
;                     const f32x2 a2 = {nA[0], nA[1]}, w2 = {nA[2], nA[3]}, b2 = {nB[0], nB[1]}, k2 = {nB[2], nB[3]}, r2 = nr; const float v = nv;
;                     if (t + 1 < 32) { nA = *(const f32x4*)(pp + (t + 1) * 384); nB = *(const f32x4*)(pp + (t + 1) * 384 + 4); nr = *(const f32x2*)(pp + (t + 1) * 384 + 8); nv = pv[(t + 1) * 16]; }
;                     float S0 = S.x, S1 = S.y;
;                     float d = S0 * a2.x; d = __builtin_fmaf(S1, a2.y, d);
;                     float t0 = S0 * w2.x; t0 = __builtin_fmaf(v, k2.x, t0); asm volatile("" : "+v"(t0));
;                     float t1 = S1 * w2.y; t1 = __builtin_fmaf(v, k2.y, t1); asm volatile("" : "+v"(t1));
;                     float yprev; const float sa = wkv_reduce(d, ep, yprev);
;                     S0 = __builtin_fmaf(sa, b2.x, t0); asm volatile("" : "+v"(S0));
;                     S1 = __builtin_fmaf(sa, b2.y, t1); asm volatile("" : "+v"(S1));
;                     ep = S0 * r2.x; ep = __builtin_fmaf(S1, r2.y, ep);
;                     S.x = S0; S.y = S1;
;                     if (t >= 1) { const bool hit = oddrow && ((lane & 15) == ((t - 1) & 15)); if (t <= 16) yk0 = hit ? yprev : yk0; else yk1 = hit ? yprev : yk1; }
;                 }
	v_pk_mul_f32 v[150:151], v[142:143], v[190:191]
	v_pk_fma_f32 v[150:151], v[144:145], v[198:199], v[150:151]
	v_pk_mul_f32 v[152:153], v[142:143], v[236:237]
	v_add_f32_e32 v154, v150, v151
	v_pk_fma_f32 v[152:153], v[144:145], v[238:239], v[152:153]
	v_pk_mul_f32 v[146:147], v[142:143], v[192:193]
	v_add_f32_dpp v154, v154, v154 quad_perm:[1,0,3,2] row_mask:0xf bank_mask:0xf bound_ctrl:1
	v_pk_mul_f32 v[148:149], v[144:145], v[200:201]
	v_add_f32_e32 v161, v152, v153
	v_add_f32_dpp v154, v154, v154 quad_perm:[2,3,0,1] row_mask:0xf bank_mask:0xf bound_ctrl:1
	v_pk_fma_f32 v[146:147], v[240:241], v[196:197], v[146:147] op_sel:[0,0,0] op_sel_hi:[0,1,1]
	v_pk_fma_f32 v[148:149], v[240:241], v[204:205], v[148:149] op_sel:[0,0,0] op_sel_hi:[0,1,1]
	v_add_f32_dpp v154, v154, v154 row_half_mirror row_mask:0xf bank_mask:0xf bound_ctrl:1
	ds_read_b128 v[126:129], v182 offset:61440
	ds_read_b128 v[130:133], v182 offset:61456
	v_add_f32_dpp v154, v154, v154 row_mirror row_mask:0xf bank_mask:0xf bound_ctrl:1
	ds_read_b64 v[236:237], v182 offset:61472
	ds_read_b128 v[134:137], v183 offset:61440
	v_pk_fma_f32 v[146:147], v[154:155], v[194:195], v[146:147] op_sel_hi:[0,1,1]
	v_pk_fma_f32 v[148:149], v[154:155], v[202:203], v[148:149] op_sel_hi:[0,1,1]
	ds_read_b128 v[222:225], v183 offset:61456
	ds_read_b64 v[238:239], v183 offset:61472
	ds_read_b32 v242, v186 offset:2560
	s_waitcnt lgkmcnt(7)
	v_pk_mul_f32 v[150:151], v[146:147], v[206:207]
	v_pk_fma_f32 v[150:151], v[148:149], v[214:215], v[150:151]
	v_pk_mul_f32 v[152:153], v[146:147], v[228:229]
	v_add_f32_e32 v154, v150, v151
	v_pk_fma_f32 v[152:153], v[148:149], v[230:231], v[152:153]
	v_pk_mul_f32 v[142:143], v[146:147], v[208:209]
	v_add_f32_dpp v154, v154, v154 quad_perm:[1,0,3,2] row_mask:0xf bank_mask:0xf bound_ctrl:1
	v_pk_mul_f32 v[144:145], v[148:149], v[216:217]
	v_add_f32_e32 v162, v152, v153
	v_add_f32_dpp v154, v154, v154 quad_perm:[2,3,0,1] row_mask:0xf bank_mask:0xf bound_ctrl:1
	v_pk_fma_f32 v[142:143], v[240:241], v[212:213], v[142:143] op_sel:[1,0,0] op_sel_hi:[1,1,1]
	v_pk_fma_f32 v[144:145], v[240:241], v[220:221], v[144:145] op_sel:[1,0,0] op_sel_hi:[1,1,1]
	v_add_f32_dpp v154, v154, v154 row_half_mirror row_mask:0xf bank_mask:0xf bound_ctrl:1
	ds_read_b128 v[190:193], v182 offset:62976
	ds_read_b128 v[194:197], v182 offset:62992
	v_add_f32_dpp v154, v154, v154 row_mirror row_mask:0xf bank_mask:0xf bound_ctrl:1
	ds_read_b64 v[228:229], v182 offset:63008
	ds_read_b128 v[198:201], v183 offset:62976
	v_pk_fma_f32 v[142:143], v[154:155], v[210:211], v[142:143] op_sel_hi:[0,1,1]
	v_pk_fma_f32 v[144:145], v[154:155], v[218:219], v[144:145] op_sel_hi:[0,1,1]
	ds_read_b128 v[202:205], v183 offset:62992
	ds_read_b64 v[230:231], v183 offset:63008
	ds_read_b32 v240, v186 offset:2624
	s_waitcnt lgkmcnt(7)
	v_pk_mul_f32 v[150:151], v[142:143], v[126:127]
	v_pk_fma_f32 v[150:151], v[144:145], v[134:135], v[150:151]
	v_pk_mul_f32 v[152:153], v[142:143], v[232:233]
	v_add_f32_e32 v154, v150, v151
	v_pk_fma_f32 v[152:153], v[144:145], v[234:235], v[152:153]
	v_pk_mul_f32 v[146:147], v[142:143], v[128:129]
	v_add_f32_dpp v154, v154, v154 quad_perm:[1,0,3,2] row_mask:0xf bank_mask:0xf bound_ctrl:1
	v_pk_mul_f32 v[148:149], v[144:145], v[136:137]
	v_add_f32_e32 v163, v152, v153
	v_add_f32_dpp v154, v154, v154 quad_perm:[2,3,0,1] row_mask:0xf bank_mask:0xf bound_ctrl:1
	v_pk_fma_f32 v[146:147], v[242:243], v[132:133], v[146:147] op_sel:[0,0,0] op_sel_hi:[0,1,1]
	v_pk_fma_f32 v[148:149], v[242:243], v[224:225], v[148:149] op_sel:[0,0,0] op_sel_hi:[0,1,1]
	v_add_f32_dpp v154, v154, v154 row_half_mirror row_mask:0xf bank_mask:0xf bound_ctrl:1
	ds_read_b128 v[206:209], v182 offset:64512
	ds_read_b128 v[210:213], v182 offset:64528
	v_add_f32_dpp v154, v154, v154 row_mirror row_mask:0xf bank_mask:0xf bound_ctrl:1
	ds_read_b64 v[232:233], v182 offset:64544
	ds_read_b128 v[214:217], v183 offset:64512
	v_pk_fma_f32 v[146:147], v[154:155], v[130:131], v[146:147] op_sel_hi:[0,1,1]
	v_pk_fma_f32 v[148:149], v[154:155], v[222:223], v[148:149] op_sel_hi:[0,1,1]
	ds_read_b128 v[218:221], v183 offset:64528
	ds_read_b64 v[234:235], v183 offset:64544
	ds_read_b32 v241, v186 offset:2688
	s_waitcnt lgkmcnt(7)
	v_pk_mul_f32 v[150:151], v[146:147], v[190:191]
	v_pk_fma_f32 v[150:151], v[148:149], v[198:199], v[150:151]
	v_pk_mul_f32 v[152:153], v[146:147], v[236:237]
	v_add_f32_e32 v154, v150, v151
	v_pk_fma_f32 v[152:153], v[148:149], v[238:239], v[152:153]
	v_pk_mul_f32 v[142:143], v[146:147], v[192:193]
	v_add_f32_dpp v154, v154, v154 quad_perm:[1,0,3,2] row_mask:0xf bank_mask:0xf bound_ctrl:1
	v_pk_mul_f32 v[144:145], v[148:149], v[200:201]
	v_add_f32_e32 v164, v152, v153
	v_add_f32_dpp v154, v154, v154 quad_perm:[2,3,0,1] row_mask:0xf bank_mask:0xf bound_ctrl:1
	v_pk_fma_f32 v[142:143], v[240:241], v[196:197], v[142:143] op_sel:[0,0,0] op_sel_hi:[0,1,1]
	v_pk_fma_f32 v[144:145], v[240:241], v[204:205], v[144:145] op_sel:[0,0,0] op_sel_hi:[0,1,1]
	v_add_f32_dpp v154, v154, v154 row_half_mirror row_mask:0xf bank_mask:0xf bound_ctrl:1
	ds_read_b128 v[126:129], v184
	ds_read_b128 v[130:133], v184 offset:16
	v_add_f32_dpp v154, v154, v154 row_mirror row_mask:0xf bank_mask:0xf bound_ctrl:1
	ds_read_b64 v[236:237], v184 offset:32
	ds_read_b128 v[134:137], v185
	v_pk_fma_f32 v[142:143], v[154:155], v[194:195], v[142:143] op_sel_hi:[0,1,1]
	v_pk_fma_f32 v[144:145], v[154:155], v[202:203], v[144:145] op_sel_hi:[0,1,1]
	ds_read_b128 v[222:225], v185 offset:16
	ds_read_b64 v[238:239], v185 offset:32
	ds_read_b32 v242, v186 offset:2752
	s_waitcnt lgkmcnt(7)
; __device__ __forceinline__ void wkv_phase(const WkvT& W, unsigned char* lds) {
;     ...
;                 for (int t = 0; t < 32; ++t) {
;                     const f32x2 a2 = {nA[0], nA[1]}, w2 = {nA[2], nA[3]}, b2 = {nB[0], nB[1]}, k2 = {nB[2], nB[3]}, r2 = nr; const float v = nv;
;                     if (t + 1 < 32) { nA = *(const f32x4*)(pp + (t + 1) * 384); nB = *(const f32x4*)(pp + (t + 1) * 384 + 4); nr = *(const f32x2*)(pp + (t + 1) * 384 + 8); nv = pv[(t + 1) * 16]; }
;                     float S0 = S.x, S1 = S.y;
;                     float d = S0 * a2.x; d = __builtin_fmaf(S1, a2.y, d);
;                     float t0 = S0 * w2.x; t0 = __builtin_fmaf(v, k2.x, t0); asm volatile("" : "+v"(t0));
;                     float t1 = S1 * w2.y; t1 = __builtin_fmaf(v, k2.y, t1); asm volatile("" : "+v"(t1));
;                     float yprev; const float sa = wkv_reduce(d, ep, yprev);
;                     S0 = __builtin_fmaf(sa, b2.x, t0); asm volatile("" : "+v"(S0));
;                     S1 = __builtin_fmaf(sa, b2.y, t1); asm volatile("" : "+v"(S1));
;                     ep = S0 * r2.x; ep = __builtin_fmaf(S1, r2.y, ep);
;                     S.x = S0; S.y = S1;
;                     if (t >= 1) { const bool hit = oddrow && ((lane & 15) == ((t - 1) & 15)); if (t <= 16) yk0 = hit ? yprev : yk0; else yk1 = hit ? yprev : yk1; }
;                 }
	v_pk_mul_f32 v[150:151], v[142:143], v[206:207]
	v_pk_fma_f32 v[150:151], v[144:145], v[214:215], v[150:151]
	v_pk_mul_f32 v[152:153], v[142:143], v[228:229]
	v_add_f32_e32 v154, v150, v151
	v_pk_fma_f32 v[152:153], v[144:145], v[230:231], v[152:153]
	v_pk_mul_f32 v[146:147], v[142:143], v[208:209]
	v_add_f32_dpp v154, v154, v154 quad_perm:[1,0,3,2] row_mask:0xf bank_mask:0xf bound_ctrl:1
	v_pk_mul_f32 v[148:149], v[144:145], v[216:217]
	v_add_f32_e32 v165, v152, v153
	v_add_f32_dpp v154, v154, v154 quad_perm:[2,3,0,1] row_mask:0xf bank_mask:0xf bound_ctrl:1
	v_pk_fma_f32 v[146:147], v[240:241], v[212:213], v[146:147] op_sel:[1,0,0] op_sel_hi:[1,1,1]
	v_pk_fma_f32 v[148:149], v[240:241], v[220:221], v[148:149] op_sel:[1,0,0] op_sel_hi:[1,1,1]
	v_add_f32_dpp v154, v154, v154 row_half_mirror row_mask:0xf bank_mask:0xf bound_ctrl:1
	ds_read_b128 v[190:193], v184 offset:1536
	ds_read_b128 v[194:197], v184 offset:1552
	v_add_f32_dpp v154, v154, v154 row_mirror row_mask:0xf bank_mask:0xf bound_ctrl:1
	ds_read_b64 v[228:229], v184 offset:1568
	ds_read_b128 v[198:201], v185 offset:1536
	v_pk_fma_f32 v[146:147], v[154:155], v[210:211], v[146:147] op_sel_hi:[0,1,1]
	v_pk_fma_f32 v[148:149], v[154:155], v[218:219], v[148:149] op_sel_hi:[0,1,1]
	ds_read_b128 v[202:205], v185 offset:1552
	ds_read_b64 v[230:231], v185 offset:1568
	ds_read_b32 v240, v186 offset:2816
	s_waitcnt lgkmcnt(7)
	v_pk_mul_f32 v[150:151], v[146:147], v[126:127]
	v_pk_fma_f32 v[150:151], v[148:149], v[134:135], v[150:151]
	v_pk_mul_f32 v[152:153], v[146:147], v[232:233]
	v_add_f32_e32 v154, v150, v151
	v_pk_fma_f32 v[152:153], v[148:149], v[234:235], v[152:153]
	v_pk_mul_f32 v[142:143], v[146:147], v[128:129]
	v_add_f32_dpp v154, v154, v154 quad_perm:[1,0,3,2] row_mask:0xf bank_mask:0xf bound_ctrl:1
	v_pk_mul_f32 v[144:145], v[148:149], v[136:137]
	v_add_f32_e32 v166, v152, v153
	v_add_f32_dpp v154, v154, v154 quad_perm:[2,3,0,1] row_mask:0xf bank_mask:0xf bound_ctrl:1
	v_pk_fma_f32 v[142:143], v[242:243], v[132:133], v[142:143] op_sel:[0,0,0] op_sel_hi:[0,1,1]
	v_pk_fma_f32 v[144:145], v[242:243], v[224:225], v[144:145] op_sel:[0,0,0] op_sel_hi:[0,1,1]
	v_add_f32_dpp v154, v154, v154 row_half_mirror row_mask:0xf bank_mask:0xf bound_ctrl:1
	ds_read_b128 v[206:209], v184 offset:3072
	ds_read_b128 v[210:213], v184 offset:3088
	v_add_f32_dpp v154, v154, v154 row_mirror row_mask:0xf bank_mask:0xf bound_ctrl:1
	ds_read_b64 v[232:233], v184 offset:3104
	ds_read_b128 v[214:217], v185 offset:3072
	v_pk_fma_f32 v[142:143], v[154:155], v[130:131], v[142:143] op_sel_hi:[0,1,1]
	v_pk_fma_f32 v[144:145], v[154:155], v[222:223], v[144:145] op_sel_hi:[0,1,1]
	ds_read_b128 v[218:221], v185 offset:3088
	ds_read_b64 v[234:235], v185 offset:3104
	ds_read_b32 v241, v186 offset:2880
	s_waitcnt lgkmcnt(7)
	v_pk_mul_f32 v[150:151], v[142:143], v[190:191]
	v_pk_fma_f32 v[150:151], v[144:145], v[198:199], v[150:151]
	v_pk_mul_f32 v[152:153], v[142:143], v[236:237]
	v_add_f32_e32 v154, v150, v151
	v_pk_fma_f32 v[152:153], v[144:145], v[238:239], v[152:153]
	v_pk_mul_f32 v[146:147], v[142:143], v[192:193]
	v_add_f32_dpp v154, v154, v154 quad_perm:[1,0,3,2] row_mask:0xf bank_mask:0xf bound_ctrl:1
	v_pk_mul_f32 v[148:149], v[144:145], v[200:201]
	v_add_f32_e32 v167, v152, v153
	v_add_f32_dpp v154, v154, v154 quad_perm:[2,3,0,1] row_mask:0xf bank_mask:0xf bound_ctrl:1
	v_pk_fma_f32 v[146:147], v[240:241], v[196:197], v[146:147] op_sel:[0,0,0] op_sel_hi:[0,1,1]
	v_pk_fma_f32 v[148:149], v[240:241], v[204:205], v[148:149] op_sel:[0,0,0] op_sel_hi:[0,1,1]
	v_add_f32_dpp v154, v154, v154 row_half_mirror row_mask:0xf bank_mask:0xf bound_ctrl:1
	ds_read_b128 v[126:129], v184 offset:4608
	ds_read_b128 v[130:133], v184 offset:4624
	v_add_f32_dpp v154, v154, v154 row_mirror row_mask:0xf bank_mask:0xf bound_ctrl:1
	ds_read_b64 v[236:237], v184 offset:4640
	ds_read_b128 v[134:137], v185 offset:4608
	v_pk_fma_f32 v[146:147], v[154:155], v[194:195], v[146:147] op_sel_hi:[0,1,1]
	v_pk_fma_f32 v[148:149], v[154:155], v[202:203], v[148:149] op_sel_hi:[0,1,1]
	ds_read_b128 v[222:225], v185 offset:4624
	ds_read_b64 v[238:239], v185 offset:4640
	ds_read_b32 v242, v186 offset:2944
	s_waitcnt lgkmcnt(7)
	v_pk_mul_f32 v[150:151], v[146:147], v[206:207]
	v_pk_fma_f32 v[150:151], v[148:149], v[214:215], v[150:151]
	v_pk_mul_f32 v[152:153], v[146:147], v[228:229]
	v_add_f32_e32 v154, v150, v151
	v_pk_fma_f32 v[152:153], v[148:149], v[230:231], v[152:153]
	v_pk_mul_f32 v[142:143], v[146:147], v[208:209]
	v_add_f32_dpp v154, v154, v154 quad_perm:[1,0,3,2] row_mask:0xf bank_mask:0xf bound_ctrl:1
	v_pk_mul_f32 v[144:145], v[148:149], v[216:217]
	v_add_f32_e32 v168, v152, v153
	v_add_f32_dpp v154, v154, v154 quad_perm:[2,3,0,1] row_mask:0xf bank_mask:0xf bound_ctrl:1
	v_pk_fma_f32 v[142:143], v[240:241], v[212:213], v[142:143] op_sel:[1,0,0] op_sel_hi:[1,1,1]
	v_pk_fma_f32 v[144:145], v[240:241], v[220:221], v[144:145] op_sel:[1,0,0] op_sel_hi:[1,1,1]
	v_add_f32_dpp v154, v154, v154 row_half_mirror row_mask:0xf bank_mask:0xf bound_ctrl:1
	ds_read_b128 v[190:193], v184 offset:6144
	ds_read_b128 v[194:197], v184 offset:6160
	v_add_f32_dpp v154, v154, v154 row_mirror row_mask:0xf bank_mask:0xf bound_ctrl:1
	ds_read_b64 v[228:229], v184 offset:6176
	ds_read_b128 v[198:201], v185 offset:6144
	v_pk_fma_f32 v[142:143], v[154:155], v[210:211], v[142:143] op_sel_hi:[0,1,1]
	v_pk_fma_f32 v[144:145], v[154:155], v[218:219], v[144:145] op_sel_hi:[0,1,1]
	ds_read_b128 v[202:205], v185 offset:6160
	ds_read_b64 v[230:231], v185 offset:6176
	ds_read_b32 v240, v186 offset:3008
	s_waitcnt lgkmcnt(7)
; __device__ __forceinline__ void wkv_phase(const WkvT& W, unsigned char* lds) {
;     ...
;                 for (int t = 0; t < 32; ++t) {
;                     const f32x2 a2 = {nA[0], nA[1]}, w2 = {nA[2], nA[3]}, b2 = {nB[0], nB[1]}, k2 = {nB[2], nB[3]}, r2 = nr; const float v = nv;
;                     if (t + 1 < 32) { nA = *(const f32x4*)(pp + (t + 1) * 384); nB = *(const f32x4*)(pp + (t + 1) * 384 + 4); nr = *(const f32x2*)(pp + (t + 1) * 384 + 8); nv = pv[(t + 1) * 16]; }
;                     float S0 = S.x, S1 = S.y;
;                     float d = S0 * a2.x; d = __builtin_fmaf(S1, a2.y, d);
;                     float t0 = S0 * w2.x; t0 = __builtin_fmaf(v, k2.x, t0); asm volatile("" : "+v"(t0));
;                     float t1 = S1 * w2.y; t1 = __builtin_fmaf(v, k2.y, t1); asm volatile("" : "+v"(t1));
;                     float yprev; const float sa = wkv_reduce(d, ep, yprev);
;                     S0 = __builtin_fmaf(sa, b2.x, t0); asm volatile("" : "+v"(S0));
;                     S1 = __builtin_fmaf(sa, b2.y, t1); asm volatile("" : "+v"(S1));
;                     ep = S0 * r2.x; ep = __builtin_fmaf(S1, r2.y, ep);
;                     S.x = S0; S.y = S1;
;                     if (t >= 1) { const bool hit = oddrow && ((lane & 15) == ((t - 1) & 15)); if (t <= 16) yk0 = hit ? yprev : yk0; else yk1 = hit ? yprev : yk1; }
;                 }
;                 { float ylast; (void)wkv_reduce(0.f, ep, ylast); yk1 = (oddrow && (lane & 15) == 15) ? ylast : yk1; }
;                 if (oddrow) { sY[bi * 512 + (lane & 15) * 16 + il] = yk0; sY[bi * 512 + (16 + (lane & 15)) * 16 + il] = yk1; }
	v_pk_mul_f32 v[150:151], v[142:143], v[126:127]
	v_pk_fma_f32 v[150:151], v[144:145], v[134:135], v[150:151]
	v_pk_mul_f32 v[152:153], v[142:143], v[232:233]
	v_add_f32_e32 v154, v150, v151
	v_pk_fma_f32 v[152:153], v[144:145], v[234:235], v[152:153]
	v_pk_mul_f32 v[146:147], v[142:143], v[128:129]
	v_add_f32_dpp v154, v154, v154 quad_perm:[1,0,3,2] row_mask:0xf bank_mask:0xf bound_ctrl:1
	v_pk_mul_f32 v[148:149], v[144:145], v[136:137]
	v_add_f32_e32 v169, v152, v153
	v_add_f32_dpp v154, v154, v154 quad_perm:[2,3,0,1] row_mask:0xf bank_mask:0xf bound_ctrl:1
	v_pk_fma_f32 v[146:147], v[242:243], v[132:133], v[146:147] op_sel:[0,0,0] op_sel_hi:[0,1,1]
	v_pk_fma_f32 v[148:149], v[242:243], v[224:225], v[148:149] op_sel:[0,0,0] op_sel_hi:[0,1,1]
	v_add_f32_dpp v154, v154, v154 row_half_mirror row_mask:0xf bank_mask:0xf bound_ctrl:1
	ds_read_b128 v[206:209], v184 offset:7680
	ds_read_b128 v[210:213], v184 offset:7696
	v_add_f32_dpp v154, v154, v154 row_mirror row_mask:0xf bank_mask:0xf bound_ctrl:1
	ds_read_b64 v[232:233], v184 offset:7712
	ds_read_b128 v[214:217], v185 offset:7680
	v_pk_fma_f32 v[146:147], v[154:155], v[130:131], v[146:147] op_sel_hi:[0,1,1]
	v_pk_fma_f32 v[148:149], v[154:155], v[222:223], v[148:149] op_sel_hi:[0,1,1]
	ds_read_b128 v[218:221], v185 offset:7696
	ds_read_b64 v[234:235], v185 offset:7712
	ds_read_b32 v241, v186 offset:3072
	s_waitcnt lgkmcnt(7)
	v_pk_mul_f32 v[150:151], v[146:147], v[190:191]
	v_pk_fma_f32 v[150:151], v[148:149], v[198:199], v[150:151]
	v_pk_mul_f32 v[152:153], v[146:147], v[236:237]
	v_add_f32_e32 v154, v150, v151
	v_pk_fma_f32 v[152:153], v[148:149], v[238:239], v[152:153]
	v_pk_mul_f32 v[142:143], v[146:147], v[192:193]
	v_add_f32_dpp v154, v154, v154 quad_perm:[1,0,3,2] row_mask:0xf bank_mask:0xf bound_ctrl:1
	v_pk_mul_f32 v[144:145], v[148:149], v[200:201]
	v_add_f32_e32 v170, v152, v153
	v_add_f32_dpp v154, v154, v154 quad_perm:[2,3,0,1] row_mask:0xf bank_mask:0xf bound_ctrl:1
	v_pk_fma_f32 v[142:143], v[240:241], v[196:197], v[142:143] op_sel:[0,0,0] op_sel_hi:[0,1,1]
	v_pk_fma_f32 v[144:145], v[240:241], v[204:205], v[144:145] op_sel:[0,0,0] op_sel_hi:[0,1,1]
	v_add_f32_dpp v154, v154, v154 row_half_mirror row_mask:0xf bank_mask:0xf bound_ctrl:1
	ds_read_b128 v[126:129], v184 offset:9216
	ds_read_b128 v[130:133], v184 offset:9232
	v_add_f32_dpp v154, v154, v154 row_mirror row_mask:0xf bank_mask:0xf bound_ctrl:1
	ds_read_b64 v[236:237], v184 offset:9248
	ds_read_b128 v[134:137], v185 offset:9216
	v_pk_fma_f32 v[142:143], v[154:155], v[194:195], v[142:143] op_sel_hi:[0,1,1]
	v_pk_fma_f32 v[144:145], v[154:155], v[202:203], v[144:145] op_sel_hi:[0,1,1]
	ds_read_b128 v[222:225], v185 offset:9232
	ds_read_b64 v[238:239], v185 offset:9248
	ds_read_b32 v242, v186 offset:3136
	s_waitcnt lgkmcnt(7)
	v_pk_mul_f32 v[150:151], v[142:143], v[206:207]
	v_pk_fma_f32 v[150:151], v[144:145], v[214:215], v[150:151]
	v_pk_mul_f32 v[152:153], v[142:143], v[228:229]
	v_add_f32_e32 v154, v150, v151
	v_pk_fma_f32 v[152:153], v[144:145], v[230:231], v[152:153]
	v_pk_mul_f32 v[146:147], v[142:143], v[208:209]
	v_add_f32_dpp v154, v154, v154 quad_perm:[1,0,3,2] row_mask:0xf bank_mask:0xf bound_ctrl:1
	v_pk_mul_f32 v[148:149], v[144:145], v[216:217]
	v_add_f32_e32 v171, v152, v153
	v_add_f32_dpp v154, v154, v154 quad_perm:[2,3,0,1] row_mask:0xf bank_mask:0xf bound_ctrl:1
	v_pk_fma_f32 v[146:147], v[240:241], v[212:213], v[146:147] op_sel:[1,0,0] op_sel_hi:[1,1,1]
	v_pk_fma_f32 v[148:149], v[240:241], v[220:221], v[148:149] op_sel:[1,0,0] op_sel_hi:[1,1,1]
	v_add_f32_dpp v154, v154, v154 row_half_mirror row_mask:0xf bank_mask:0xf bound_ctrl:1
	ds_read_b128 v[190:193], v184 offset:10752
	ds_read_b128 v[194:197], v184 offset:10768
	v_add_f32_dpp v154, v154, v154 row_mirror row_mask:0xf bank_mask:0xf bound_ctrl:1
	ds_read_b64 v[228:229], v184 offset:10784
	ds_read_b128 v[198:201], v185 offset:10752
	v_pk_fma_f32 v[146:147], v[154:155], v[210:211], v[146:147] op_sel_hi:[0,1,1]
	v_pk_fma_f32 v[148:149], v[154:155], v[218:219], v[148:149] op_sel_hi:[0,1,1]
	ds_read_b128 v[202:205], v185 offset:10768
	ds_read_b64 v[230:231], v185 offset:10784
	ds_read_b32 v240, v186 offset:3200
	s_waitcnt lgkmcnt(7)
	v_cndmask_b32_e64 v172, v164, v156, s[10:11]
	v_cndmask_b32_e64 v174, v165, v157, s[10:11]
	v_cndmask_b32_e64 v176, v166, v158, s[10:11]
	v_cndmask_b32_e64 v178, v167, v159, s[10:11]
	v_cndmask_b32_e64 v173, v156, v164, s[10:11]
	v_cndmask_b32_e64 v175, v157, v165, s[10:11]
	v_cndmask_b32_e64 v177, v158, v166, s[10:11]
	v_cndmask_b32_e64 v179, v159, v167, s[10:11]
	v_add_f32_dpp v156, v172, v173 row_ror:8 row_mask:0xf bank_mask:0xf
	v_add_f32_dpp v157, v174, v175 row_ror:8 row_mask:0xf bank_mask:0xf
	v_add_f32_dpp v158, v176, v177 row_ror:8 row_mask:0xf bank_mask:0xf
	v_add_f32_dpp v159, v178, v179 row_ror:8 row_mask:0xf bank_mask:0xf
	v_cndmask_b32_e64 v172, v168, v160, s[10:11]
	v_cndmask_b32_e64 v174, v169, v161, s[10:11]
	v_cndmask_b32_e64 v176, v170, v162, s[10:11]
	v_cndmask_b32_e64 v178, v171, v163, s[10:11]
	v_cndmask_b32_e64 v173, v160, v168, s[10:11]
	v_cndmask_b32_e64 v175, v161, v169, s[10:11]
	v_cndmask_b32_e64 v177, v162, v170, s[10:11]
	v_cndmask_b32_e64 v179, v163, v171, s[10:11]
	v_add_f32_dpp v160, v172, v173 row_ror:8 row_mask:0xf bank_mask:0xf
	v_add_f32_dpp v161, v174, v175 row_ror:8 row_mask:0xf bank_mask:0xf
	v_add_f32_dpp v162, v176, v177 row_ror:8 row_mask:0xf bank_mask:0xf
	v_add_f32_dpp v163, v178, v179 row_ror:8 row_mask:0xf bank_mask:0xf
	v_cndmask_b32_e64 v172, v160, v156, s[12:13]
	v_cndmask_b32_e64 v174, v161, v157, s[12:13]
	v_cndmask_b32_e64 v176, v162, v158, s[12:13]
; __device__ __forceinline__ void wkv_phase(const WkvT& W, unsigned char* lds) {
;     ...
;                 for (int t = 0; t < 32; ++t) {
;                     const f32x2 a2 = {nA[0], nA[1]}, w2 = {nA[2], nA[3]}, b2 = {nB[0], nB[1]}, k2 = {nB[2], nB[3]}, r2 = nr; const float v = nv;
;                     if (t + 1 < 32) { nA = *(const f32x4*)(pp + (t + 1) * 384); nB = *(const f32x4*)(pp + (t + 1) * 384 + 4); nr = *(const f32x2*)(pp + (t + 1) * 384 + 8); nv = pv[(t + 1) * 16]; }
;                     float S0 = S.x, S1 = S.y;
;                     float d = S0 * a2.x; d = __builtin_fmaf(S1, a2.y, d);
;                     float t0 = S0 * w2.x; t0 = __builtin_fmaf(v, k2.x, t0); asm volatile("" : "+v"(t0));
;                     float t1 = S1 * w2.y; t1 = __builtin_fmaf(v, k2.y, t1); asm volatile("" : "+v"(t1));
;                     float yprev; const float sa = wkv_reduce(d, ep, yprev);
;                     S0 = __builtin_fmaf(sa, b2.x, t0); asm volatile("" : "+v"(S0));
;                     S1 = __builtin_fmaf(sa, b2.y, t1); asm volatile("" : "+v"(S1));
;                     ep = S0 * r2.x; ep = __builtin_fmaf(S1, r2.y, ep);
;                     S.x = S0; S.y = S1;
;                     if (t >= 1) { const bool hit = oddrow && ((lane & 15) == ((t - 1) & 15)); if (t <= 16) yk0 = hit ? yprev : yk0; else yk1 = hit ? yprev : yk1; }
;                 }
;                 { float ylast; (void)wkv_reduce(0.f, ep, ylast); yk1 = (oddrow && (lane & 15) == 15) ? ylast : yk1; }
;                 if (oddrow) { sY[bi * 512 + (lane & 15) * 16 + il] = yk0; sY[bi * 512 + (16 + (lane & 15)) * 16 + il] = yk1; }
	v_cndmask_b32_e64 v178, v163, v159, s[12:13]
	v_cndmask_b32_e64 v173, v156, v160, s[12:13]
	v_cndmask_b32_e64 v175, v157, v161, s[12:13]
	v_cndmask_b32_e64 v177, v158, v162, s[12:13]
	v_cndmask_b32_e64 v179, v159, v163, s[12:13]
	v_add_f32_dpp v156, v172, v173 row_half_mirror row_mask:0xf bank_mask:0xf
	v_add_f32_dpp v157, v174, v175 row_half_mirror row_mask:0xf bank_mask:0xf
	v_add_f32_dpp v158, v176, v177 row_half_mirror row_mask:0xf bank_mask:0xf
	v_add_f32_dpp v159, v178, v179 row_half_mirror row_mask:0xf bank_mask:0xf
	v_cndmask_b32_e64 v172, v158, v156, s[14:15]
	v_cndmask_b32_e64 v174, v159, v157, s[14:15]
	v_cndmask_b32_e64 v173, v156, v158, s[14:15]
	v_cndmask_b32_e64 v175, v157, v159, s[14:15]
	v_add_f32_dpp v156, v172, v173 quad_perm:[2,3,0,1] row_mask:0xf bank_mask:0xf
	v_add_f32_dpp v157, v174, v175 quad_perm:[2,3,0,1] row_mask:0xf bank_mask:0xf
	v_cndmask_b32_e64 v172, v157, v156, s[16:17]
	v_cndmask_b32_e64 v173, v156, v157, s[16:17]
	s_nop 0
	v_add_f32_dpp v156, v172, v173 quad_perm:[1,0,3,2] row_mask:0xf bank_mask:0xf
	v_mov_b32_e32 v180, v156
	v_pk_mul_f32 v[150:151], v[146:147], v[126:127]
	v_pk_fma_f32 v[150:151], v[148:149], v[134:135], v[150:151]
	v_pk_mul_f32 v[152:153], v[146:147], v[232:233]
	v_add_f32_e32 v154, v150, v151
	v_pk_fma_f32 v[152:153], v[148:149], v[234:235], v[152:153]
	v_pk_mul_f32 v[142:143], v[146:147], v[128:129]
	v_add_f32_dpp v154, v154, v154 quad_perm:[1,0,3,2] row_mask:0xf bank_mask:0xf bound_ctrl:1
	v_pk_mul_f32 v[144:145], v[148:149], v[136:137]
	v_add_f32_e32 v156, v152, v153
	v_add_f32_dpp v154, v154, v154 quad_perm:[2,3,0,1] row_mask:0xf bank_mask:0xf bound_ctrl:1
	v_pk_fma_f32 v[142:143], v[242:243], v[132:133], v[142:143] op_sel:[0,0,0] op_sel_hi:[0,1,1]
	v_pk_fma_f32 v[144:145], v[242:243], v[224:225], v[144:145] op_sel:[0,0,0] op_sel_hi:[0,1,1]
	v_add_f32_dpp v154, v154, v154 row_half_mirror row_mask:0xf bank_mask:0xf bound_ctrl:1
	ds_read_b128 v[206:209], v184 offset:12288
	ds_read_b128 v[210:213], v184 offset:12304
	v_add_f32_dpp v154, v154, v154 row_mirror row_mask:0xf bank_mask:0xf bound_ctrl:1
	ds_read_b64 v[232:233], v184 offset:12320
	ds_read_b128 v[214:217], v185 offset:12288
	v_pk_fma_f32 v[142:143], v[154:155], v[130:131], v[142:143] op_sel_hi:[0,1,1]
	v_pk_fma_f32 v[144:145], v[154:155], v[222:223], v[144:145] op_sel_hi:[0,1,1]
	ds_read_b128 v[218:221], v185 offset:12304
	ds_read_b64 v[234:235], v185 offset:12320
	ds_read_b32 v241, v186 offset:3264
	s_waitcnt lgkmcnt(7)
	v_pk_mul_f32 v[150:151], v[142:143], v[190:191]
	v_pk_fma_f32 v[150:151], v[144:145], v[198:199], v[150:151]
	v_pk_mul_f32 v[152:153], v[142:143], v[236:237]
	v_add_f32_e32 v154, v150, v151
	v_pk_fma_f32 v[152:153], v[144:145], v[238:239], v[152:153]
	v_pk_mul_f32 v[146:147], v[142:143], v[192:193]
	v_add_f32_dpp v154, v154, v154 quad_perm:[1,0,3,2] row_mask:0xf bank_mask:0xf bound_ctrl:1
	v_pk_mul_f32 v[148:149], v[144:145], v[200:201]
	v_add_f32_e32 v157, v152, v153
	v_add_f32_dpp v154, v154, v154 quad_perm:[2,3,0,1] row_mask:0xf bank_mask:0xf bound_ctrl:1
	v_pk_fma_f32 v[146:147], v[240:241], v[196:197], v[146:147] op_sel:[0,0,0] op_sel_hi:[0,1,1]
	v_pk_fma_f32 v[148:149], v[240:241], v[204:205], v[148:149] op_sel:[0,0,0] op_sel_hi:[0,1,1]
	v_add_f32_dpp v154, v154, v154 row_half_mirror row_mask:0xf bank_mask:0xf bound_ctrl:1
	ds_read_b128 v[126:129], v184 offset:13824
	ds_read_b128 v[130:133], v184 offset:13840
	v_add_f32_dpp v154, v154, v154 row_mirror row_mask:0xf bank_mask:0xf bound_ctrl:1
	ds_read_b64 v[236:237], v184 offset:13856
	ds_read_b128 v[134:137], v185 offset:13824
	v_pk_fma_f32 v[146:147], v[154:155], v[194:195], v[146:147] op_sel_hi:[0,1,1]
	v_pk_fma_f32 v[148:149], v[154:155], v[202:203], v[148:149] op_sel_hi:[0,1,1]
	ds_read_b128 v[222:225], v185 offset:13840
	ds_read_b64 v[238:239], v185 offset:13856
	ds_read_b32 v242, v186 offset:3328
	s_waitcnt lgkmcnt(7)
	v_pk_mul_f32 v[150:151], v[146:147], v[206:207]
	v_pk_fma_f32 v[150:151], v[148:149], v[214:215], v[150:151]
	v_pk_mul_f32 v[152:153], v[146:147], v[228:229]
	v_add_f32_e32 v154, v150, v151
	v_pk_fma_f32 v[152:153], v[148:149], v[230:231], v[152:153]
	v_pk_mul_f32 v[142:143], v[146:147], v[208:209]
	v_add_f32_dpp v154, v154, v154 quad_perm:[1,0,3,2] row_mask:0xf bank_mask:0xf bound_ctrl:1
	v_pk_mul_f32 v[144:145], v[148:149], v[216:217]
	v_add_f32_e32 v158, v152, v153
	v_add_f32_dpp v154, v154, v154 quad_perm:[2,3,0,1] row_mask:0xf bank_mask:0xf bound_ctrl:1
	v_pk_fma_f32 v[142:143], v[240:241], v[212:213], v[142:143] op_sel:[1,0,0] op_sel_hi:[1,1,1]
	v_pk_fma_f32 v[144:145], v[240:241], v[220:221], v[144:145] op_sel:[1,0,0] op_sel_hi:[1,1,1]
	v_add_f32_dpp v154, v154, v154 row_half_mirror row_mask:0xf bank_mask:0xf bound_ctrl:1
	ds_read_b128 v[190:193], v184 offset:15360
	ds_read_b128 v[194:197], v184 offset:15376
	v_add_f32_dpp v154, v154, v154 row_mirror row_mask:0xf bank_mask:0xf bound_ctrl:1
	ds_read_b64 v[228:229], v184 offset:15392
	ds_read_b128 v[198:201], v185 offset:15360
	v_pk_fma_f32 v[142:143], v[154:155], v[210:211], v[142:143] op_sel_hi:[0,1,1]
	v_pk_fma_f32 v[144:145], v[154:155], v[218:219], v[144:145] op_sel_hi:[0,1,1]
	ds_read_b128 v[202:205], v185 offset:15376
	ds_read_b64 v[230:231], v185 offset:15392
	ds_read_b32 v240, v186 offset:3392
	s_waitcnt lgkmcnt(7)
; __device__ __forceinline__ void wkv_phase(const WkvT& W, unsigned char* lds) {
;     ...
;                 for (int t = 0; t < 32; ++t) {
;                     const f32x2 a2 = {nA[0], nA[1]}, w2 = {nA[2], nA[3]}, b2 = {nB[0], nB[1]}, k2 = {nB[2], nB[3]}, r2 = nr; const float v = nv;
;                     if (t + 1 < 32) { nA = *(const f32x4*)(pp + (t + 1) * 384); nB = *(const f32x4*)(pp + (t + 1) * 384 + 4); nr = *(const f32x2*)(pp + (t + 1) * 384 + 8); nv = pv[(t + 1) * 16]; }
;                     float S0 = S.x, S1 = S.y;
;                     float d = S0 * a2.x; d = __builtin_fmaf(S1, a2.y, d);
;                     float t0 = S0 * w2.x; t0 = __builtin_fmaf(v, k2.x, t0); asm volatile("" : "+v"(t0));
;                     float t1 = S1 * w2.y; t1 = __builtin_fmaf(v, k2.y, t1); asm volatile("" : "+v"(t1));
;                     float yprev; const float sa = wkv_reduce(d, ep, yprev);
;                     S0 = __builtin_fmaf(sa, b2.x, t0); asm volatile("" : "+v"(S0));
;                     S1 = __builtin_fmaf(sa, b2.y, t1); asm volatile("" : "+v"(S1));
;                     ep = S0 * r2.x; ep = __builtin_fmaf(S1, r2.y, ep);
;                     S.x = S0; S.y = S1;
;                     if (t >= 1) { const bool hit = oddrow && ((lane & 15) == ((t - 1) & 15)); if (t <= 16) yk0 = hit ? yprev : yk0; else yk1 = hit ? yprev : yk1; }
;                 }
	v_pk_mul_f32 v[150:151], v[142:143], v[126:127]
	v_pk_fma_f32 v[150:151], v[144:145], v[134:135], v[150:151]
	v_pk_mul_f32 v[152:153], v[142:143], v[232:233]
	v_add_f32_e32 v154, v150, v151
	v_pk_fma_f32 v[152:153], v[144:145], v[234:235], v[152:153]
	v_pk_mul_f32 v[146:147], v[142:143], v[128:129]
	v_add_f32_dpp v154, v154, v154 quad_perm:[1,0,3,2] row_mask:0xf bank_mask:0xf bound_ctrl:1
	v_pk_mul_f32 v[148:149], v[144:145], v[136:137]
	v_add_f32_e32 v159, v152, v153
	v_add_f32_dpp v154, v154, v154 quad_perm:[2,3,0,1] row_mask:0xf bank_mask:0xf bound_ctrl:1
	v_pk_fma_f32 v[146:147], v[242:243], v[132:133], v[146:147] op_sel:[0,0,0] op_sel_hi:[0,1,1]
	v_pk_fma_f32 v[148:149], v[242:243], v[224:225], v[148:149] op_sel:[0,0,0] op_sel_hi:[0,1,1]
	v_add_f32_dpp v154, v154, v154 row_half_mirror row_mask:0xf bank_mask:0xf bound_ctrl:1
	ds_read_b128 v[206:209], v184 offset:16896
	ds_read_b128 v[210:213], v184 offset:16912
	v_add_f32_dpp v154, v154, v154 row_mirror row_mask:0xf bank_mask:0xf bound_ctrl:1
	ds_read_b64 v[232:233], v184 offset:16928
	ds_read_b128 v[214:217], v185 offset:16896
	v_pk_fma_f32 v[146:147], v[154:155], v[130:131], v[146:147] op_sel_hi:[0,1,1]
	v_pk_fma_f32 v[148:149], v[154:155], v[222:223], v[148:149] op_sel_hi:[0,1,1]
	ds_read_b128 v[218:221], v185 offset:16912
	ds_read_b64 v[234:235], v185 offset:16928
	ds_read_b32 v241, v186 offset:3456
	s_waitcnt lgkmcnt(7)
	v_pk_mul_f32 v[150:151], v[146:147], v[190:191]
	v_pk_fma_f32 v[150:151], v[148:149], v[198:199], v[150:151]
	v_pk_mul_f32 v[152:153], v[146:147], v[236:237]
	v_add_f32_e32 v154, v150, v151
	v_pk_fma_f32 v[152:153], v[148:149], v[238:239], v[152:153]
	v_pk_mul_f32 v[142:143], v[146:147], v[192:193]
	v_add_f32_dpp v154, v154, v154 quad_perm:[1,0,3,2] row_mask:0xf bank_mask:0xf bound_ctrl:1
	v_pk_mul_f32 v[144:145], v[148:149], v[200:201]
	v_add_f32_e32 v160, v152, v153
	v_add_f32_dpp v154, v154, v154 quad_perm:[2,3,0,1] row_mask:0xf bank_mask:0xf bound_ctrl:1
	v_pk_fma_f32 v[142:143], v[240:241], v[196:197], v[142:143] op_sel:[0,0,0] op_sel_hi:[0,1,1]
	v_pk_fma_f32 v[144:145], v[240:241], v[204:205], v[144:145] op_sel:[0,0,0] op_sel_hi:[0,1,1]
	v_add_f32_dpp v154, v154, v154 row_half_mirror row_mask:0xf bank_mask:0xf bound_ctrl:1
	ds_read_b128 v[126:129], v184 offset:18432
	ds_read_b128 v[130:133], v184 offset:18448
	v_add_f32_dpp v154, v154, v154 row_mirror row_mask:0xf bank_mask:0xf bound_ctrl:1
	ds_read_b64 v[236:237], v184 offset:18464
	ds_read_b128 v[134:137], v185 offset:18432
	v_pk_fma_f32 v[142:143], v[154:155], v[194:195], v[142:143] op_sel_hi:[0,1,1]
	v_pk_fma_f32 v[144:145], v[154:155], v[202:203], v[144:145] op_sel_hi:[0,1,1]
	ds_read_b128 v[222:225], v185 offset:18448
	ds_read_b64 v[238:239], v185 offset:18464
	ds_read_b32 v242, v186 offset:3520
	s_waitcnt lgkmcnt(7)
	v_pk_mul_f32 v[150:151], v[142:143], v[206:207]
	v_pk_fma_f32 v[150:151], v[144:145], v[214:215], v[150:151]
	v_pk_mul_f32 v[152:153], v[142:143], v[228:229]
	v_add_f32_e32 v154, v150, v151
	v_pk_fma_f32 v[152:153], v[144:145], v[230:231], v[152:153]
	v_pk_mul_f32 v[146:147], v[142:143], v[208:209]
	v_add_f32_dpp v154, v154, v154 quad_perm:[1,0,3,2] row_mask:0xf bank_mask:0xf bound_ctrl:1
	v_pk_mul_f32 v[148:149], v[144:145], v[216:217]
	v_add_f32_e32 v161, v152, v153
	v_add_f32_dpp v154, v154, v154 quad_perm:[2,3,0,1] row_mask:0xf bank_mask:0xf bound_ctrl:1
	v_pk_fma_f32 v[146:147], v[240:241], v[212:213], v[146:147] op_sel:[1,0,0] op_sel_hi:[1,1,1]
	v_pk_fma_f32 v[148:149], v[240:241], v[220:221], v[148:149] op_sel:[1,0,0] op_sel_hi:[1,1,1]
	v_add_f32_dpp v154, v154, v154 row_half_mirror row_mask:0xf bank_mask:0xf bound_ctrl:1
	ds_read_b128 v[190:193], v184 offset:19968
	ds_read_b128 v[194:197], v184 offset:19984
	v_add_f32_dpp v154, v154, v154 row_mirror row_mask:0xf bank_mask:0xf bound_ctrl:1
	ds_read_b64 v[228:229], v184 offset:20000
	ds_read_b128 v[198:201], v185 offset:19968
	v_pk_fma_f32 v[146:147], v[154:155], v[210:211], v[146:147] op_sel_hi:[0,1,1]
	v_pk_fma_f32 v[148:149], v[154:155], v[218:219], v[148:149] op_sel_hi:[0,1,1]
	ds_read_b128 v[202:205], v185 offset:19984
	ds_read_b64 v[230:231], v185 offset:20000
	ds_read_b32 v240, v186 offset:3584
	s_waitcnt lgkmcnt(7)
	v_pk_mul_f32 v[150:151], v[146:147], v[126:127]
	v_pk_fma_f32 v[150:151], v[148:149], v[134:135], v[150:151]
	v_pk_mul_f32 v[152:153], v[146:147], v[232:233]
	v_add_f32_e32 v154, v150, v151
	v_pk_fma_f32 v[152:153], v[148:149], v[234:235], v[152:153]
	v_pk_mul_f32 v[142:143], v[146:147], v[128:129]
	v_add_f32_dpp v154, v154, v154 quad_perm:[1,0,3,2] row_mask:0xf bank_mask:0xf bound_ctrl:1
	v_pk_mul_f32 v[144:145], v[148:149], v[136:137]
	v_add_f32_e32 v162, v152, v153
	v_add_f32_dpp v154, v154, v154 quad_perm:[2,3,0,1] row_mask:0xf bank_mask:0xf bound_ctrl:1
	v_pk_fma_f32 v[142:143], v[242:243], v[132:133], v[142:143] op_sel:[0,0,0] op_sel_hi:[0,1,1]
	v_pk_fma_f32 v[144:145], v[242:243], v[224:225], v[144:145] op_sel:[0,0,0] op_sel_hi:[0,1,1]
	v_add_f32_dpp v154, v154, v154 row_half_mirror row_mask:0xf bank_mask:0xf bound_ctrl:1
	ds_read_b128 v[206:209], v184 offset:21504
	ds_read_b128 v[210:213], v184 offset:21520
	v_add_f32_dpp v154, v154, v154 row_mirror row_mask:0xf bank_mask:0xf bound_ctrl:1
	ds_read_b64 v[232:233], v184 offset:21536
	ds_read_b128 v[214:217], v185 offset:21504
	v_pk_fma_f32 v[142:143], v[154:155], v[130:131], v[142:143] op_sel_hi:[0,1,1]
	v_pk_fma_f32 v[144:145], v[154:155], v[222:223], v[144:145] op_sel_hi:[0,1,1]
	ds_read_b128 v[218:221], v185 offset:21520
	ds_read_b64 v[234:235], v185 offset:21536
	ds_read_b32 v241, v186 offset:3648
	s_waitcnt lgkmcnt(7)
; __device__ __forceinline__ void wkv_phase(const WkvT& W, unsigned char* lds) {
;     ...
;                 for (int t = 0; t < 32; ++t) {
;                     const f32x2 a2 = {nA[0], nA[1]}, w2 = {nA[2], nA[3]}, b2 = {nB[0], nB[1]}, k2 = {nB[2], nB[3]}, r2 = nr; const float v = nv;
;                     if (t + 1 < 32) { nA = *(const f32x4*)(pp + (t + 1) * 384); nB = *(const f32x4*)(pp + (t + 1) * 384 + 4); nr = *(const f32x2*)(pp + (t + 1) * 384 + 8); nv = pv[(t + 1) * 16]; }
;                     float S0 = S.x, S1 = S.y;
;                     float d = S0 * a2.x; d = __builtin_fmaf(S1, a2.y, d);
;                     float t0 = S0 * w2.x; t0 = __builtin_fmaf(v, k2.x, t0); asm volatile("" : "+v"(t0));
;                     float t1 = S1 * w2.y; t1 = __builtin_fmaf(v, k2.y, t1); asm volatile("" : "+v"(t1));
;                     float yprev; const float sa = wkv_reduce(d, ep, yprev);
;                     S0 = __builtin_fmaf(sa, b2.x, t0); asm volatile("" : "+v"(S0));
;                     S1 = __builtin_fmaf(sa, b2.y, t1); asm volatile("" : "+v"(S1));
;                     ep = S0 * r2.x; ep = __builtin_fmaf(S1, r2.y, ep);
;                     S.x = S0; S.y = S1;
;                     if (t >= 1) { const bool hit = oddrow && ((lane & 15) == ((t - 1) & 15)); if (t <= 16) yk0 = hit ? yprev : yk0; else yk1 = hit ? yprev : yk1; }
;                 }
	v_pk_mul_f32 v[150:151], v[142:143], v[190:191]
	v_pk_fma_f32 v[150:151], v[144:145], v[198:199], v[150:151]
	v_pk_mul_f32 v[152:153], v[142:143], v[236:237]
	v_add_f32_e32 v154, v150, v151
	v_pk_fma_f32 v[152:153], v[144:145], v[238:239], v[152:153]
	v_pk_mul_f32 v[146:147], v[142:143], v[192:193]
	v_add_f32_dpp v154, v154, v154 quad_perm:[1,0,3,2] row_mask:0xf bank_mask:0xf bound_ctrl:1
	v_pk_mul_f32 v[148:149], v[144:145], v[200:201]
	v_add_f32_e32 v163, v152, v153
	v_add_f32_dpp v154, v154, v154 quad_perm:[2,3,0,1] row_mask:0xf bank_mask:0xf bound_ctrl:1
	v_pk_fma_f32 v[146:147], v[240:241], v[196:197], v[146:147] op_sel:[0,0,0] op_sel_hi:[0,1,1]
	v_pk_fma_f32 v[148:149], v[240:241], v[204:205], v[148:149] op_sel:[0,0,0] op_sel_hi:[0,1,1]
	v_add_f32_dpp v154, v154, v154 row_half_mirror row_mask:0xf bank_mask:0xf bound_ctrl:1
	ds_read_b128 v[126:129], v184 offset:23040
	ds_read_b128 v[130:133], v184 offset:23056
	v_add_f32_dpp v154, v154, v154 row_mirror row_mask:0xf bank_mask:0xf bound_ctrl:1
	ds_read_b64 v[236:237], v184 offset:23072
	ds_read_b128 v[134:137], v185 offset:23040
	v_pk_fma_f32 v[146:147], v[154:155], v[194:195], v[146:147] op_sel_hi:[0,1,1]
	v_pk_fma_f32 v[148:149], v[154:155], v[202:203], v[148:149] op_sel_hi:[0,1,1]
	ds_read_b128 v[222:225], v185 offset:23056
	ds_read_b64 v[238:239], v185 offset:23072
	ds_read_b32 v242, v186 offset:3712
	s_waitcnt lgkmcnt(7)
	v_pk_mul_f32 v[150:151], v[146:147], v[206:207]
	v_pk_fma_f32 v[150:151], v[148:149], v[214:215], v[150:151]
	v_pk_mul_f32 v[152:153], v[146:147], v[228:229]
	v_add_f32_e32 v154, v150, v151
	v_pk_fma_f32 v[152:153], v[148:149], v[230:231], v[152:153]
	v_pk_mul_f32 v[142:143], v[146:147], v[208:209]
	v_add_f32_dpp v154, v154, v154 quad_perm:[1,0,3,2] row_mask:0xf bank_mask:0xf bound_ctrl:1
	v_pk_mul_f32 v[144:145], v[148:149], v[216:217]
	v_add_f32_e32 v164, v152, v153
	v_add_f32_dpp v154, v154, v154 quad_perm:[2,3,0,1] row_mask:0xf bank_mask:0xf bound_ctrl:1
	v_pk_fma_f32 v[142:143], v[240:241], v[212:213], v[142:143] op_sel:[1,0,0] op_sel_hi:[1,1,1]
	v_pk_fma_f32 v[144:145], v[240:241], v[220:221], v[144:145] op_sel:[1,0,0] op_sel_hi:[1,1,1]
	v_add_f32_dpp v154, v154, v154 row_half_mirror row_mask:0xf bank_mask:0xf bound_ctrl:1
	ds_read_b128 v[190:193], v184 offset:24576
	ds_read_b128 v[194:197], v184 offset:24592
	v_add_f32_dpp v154, v154, v154 row_mirror row_mask:0xf bank_mask:0xf bound_ctrl:1
	ds_read_b64 v[228:229], v184 offset:24608
	ds_read_b128 v[198:201], v185 offset:24576
	v_pk_fma_f32 v[142:143], v[154:155], v[210:211], v[142:143] op_sel_hi:[0,1,1]
	v_pk_fma_f32 v[144:145], v[154:155], v[218:219], v[144:145] op_sel_hi:[0,1,1]
	ds_read_b128 v[202:205], v185 offset:24592
	ds_read_b64 v[230:231], v185 offset:24608
	ds_read_b32 v240, v186 offset:3776
	s_waitcnt lgkmcnt(7)
	v_pk_mul_f32 v[150:151], v[142:143], v[126:127]
	v_pk_fma_f32 v[150:151], v[144:145], v[134:135], v[150:151]
	v_pk_mul_f32 v[152:153], v[142:143], v[232:233]
	v_add_f32_e32 v154, v150, v151
	v_pk_fma_f32 v[152:153], v[144:145], v[234:235], v[152:153]
	v_pk_mul_f32 v[146:147], v[142:143], v[128:129]
	v_add_f32_dpp v154, v154, v154 quad_perm:[1,0,3,2] row_mask:0xf bank_mask:0xf bound_ctrl:1
	v_pk_mul_f32 v[148:149], v[144:145], v[136:137]
	v_add_f32_e32 v165, v152, v153
	v_add_f32_dpp v154, v154, v154 quad_perm:[2,3,0,1] row_mask:0xf bank_mask:0xf bound_ctrl:1
	v_pk_fma_f32 v[146:147], v[242:243], v[132:133], v[146:147] op_sel:[0,0,0] op_sel_hi:[0,1,1]
	v_pk_fma_f32 v[148:149], v[242:243], v[224:225], v[148:149] op_sel:[0,0,0] op_sel_hi:[0,1,1]
	v_add_f32_dpp v154, v154, v154 row_half_mirror row_mask:0xf bank_mask:0xf bound_ctrl:1
	ds_read_b128 v[206:209], v184 offset:26112
	ds_read_b128 v[210:213], v184 offset:26128
	v_add_f32_dpp v154, v154, v154 row_mirror row_mask:0xf bank_mask:0xf bound_ctrl:1
	ds_read_b64 v[232:233], v184 offset:26144
	ds_read_b128 v[214:217], v185 offset:26112
	v_pk_fma_f32 v[146:147], v[154:155], v[130:131], v[146:147] op_sel_hi:[0,1,1]
	v_pk_fma_f32 v[148:149], v[154:155], v[222:223], v[148:149] op_sel_hi:[0,1,1]
	ds_read_b128 v[218:221], v185 offset:26128
	ds_read_b64 v[234:235], v185 offset:26144
	ds_read_b32 v241, v186 offset:3840
	s_waitcnt lgkmcnt(7)
	v_pk_mul_f32 v[150:151], v[146:147], v[190:191]
	v_pk_fma_f32 v[150:151], v[148:149], v[198:199], v[150:151]
	v_pk_mul_f32 v[152:153], v[146:147], v[236:237]
	v_add_f32_e32 v154, v150, v151
	v_pk_fma_f32 v[152:153], v[148:149], v[238:239], v[152:153]
	v_pk_mul_f32 v[142:143], v[146:147], v[192:193]
	v_add_f32_dpp v154, v154, v154 quad_perm:[1,0,3,2] row_mask:0xf bank_mask:0xf bound_ctrl:1
	v_pk_mul_f32 v[144:145], v[148:149], v[200:201]
	v_add_f32_e32 v166, v152, v153
	v_add_f32_dpp v154, v154, v154 quad_perm:[2,3,0,1] row_mask:0xf bank_mask:0xf bound_ctrl:1
	v_pk_fma_f32 v[142:143], v[240:241], v[196:197], v[142:143] op_sel:[0,0,0] op_sel_hi:[0,1,1]
	v_pk_fma_f32 v[144:145], v[240:241], v[204:205], v[144:145] op_sel:[0,0,0] op_sel_hi:[0,1,1]
	v_add_f32_dpp v154, v154, v154 row_half_mirror row_mask:0xf bank_mask:0xf bound_ctrl:1
	ds_read_b128 v[126:129], v184 offset:27648
	ds_read_b128 v[130:133], v184 offset:27664
	v_add_f32_dpp v154, v154, v154 row_mirror row_mask:0xf bank_mask:0xf bound_ctrl:1
	ds_read_b64 v[236:237], v184 offset:27680
	ds_read_b128 v[134:137], v185 offset:27648
	v_pk_fma_f32 v[142:143], v[154:155], v[194:195], v[142:143] op_sel_hi:[0,1,1]
	v_pk_fma_f32 v[144:145], v[154:155], v[202:203], v[144:145] op_sel_hi:[0,1,1]
	ds_read_b128 v[222:225], v185 offset:27664
	ds_read_b64 v[238:239], v185 offset:27680
	ds_read_b32 v242, v186 offset:3904
	s_waitcnt lgkmcnt(7)
; __device__ __forceinline__ void wkv_phase(const WkvT& W, unsigned char* lds) {
;     ...
;                 for (int t = 0; t < 32; ++t) {
;                     const f32x2 a2 = {nA[0], nA[1]}, w2 = {nA[2], nA[3]}, b2 = {nB[0], nB[1]}, k2 = {nB[2], nB[3]}, r2 = nr; const float v = nv;
;                     if (t + 1 < 32) { nA = *(const f32x4*)(pp + (t + 1) * 384); nB = *(const f32x4*)(pp + (t + 1) * 384 + 4); nr = *(const f32x2*)(pp + (t + 1) * 384 + 8); nv = pv[(t + 1) * 16]; }
;                     float S0 = S.x, S1 = S.y;
;                     float d = S0 * a2.x; d = __builtin_fmaf(S1, a2.y, d);
;                     float t0 = S0 * w2.x; t0 = __builtin_fmaf(v, k2.x, t0); asm volatile("" : "+v"(t0));
;                     float t1 = S1 * w2.y; t1 = __builtin_fmaf(v, k2.y, t1); asm volatile("" : "+v"(t1));
;                     float yprev; const float sa = wkv_reduce(d, ep, yprev);
;                     S0 = __builtin_fmaf(sa, b2.x, t0); asm volatile("" : "+v"(S0));
;                     S1 = __builtin_fmaf(sa, b2.y, t1); asm volatile("" : "+v"(S1));
;                     ep = S0 * r2.x; ep = __builtin_fmaf(S1, r2.y, ep);
;                     S.x = S0; S.y = S1;
;                     if (t >= 1) { const bool hit = oddrow && ((lane & 15) == ((t - 1) & 15)); if (t <= 16) yk0 = hit ? yprev : yk0; else yk1 = hit ? yprev : yk1; }
;                 }
	v_pk_mul_f32 v[150:151], v[142:143], v[206:207]
	v_pk_fma_f32 v[150:151], v[144:145], v[214:215], v[150:151]
	v_pk_mul_f32 v[152:153], v[142:143], v[228:229]
	v_add_f32_e32 v154, v150, v151
	v_pk_fma_f32 v[152:153], v[144:145], v[230:231], v[152:153]
	v_pk_mul_f32 v[146:147], v[142:143], v[208:209]
	v_add_f32_dpp v154, v154, v154 quad_perm:[1,0,3,2] row_mask:0xf bank_mask:0xf bound_ctrl:1
	v_pk_mul_f32 v[148:149], v[144:145], v[216:217]
	v_add_f32_e32 v167, v152, v153
	v_add_f32_dpp v154, v154, v154 quad_perm:[2,3,0,1] row_mask:0xf bank_mask:0xf bound_ctrl:1
	v_pk_fma_f32 v[146:147], v[240:241], v[212:213], v[146:147] op_sel:[1,0,0] op_sel_hi:[1,1,1]
	v_pk_fma_f32 v[148:149], v[240:241], v[220:221], v[148:149] op_sel:[1,0,0] op_sel_hi:[1,1,1]
	v_add_f32_dpp v154, v154, v154 row_half_mirror row_mask:0xf bank_mask:0xf bound_ctrl:1
	ds_read_b128 v[190:193], v184 offset:29184
	ds_read_b128 v[194:197], v184 offset:29200
	v_add_f32_dpp v154, v154, v154 row_mirror row_mask:0xf bank_mask:0xf bound_ctrl:1
	ds_read_b64 v[228:229], v184 offset:29216
	ds_read_b128 v[198:201], v185 offset:29184
	v_pk_fma_f32 v[146:147], v[154:155], v[210:211], v[146:147] op_sel_hi:[0,1,1]
	v_pk_fma_f32 v[148:149], v[154:155], v[218:219], v[148:149] op_sel_hi:[0,1,1]
	ds_read_b128 v[202:205], v185 offset:29200
	ds_read_b64 v[230:231], v185 offset:29216
	ds_read_b32 v240, v186 offset:3968
	s_waitcnt lgkmcnt(7)
	v_pk_mul_f32 v[150:151], v[146:147], v[126:127]
	v_pk_fma_f32 v[150:151], v[148:149], v[134:135], v[150:151]
	v_pk_mul_f32 v[152:153], v[146:147], v[232:233]
	v_add_f32_e32 v154, v150, v151
	v_pk_fma_f32 v[152:153], v[148:149], v[234:235], v[152:153]
	v_pk_mul_f32 v[142:143], v[146:147], v[128:129]
	v_add_f32_dpp v154, v154, v154 quad_perm:[1,0,3,2] row_mask:0xf bank_mask:0xf bound_ctrl:1
	v_pk_mul_f32 v[144:145], v[148:149], v[136:137]
	v_add_f32_e32 v168, v152, v153
	v_add_f32_dpp v154, v154, v154 quad_perm:[2,3,0,1] row_mask:0xf bank_mask:0xf bound_ctrl:1
	v_pk_fma_f32 v[142:143], v[242:243], v[132:133], v[142:143] op_sel:[0,0,0] op_sel_hi:[0,1,1]
	v_pk_fma_f32 v[144:145], v[242:243], v[224:225], v[144:145] op_sel:[0,0,0] op_sel_hi:[0,1,1]
	v_add_f32_dpp v154, v154, v154 row_half_mirror row_mask:0xf bank_mask:0xf bound_ctrl:1
	ds_read_b128 v[206:209], v184 offset:30720
	ds_read_b128 v[210:213], v184 offset:30736
	v_add_f32_dpp v154, v154, v154 row_mirror row_mask:0xf bank_mask:0xf bound_ctrl:1
	ds_read_b64 v[232:233], v184 offset:30752
	ds_read_b128 v[214:217], v185 offset:30720
	v_pk_fma_f32 v[142:143], v[154:155], v[130:131], v[142:143] op_sel_hi:[0,1,1]
	v_pk_fma_f32 v[144:145], v[154:155], v[222:223], v[144:145] op_sel_hi:[0,1,1]
	ds_read_b128 v[218:221], v185 offset:30736
	ds_read_b64 v[234:235], v185 offset:30752
	ds_read_b32 v241, v186 offset:4032
	s_waitcnt lgkmcnt(7)
	v_pk_mul_f32 v[150:151], v[142:143], v[190:191]
	v_pk_fma_f32 v[150:151], v[144:145], v[198:199], v[150:151]
	v_pk_mul_f32 v[152:153], v[142:143], v[236:237]
	v_add_f32_e32 v154, v150, v151
	v_pk_fma_f32 v[152:153], v[144:145], v[238:239], v[152:153]
	v_pk_mul_f32 v[146:147], v[142:143], v[192:193]
	v_add_f32_dpp v154, v154, v154 quad_perm:[1,0,3,2] row_mask:0xf bank_mask:0xf bound_ctrl:1
	v_pk_mul_f32 v[148:149], v[144:145], v[200:201]
	v_add_f32_e32 v169, v152, v153
	v_add_f32_dpp v154, v154, v154 quad_perm:[2,3,0,1] row_mask:0xf bank_mask:0xf bound_ctrl:1
	v_pk_fma_f32 v[146:147], v[240:241], v[196:197], v[146:147] op_sel:[0,0,0] op_sel_hi:[0,1,1]
	v_pk_fma_f32 v[148:149], v[240:241], v[204:205], v[148:149] op_sel:[0,0,0] op_sel_hi:[0,1,1]
	v_add_f32_dpp v154, v154, v154 row_half_mirror row_mask:0xf bank_mask:0xf bound_ctrl:1
	s_nop 1
	v_add_f32_dpp v154, v154, v154 row_mirror row_mask:0xf bank_mask:0xf bound_ctrl:1
	v_pk_fma_f32 v[146:147], v[154:155], v[194:195], v[146:147] op_sel_hi:[0,1,1]
	v_pk_fma_f32 v[148:149], v[154:155], v[202:203], v[148:149] op_sel_hi:[0,1,1]
	s_waitcnt lgkmcnt(0)
; __device__ __forceinline__ void wkv_phase(const WkvT& W, unsigned char* lds) {
;     ...
;                 for (int t = 0; t < 32; ++t) {
;                     const f32x2 a2 = {nA[0], nA[1]}, w2 = {nA[2], nA[3]}, b2 = {nB[0], nB[1]}, k2 = {nB[2], nB[3]}, r2 = nr; const float v = nv;
;                     if (t + 1 < 32) { nA = *(const f32x4*)(pp + (t + 1) * 384); nB = *(const f32x4*)(pp + (t + 1) * 384 + 4); nr = *(const f32x2*)(pp + (t + 1) * 384 + 8); nv = pv[(t + 1) * 16]; }
;                     float S0 = S.x, S1 = S.y;
;                     float d = S0 * a2.x; d = __builtin_fmaf(S1, a2.y, d);
;                     float t0 = S0 * w2.x; t0 = __builtin_fmaf(v, k2.x, t0); asm volatile("" : "+v"(t0));
;                     float t1 = S1 * w2.y; t1 = __builtin_fmaf(v, k2.y, t1); asm volatile("" : "+v"(t1));
;                     float yprev; const float sa = wkv_reduce(d, ep, yprev);
;                     S0 = __builtin_fmaf(sa, b2.x, t0); asm volatile("" : "+v"(S0));
;                     S1 = __builtin_fmaf(sa, b2.y, t1); asm volatile("" : "+v"(S1));
;                     ep = S0 * r2.x; ep = __builtin_fmaf(S1, r2.y, ep);
;                     S.x = S0; S.y = S1;
;                     if (t >= 1) { const bool hit = oddrow && ((lane & 15) == ((t - 1) & 15)); if (t <= 16) yk0 = hit ? yprev : yk0; else yk1 = hit ? yprev : yk1; }
;                 }
;                 { float ylast; (void)wkv_reduce(0.f, ep, ylast); yk1 = (oddrow && (lane & 15) == 15) ? ylast : yk1; }
;                 if (oddrow) { sY[bi * 512 + (lane & 15) * 16 + il] = yk0; sY[bi * 512 + (16 + (lane & 15)) * 16 + il] = yk1; }
	v_pk_mul_f32 v[150:151], v[146:147], v[206:207]
	v_pk_fma_f32 v[150:151], v[148:149], v[214:215], v[150:151]
	v_pk_mul_f32 v[152:153], v[146:147], v[228:229]
	v_add_f32_e32 v154, v150, v151
	v_pk_fma_f32 v[152:153], v[148:149], v[230:231], v[152:153]
	v_pk_mul_f32 v[142:143], v[146:147], v[208:209]
	v_add_f32_dpp v154, v154, v154 quad_perm:[1,0,3,2] row_mask:0xf bank_mask:0xf bound_ctrl:1
	v_pk_mul_f32 v[144:145], v[148:149], v[216:217]
	v_add_f32_e32 v170, v152, v153
	v_add_f32_dpp v154, v154, v154 quad_perm:[2,3,0,1] row_mask:0xf bank_mask:0xf bound_ctrl:1
	v_pk_fma_f32 v[142:143], v[240:241], v[212:213], v[142:143] op_sel:[1,0,0] op_sel_hi:[1,1,1]
	v_pk_fma_f32 v[144:145], v[240:241], v[220:221], v[144:145] op_sel:[1,0,0] op_sel_hi:[1,1,1]
	v_add_f32_dpp v154, v154, v154 row_half_mirror row_mask:0xf bank_mask:0xf bound_ctrl:1
	s_nop 1
	v_add_f32_dpp v154, v154, v154 row_mirror row_mask:0xf bank_mask:0xf bound_ctrl:1
	v_pk_fma_f32 v[142:143], v[154:155], v[210:211], v[142:143] op_sel_hi:[0,1,1]
	v_pk_fma_f32 v[144:145], v[154:155], v[218:219], v[144:145] op_sel_hi:[0,1,1]
	v_pk_mul_f32 v[152:153], v[142:143], v[232:233]
	v_pk_fma_f32 v[152:153], v[144:145], v[234:235], v[152:153]
	s_nop 0
	v_add_f32_e32 v171, v152, v153
	v_cndmask_b32_e64 v172, v164, v156, s[10:11]
	v_cndmask_b32_e64 v174, v165, v157, s[10:11]
	v_cndmask_b32_e64 v176, v166, v158, s[10:11]
	v_cndmask_b32_e64 v178, v167, v159, s[10:11]
	v_cndmask_b32_e64 v173, v156, v164, s[10:11]
	v_cndmask_b32_e64 v175, v157, v165, s[10:11]
	v_cndmask_b32_e64 v177, v158, v166, s[10:11]
	v_cndmask_b32_e64 v179, v159, v167, s[10:11]
	v_add_f32_dpp v156, v172, v173 row_ror:8 row_mask:0xf bank_mask:0xf
	v_add_f32_dpp v157, v174, v175 row_ror:8 row_mask:0xf bank_mask:0xf
	v_add_f32_dpp v158, v176, v177 row_ror:8 row_mask:0xf bank_mask:0xf
	v_add_f32_dpp v159, v178, v179 row_ror:8 row_mask:0xf bank_mask:0xf
	v_cndmask_b32_e64 v172, v168, v160, s[10:11]
	v_cndmask_b32_e64 v174, v169, v161, s[10:11]
	v_cndmask_b32_e64 v176, v170, v162, s[10:11]
	v_cndmask_b32_e64 v178, v171, v163, s[10:11]
	v_cndmask_b32_e64 v173, v160, v168, s[10:11]
	v_cndmask_b32_e64 v175, v161, v169, s[10:11]
	v_cndmask_b32_e64 v177, v162, v170, s[10:11]
	v_cndmask_b32_e64 v179, v163, v171, s[10:11]
	v_add_f32_dpp v160, v172, v173 row_ror:8 row_mask:0xf bank_mask:0xf
	v_add_f32_dpp v161, v174, v175 row_ror:8 row_mask:0xf bank_mask:0xf
	v_add_f32_dpp v162, v176, v177 row_ror:8 row_mask:0xf bank_mask:0xf
	v_add_f32_dpp v163, v178, v179 row_ror:8 row_mask:0xf bank_mask:0xf
	v_cndmask_b32_e64 v172, v160, v156, s[12:13]
	v_cndmask_b32_e64 v174, v161, v157, s[12:13]
	v_cndmask_b32_e64 v176, v162, v158, s[12:13]
	v_cndmask_b32_e64 v178, v163, v159, s[12:13]
	v_cndmask_b32_e64 v173, v156, v160, s[12:13]
	v_cndmask_b32_e64 v175, v157, v161, s[12:13]
	v_cndmask_b32_e64 v177, v158, v162, s[12:13]
	v_cndmask_b32_e64 v179, v159, v163, s[12:13]
	v_add_f32_dpp v156, v172, v173 row_half_mirror row_mask:0xf bank_mask:0xf
	v_add_f32_dpp v157, v174, v175 row_half_mirror row_mask:0xf bank_mask:0xf
	v_add_f32_dpp v158, v176, v177 row_half_mirror row_mask:0xf bank_mask:0xf
	v_add_f32_dpp v159, v178, v179 row_half_mirror row_mask:0xf bank_mask:0xf
	v_cndmask_b32_e64 v172, v158, v156, s[14:15]
	v_cndmask_b32_e64 v174, v159, v157, s[14:15]
	v_cndmask_b32_e64 v173, v156, v158, s[14:15]
	v_cndmask_b32_e64 v175, v157, v159, s[14:15]
	v_add_f32_dpp v156, v172, v173 quad_perm:[2,3,0,1] row_mask:0xf bank_mask:0xf
	v_add_f32_dpp v157, v174, v175 quad_perm:[2,3,0,1] row_mask:0xf bank_mask:0xf
	v_cndmask_b32_e64 v172, v157, v156, s[16:17]
	v_cndmask_b32_e64 v173, v156, v157, s[16:17]
	s_nop 0
	v_add_f32_dpp v156, v172, v173 quad_perm:[1,0,3,2] row_mask:0xf bank_mask:0xf
	v_mov_b32_e32 v181, v156
	ds_write2st64_b32 v187, v180, v181 offset0:8 offset1:12
.Lwkv4_b2_skip:
	s_mov_b64 s[96:97], exec
	s_bitcmp0_b32 s99, 8
	s_cbranch_scc1 .LBB0_1644

; __device__ __forceinline__ float bflo(unsigned w) { return __uint_as_float(w << 16); }
; __device__ __forceinline__ float bfhi(unsigned w) { return __uint_as_float(w & 0xffff0000u); }
; __device__ __forceinline__ float row16_sum(float x) { x += dpp_f(x, 0); x += dpp_f(x, 1); x += dpp_f(x, 2); x += dpp_f(x, 3); return x; }
; __device__ __forceinline__ void wkv_stage(const WkvT& W, const WkvRaw& raw, size_t rowbase, int h, int q, int c, int tid, const float (&kkc)[4], const float (&kac)[4], const float (&rkc)[4],
;                                           float* sP, float* sV) {
;     const float r[4] = {bflo(raw.r[0]), bfhi(raw.r[0]), bflo(raw.r[1]), bfhi(raw.r[1])}, k[4] = {bflo(raw.k[0]), bfhi(raw.k[0]), bflo(raw.k[1]), bfhi(raw.k[1])};
;     const float a[4] = {bflo(raw.a[0]), bfhi(raw.a[0]), bflo(raw.a[1]), bfhi(raw.a[1])}, l[4] = {bflo(raw.l[0]), bfhi(raw.l[0]), bflo(raw.l[1]), bfhi(raw.l[1])};
;     float kkr[4], km[4], n2 = 0.f, bs = 0.f;
; #pragma unroll
;     for (int e = 0; e < 4; ++e) { kkr[e] = k[e] * kkc[e]; n2 += kkr[e] * kkr[e]; km[e] = k[e] * (1.f + (a[e] - 1.f) * kac[e]); bs += r[e] * km[e] * rkc[e]; }
;     n2 = row16_sum(n2); bs = row16_sum(bs);
;     const float inv = __builtin_amdgcn_rcpf(fmaxf(sqrtf(n2), 1e-12f));
;     const int t = tid >> 4;
;     float* rec = sP + (t * 32 + 2 * (tid & 15)) * 12;
; #pragma unroll
;     for (int hlf = 0; hlf < 2; ++hlf) { const int e = 2 * hlf; float* rp = rec + hlf * 12;
;         *(f32x4*)(rp) = (f32x4){-kkr[e] * inv, -kkr[e + 1] * inv, __builtin_amdgcn_exp2f(LOG2E_ * l[e]), __builtin_amdgcn_exp2f(LOG2E_ * l[e + 1])};
;         *(f32x4*)(rp + 4) = (f32x4){kkr[e] * inv * a[e], kkr[e + 1] * inv * a[e + 1], km[e], km[e + 1]};
;         *(f32x2*)(rp + 8) = (f32x2){r[e], r[e + 1]}; }
;     if ((tid & 15) < 4) *(f32x4*)(sV + t * 16 + 4 * (tid & 15)) = (f32x4){bflo(raw.v[0]), bfhi(raw.v[0]), bflo(raw.v[1]), bfhi(raw.v[1])};
;     if (q == 0 && (tid & 15) == 0) W.bonus[(rowbase + (size_t)c * 32 + t) * 32 + h] = bs;
; }
.LBB0_1643:
	s_or_b64 exec, exec, s[46:47]
	v_add_u32_e32 v208, 0xffffa000, v125
	v_add_u32_e32 v209, 0xfffffc00, v15
	v_subrev_co_u32_e32 v210, vcc, 0x800, v38
	s_nop 1
	v_subbrev_co_u32_e32 v211, vcc, 0, v39, vcc
	s_waitcnt vmcnt(2)
	v_lshlrev_b32_e32 v130, 16, v200
	v_and_b32_e32 v131, 0xffff0000, v200
	v_and_b32_e32 v207, 0xffff0000, v201
	v_lshlrev_b32_e32 v206, 16, v201
	v_pk_mul_f32 v[200:201], v[6:7], v[130:131]
	v_pk_mul_f32 v[126:127], v[8:9], v[206:207]
	v_pk_mul_f32 v[132:133], v[200:201], v[200:201]
	v_pk_mul_f32 v[128:129], v[126:127], v[126:127]
	v_add_f32_e32 v16, v132, v133
	v_add_f32_e32 v16, v128, v16
	v_add_f32_e32 v16, v129, v16
	v_lshlrev_b32_e32 v202, 16, v198
	v_and_b32_e32 v203, 0xffff0000, v198
	v_add_f32_dpp v16, v16, v16 quad_perm:[1,0,3,2] row_mask:0xf bank_mask:0xf bound_ctrl:1
	v_lshlrev_b32_e32 v204, 16, v199
	v_and_b32_e32 v205, 0xffff0000, v199
	v_add_f32_dpp v16, v16, v16 quad_perm:[2,3,0,1] row_mask:0xf bank_mask:0xf bound_ctrl:1
	s_waitcnt vmcnt(0)
	v_lshlrev_b32_e32 v199, 16, v196
	v_and_b32_e32 v196, 0xffff0000, v196
	v_add_f32_dpp v16, v16, v16 row_half_mirror row_mask:0xf bank_mask:0xf bound_ctrl:1
	s_nop 1
	v_add_f32_dpp v16, v16, v16 row_mirror row_mask:0xf bank_mask:0xf bound_ctrl:1
	v_mul_f32_e32 v198, 0x4f800000, v16
	v_cmp_gt_f32_e32 vcc, s3, v16
	s_nop 1
	v_cndmask_b32_e32 v16, v16, v198, vcc
	v_sqrt_f32_e32 v198, v16
	s_nop 0
	v_add_u32_e32 v128, -1, v198
	v_fma_f32 v129, -v128, v198, v16
	v_cmp_ge_f32_e64 s[46:47], 0, v129
	v_add_u32_e32 v129, 1, v198
	s_nop 0
	v_cndmask_b32_e64 v128, v198, v128, s[46:47]
	v_fma_f32 v198, -v129, v198, v16
	v_cmp_lt_f32_e64 s[46:47], 0, v198
	s_nop 1
	v_cndmask_b32_e64 v198, v128, v129, s[46:47]
	v_mul_f32_e32 v128, 0x37800000, v198
	v_cndmask_b32_e32 v198, v198, v128, vcc
	v_cmp_class_f32_e32 vcc, v16, v124
	v_and_b32_e32 v129, 0xffff0000, v197
	s_nop 0
	v_cndmask_b32_e32 v16, v198, v16, vcc
	v_max_f32_e32 v16, 0x2b8cbccc, v16
	v_rcp_f32_e32 v128, v16
	v_mul_f32_e32 v16, 0x3fb8aa3b, v199
	v_exp_f32_e32 v198, v16
	v_mul_f32_e32 v16, 0x3fb8aa3b, v196
	v_exp_f32_e32 v199, v16
	v_lshlrev_b32_e32 v16, 16, v197
	v_pk_mul_f32 v[196:197], v[128:129], v[200:201] op_sel_hi:[0,1] neg_lo:[0,1] neg_hi:[0,1]
	v_mul_f32_e32 v16, 0x3fb8aa3b, v16
	ds_write_b128 v208, v[196:199]
	v_lshlrev_b32_e32 v196, 16, v194
	v_and_b32_e32 v197, 0xffff0000, v194
	v_pk_add_f32 v[198:199], v[196:197], -1.0 op_sel_hi:[1,0]
	s_nop 0
	v_pk_fma_f32 v[198:199], v[10:11], v[198:199], 1.0 op_sel_hi:[1,1,0]
	s_nop 0
	v_pk_mul_f32 v[198:199], v[198:199], v[130:131]
	v_pk_mul_f32 v[130:131], v[200:201], v[128:129] op_sel_hi:[1,0]
	v_exp_f32_e32 v200, v16
	v_mul_f32_e32 v16, 0x3fb8aa3b, v129
	v_mul_f32_e32 v194, v198, v202
	v_exp_f32_e32 v201, v16
	v_pk_mul_f32 v[196:197], v[130:131], v[196:197]
	v_fma_f32 v132, v2, v194, 0
	v_mul_f32_e32 v194, v199, v203
	ds_write_b128 v208, v[196:199] offset:16
	v_lshlrev_b32_e32 v196, 16, v195
	v_and_b32_e32 v197, 0xffff0000, v195
	v_fmac_f32_e32 v132, v3, v194
	v_pk_add_f32 v[194:195], v[196:197], -1.0 op_sel_hi:[1,0]
	v_pk_mul_f32 v[198:199], v[128:129], v[126:127] op_sel_hi:[0,1] neg_lo:[0,1] neg_hi:[0,1]
	v_pk_fma_f32 v[194:195], v[12:13], v[194:195], 1.0 op_sel_hi:[1,1,0]
	ds_write_b128 v208, v[198:201] offset:48
	v_pk_mul_f32 v[198:199], v[194:195], v[206:207]
	v_pk_mul_f32 v[200:201], v[126:127], v[128:129] op_sel_hi:[1,0]
	v_mul_f32_e32 v16, v198, v204
	v_mul_f32_e32 v194, v199, v205
	v_fmac_f32_e32 v132, v4, v16
	v_fmac_f32_e32 v132, v5, v194
	v_pk_mul_f32 v[196:197], v[200:201], v[196:197]
	ds_write_b128 v208, v[196:199] offset:64
	ds_write2_b64 v208, v[202:203], v[204:205] offset0:4 offset1:10
	v_add_f32_dpp v16, v132, v132 quad_perm:[1,0,3,2] row_mask:0xf bank_mask:0xf bound_ctrl:1
	s_nop 1
	v_add_f32_dpp v16, v16, v16 quad_perm:[2,3,0,1] row_mask:0xf bank_mask:0xf bound_ctrl:1
	s_nop 1
	v_add_f32_dpp v16, v16, v16 row_half_mirror row_mask:0xf bank_mask:0xf bound_ctrl:1
	s_nop 1
	v_mov_b32_dpp v194, v16 row_mirror row_mask:0xf bank_mask:0xf bound_ctrl:1
	s_and_saveexec_b64 s[46:47], s[0:1]
	v_lshlrev_b32_e32 v196, 16, v212
	v_and_b32_e32 v197, 0xffff0000, v212
	v_lshlrev_b32_e32 v198, 16, v213
	v_and_b32_e32 v199, 0xffff0000, v213
	ds_write_b128 v209, v[196:199]
	s_or_b64 exec, exec, s[46:47]
	s_and_saveexec_b64 s[46:47], s[42:43]
	s_cbranch_execz .Lst2b_1643
	v_add_f32_e32 v16, v16, v194
	v_lshl_add_u64 v[194:195], s[52:53], 0, v[210:211]
	v_add_co_u32_e32 v194, vcc, 0x1e502000, v194
	s_nop 1
	v_addc_co_u32_e32 v195, vcc, 0, v195, vcc
	global_store_dword v[194:195], v16, off

; __device__ __forceinline__ bf16_t f2bf(float f) { return (bf16_t)(pk2(f, 0.f) & 0xffffu); }
; __device__ __forceinline__ float row16_sum(float x) { x += dpp_f(x, 0); x += dpp_f(x, 1); x += dpp_f(x, 2); x += dpp_f(x, 3); return x; }
; __device__ __forceinline__ void wkv_phase(const WkvT& W, unsigned char* lds) {
;     ...
;             {
;                 const int t = tid >> 4, i = tid & 15; const float yv = sY[bi * 512 + t * 16 + i];
;                 const size_t row = rowbase + (size_t)c * 32 + t;
;                 W.Y[row * DM + cbase + q * 16 + i] = f2bf(yv);
;                 const float s1 = row16_sum(yv), s2 = row16_sum(yv * yv);
;                 if (i == 0) *(f32x2*)(W.stats + ((row * 32 + h) * 4 + q) * 2) = (f32x2){s1, s2};
;             }
.LBB0_1644:
	s_waitcnt lgkmcnt(0)
	s_barrier
	s_bitcmp0_b32 s99, 8
	s_cbranch_scc1 .LBB0_1621
	v_add_u32_e32 v220, 0xfffffc00, v60
	v_subrev_co_u32_e32 v226, vcc, 0x10000, v36
	s_nop 1
	v_subbrev_co_u32_e32 v227, vcc, 0, v37, vcc
	v_subrev_co_u32_e32 v224, vcc, 0x4000, v34
	s_nop 1
	v_subbrev_co_u32_e32 v225, vcc, 0, v35, vcc
	s_waitcnt vmcnt(1)
	ds_read_b32 v46, v220 offset:2048
	s_waitcnt vmcnt(0)
	v_lshl_add_u64 v[48:49], s[52:53], 0, v[226:227]
	s_waitcnt lgkmcnt(0)
	v_mul_f32_e32 v47, v46, v46
	v_mov_b32_dpp v50, v46 quad_perm:[1,0,3,2] row_mask:0xf bank_mask:0xf bound_ctrl:1
	s_nop 0
	v_mov_b32_dpp v51, v47 quad_perm:[1,0,3,2] row_mask:0xf bank_mask:0xf bound_ctrl:1
	v_cvt_pk_bf16_f32 v16, v46, s0
	v_pk_add_f32 v[46:47], v[46:47], v[50:51]
	global_store_short v[48:49], v16, off
	s_nop 0
	v_mov_b32_dpp v48, v46 quad_perm:[2,3,0,1] row_mask:0xf bank_mask:0xf bound_ctrl:1
	v_mov_b32_dpp v49, v47 quad_perm:[2,3,0,1] row_mask:0xf bank_mask:0xf bound_ctrl:1
	v_pk_add_f32 v[46:47], v[46:47], v[48:49]
	s_nop 1
	v_mov_b32_dpp v48, v46 row_half_mirror row_mask:0xf bank_mask:0xf bound_ctrl:1
	v_mov_b32_dpp v49, v47 row_half_mirror row_mask:0xf bank_mask:0xf bound_ctrl:1
	v_pk_add_f32 v[46:47], v[46:47], v[48:49]
	s_nop 1
	v_mov_b32_dpp v48, v46 row_mirror row_mask:0xf bank_mask:0xf bound_ctrl:1
	v_mov_b32_dpp v49, v47 row_mirror row_mask:0xf bank_mask:0xf bound_ctrl:1
	s_and_saveexec_b64 s[46:47], s[8:9]
	s_cbranch_execz .Lfl2b_end
	v_pk_add_f32 v[46:47], v[46:47], v[48:49]
	v_lshl_add_u64 v[48:49], s[52:53], 0, v[224:225]
	v_add_co_u32_e32 v48, vcc, 0x1d508000, v48
	s_nop 1
	v_addc_co_u32_e32 v49, vcc, 0, v49, vcc
	global_store_dwordx2 v[48:49], v[46:47], off
.Lfl2b_end:
	s_or_b64 exec, exec, s[46:47]
	s_waitcnt vmcnt(1)
	ds_read_b32 v46, v60 offset:2048
	s_waitcnt vmcnt(0)
	v_lshl_add_u64 v[48:49], s[52:53], 0, v[36:37]
	s_waitcnt lgkmcnt(0)
	v_mul_f32_e32 v47, v46, v46
	v_mov_b32_dpp v50, v46 quad_perm:[1,0,3,2] row_mask:0xf bank_mask:0xf bound_ctrl:1
	s_nop 0
	v_mov_b32_dpp v51, v47 quad_perm:[1,0,3,2] row_mask:0xf bank_mask:0xf bound_ctrl:1
	v_cvt_pk_bf16_f32 v16, v46, s0
	v_pk_add_f32 v[46:47], v[46:47], v[50:51]
	global_store_short v[48:49], v16, off
	s_nop 0
	v_mov_b32_dpp v48, v46 quad_perm:[2,3,0,1] row_mask:0xf bank_mask:0xf bound_ctrl:1
	v_mov_b32_dpp v49, v47 quad_perm:[2,3,0,1] row_mask:0xf bank_mask:0xf bound_ctrl:1
	v_pk_add_f32 v[46:47], v[46:47], v[48:49]
	s_nop 1
	v_mov_b32_dpp v48, v46 row_half_mirror row_mask:0xf bank_mask:0xf bound_ctrl:1
	v_mov_b32_dpp v49, v47 row_half_mirror row_mask:0xf bank_mask:0xf bound_ctrl:1
	v_pk_add_f32 v[46:47], v[46:47], v[48:49]
	s_nop 1
	v_mov_b32_dpp v48, v46 row_mirror row_mask:0xf bank_mask:0xf bound_ctrl:1
	v_mov_b32_dpp v49, v47 row_mirror row_mask:0xf bank_mask:0xf bound_ctrl:1
	s_and_saveexec_b64 s[46:47], s[8:9]
	s_cbranch_execz .LBB0_1621
	v_pk_add_f32 v[46:47], v[46:47], v[48:49]
	v_lshl_add_u64 v[48:49], s[52:53], 0, v[34:35]
	v_add_co_u32_e32 v48, vcc, 0x1d508000, v48
	s_nop 1
	v_addc_co_u32_e32 v49, vcc, 0, v49, vcc
	global_store_dwordx2 v[48:49], v[46:47], off
	s_branch .LBB0_1621

; __global__ void __launch_bounds__(512, 2) mega_fwd(Params p, int ph_lo, int ph_hi) {
;     extern __shared__ __attribute__((aligned(16))) unsigned char lds[];
	.amdhsa_kernel _Z8mega_fwd6Paramsii
		.amdhsa_group_segment_fixed_size 0
		.amdhsa_private_segment_fixed_size 0
		.amdhsa_kernarg_size 568
		.amdhsa_user_sgpr_count 2
		.amdhsa_user_sgpr_dispatch_ptr 0
		.amdhsa_user_sgpr_queue_ptr 0
		.amdhsa_user_sgpr_kernarg_segment_ptr 1
		.amdhsa_user_sgpr_dispatch_id 0
		.amdhsa_user_sgpr_kernarg_preload_length 0
		.amdhsa_user_sgpr_kernarg_preload_offset 0
		.amdhsa_user_sgpr_private_segment_size 0
		.amdhsa_uses_dynamic_stack 0
		.amdhsa_enable_private_segment 0
		.amdhsa_system_sgpr_workgroup_id_x 1
		.amdhsa_system_sgpr_workgroup_id_y 0
		.amdhsa_system_sgpr_workgroup_id_z 0
		.amdhsa_system_sgpr_workgroup_info 0
		.amdhsa_system_vgpr_workitem_id 0
		.amdhsa_next_free_vgpr 245
		.amdhsa_next_free_sgpr 102
		.amdhsa_accum_offset 248
		.amdhsa_reserve_vcc 1
		.amdhsa_float_round_mode_32 0
		.amdhsa_float_round_mode_16_64 0
		.amdhsa_float_denorm_mode_32 3
		.amdhsa_float_denorm_mode_16_64 3
		.amdhsa_dx10_clamp 1
		.amdhsa_ieee_mode 1
		.amdhsa_fp16_overflow 0
		.amdhsa_tg_split 0
		.amdhsa_exception_fp_ieee_invalid_op 0
		.amdhsa_exception_fp_denorm_src 0
		.amdhsa_exception_fp_ieee_div_zero 0
		.amdhsa_exception_fp_ieee_overflow 0
		.amdhsa_exception_fp_ieee_underflow 0
		.amdhsa_exception_fp_ieee_inexact 0
		.amdhsa_exception_int_div_zero 0
	.end_amdhsa_kernel
